# GEMM K-loop LDS-DMA loads switched to SGPR-base + 32-bit VGPR offset form (removes 64-bit VALU address adds) on top of attention barrier-head cleanup
# baseline (speedup 1.0000x reference)
; #define PG8_STAGE(bufoff, gbase, voff) do { _Pragma("unroll") for (int _i = 0; _i < 2; ++_i) \
;         __builtin_amdgcn_global_load_lds((const unsigned*)((const char*)(gbase) + (voff)[_i]), (LAS unsigned*)(lds + (bufoff) + ldsw + _i * 8192), 16, 0, 0); } while (0)
; #define PG8_WAIT_V(n) asm volatile("s_waitcnt vmcnt(" #n ")" ::: "memory")
; #define PG8_BAR __builtin_amdgcn_s_barrier()
; template <class Epi, int GM, int GN, int GK, int LDA, int AMOD, int ASTRIDE, int WG = WGM>
; __device__ __forceinline__ void gemm_phase(LAS unsigned char* lds, const Gemm g, const Epi& E, int wv_) {
;     ...
;     const char* cA = (const char*)g.A + (size_t)cur.pm * tstepA + PG8_AOFF(cur.pn); const char* cB = (const char*)g.Bt + (size_t)cur.pn * tstepB;
;     PG8_STAGE(PG8_SB(0, 0), cB, voffB); PG8_STAGE(PG8_SB(0, 1), cB + hstepB, voffB); PG8_STAGE(PG8_SA(0, 0), cA, voffA); PG8_STAGE(PG8_SA(0, 1), cA + hstepA, voffA);
;     if (wr == 1) PG8_BAR;
;     PG8_WAIT_V(2); PG8_BAR;
;     PG8_STAGE(PG8_SB(1, 0), cB + kstep, voffB); PG8_STAGE(PG8_SA(1, 0), cA + kstep, voffA); PG8_STAGE(PG8_SB(1, 1), cB + hstepB + kstep, voffB);
;     PG8_WAIT_V(6); PG8_BAR;
.LBB0_31:
	v_bfe_u32 v141, v14, 4, 2
	v_and_b32_e32 v140, 15, v14
	v_lshlrev_b32_e32 v15, 4, v141
	v_lshlrev_b32_e32 v14, 2, v14
	v_lshl_or_b32 v15, v140, 6, v15
	s_lshl_b32 s7, s15, 13
	v_and_b32_e32 v14, 32, v14
	v_bitop3_b32 v16, v15, s7, v14 bitop3:0xde
	s_lshl_b32 s7, s13, 5
	s_and_b32 s37, s7, 0x60
	s_add_i32 m0, s30, 0x18000
	v_lshl_add_u64 v[6:7], v[6:7], 0, s[70:71]
	s_lshl_b32 s36, s15, 6
	s_lshl_b32 s7, s37, 7
	s_waitcnt vmcnt(2)
	s_barrier
	global_load_lds_dwordx4 v[6:7], off
	v_lshl_add_u64 v[4:5], v[4:5], 0, s[70:71]
	s_add_i32 m0, s30, 0x1a000
	s_add_i32 s40, s30, 0x8000
	s_add_i32 s41, s30, 0xa000
	s_sext_i32_i8 s48, s12
	global_load_lds_dwordx4 v[4:5], off
	v_lshl_add_u64 v[0:1], v[0:1], 0, s[70:71]
	s_mov_b32 m0, s40
	s_add_u32 s12, s10, 0x80080
	global_load_lds_dwordx4 v[0:1], off
	v_lshl_add_u64 v[0:1], v[2:3], 0, s[70:71]
	s_mov_b32 m0, s41
	s_addc_u32 s13, s11, 0
	global_load_lds_dwordx4 v[0:1], off
	s_add_i32 m0, s30, 0x1c000
	s_nop 0
	global_load_lds_dwordx4 v160, s[12:13]
	v_lshl_add_u64 v[0:1], s[12:13], 0, v[128:129]
	s_add_i32 m0, s30, 0x1e000
	s_cmp_gt_i32 s19, 0
	global_load_lds_dwordx4 v128, s[12:13]
	v_lshlrev_b32_e32 v0, 15, v11
	v_and_b32_e32 v0, 0xffff0000, v0
	v_lshl_add_u32 v0, v12, 12, v0
	v_and_b32_e32 v1, 1, v11
	v_lshl_or_b32 v0, v1, 6, v0
	v_lshl_add_u32 v130, v13, 1, v0
	v_lshlrev_b32_e32 v0, 15, v8
	v_and_b32_e32 v0, 0xffff0000, v0
	s_waitcnt vmcnt(6)
	s_cselect_b64 s[12:13], -1, 0
	s_add_i32 s43, s19, -2
	v_lshl_add_u32 v0, v9, 12, v0
	v_and_b32_e32 v1, 1, v8
	s_cmpk_lt_u32 s14, 0x100
	v_lshl_or_b32 v0, v1, 6, v0
	v_bitop3_b32 v142, s7, v15, v14 bitop3:0xf6
	s_mov_b32 s42, 0
	s_cselect_b64 s[16:17], -1, 0
	v_mov_b32_e32 v131, v161
	v_lshl_add_u32 v132, v10, 1, v0
	v_mov_b32_e32 v133, v161
	v_add_u32_e32 v143, 0, v16
	s_barrier
	s_branch .LBB0_34

; #define PG8_STAGE(bufoff, gbase, voff) do { _Pragma("unroll") for (int _i = 0; _i < 2; ++_i) \
;         __builtin_amdgcn_global_load_lds((const unsigned*)((const char*)(gbase) + (voff)[_i]), (LAS unsigned*)(lds + (bufoff) + ldsw + _i * 8192), 16, 0, 0); } while (0)
; #define PG8_LDA(dst, b, h) do { _Pragma("unroll") for (int m = 0; m < 4; ++m) _Pragma("unroll") for (int k = 0; k < 2; ++k) dst[m][k] = *(const LAS bf16x8*)(lds + PG8_SA(b, h) + aoff + m * 2048 + k * 1024); } while (0)
; #define PG8_LDB(dst, b, h) do { _Pragma("unroll") for (int n = 0; n < 2; ++n) _Pragma("unroll") for (int k = 0; k < 2; ++k) dst[n][k] = *(const LAS bf16x8*)(lds + PG8_SB(b, h) + boff + n * 2048 + k * 1024); } while (0)
; #define PG8_MMA(ai, bj, At, Bt) do { __builtin_amdgcn_s_setprio(1); _Pragma("unroll") for (int m = 0; m < 4; ++m) _Pragma("unroll") for (int n = 0; n < 2; ++n) _Pragma("unroll") for (int k = 0; k < 2; ++k) \
;         acc[ai][bj][m][n] = __builtin_amdgcn_mfma_f32_16x16x32_bf16(Bt[n][k], At[m][k], acc[ai][bj][m][n], 0, 0, 0); __builtin_amdgcn_s_setprio(0); } while (0)
; #define PG8_WAIT_V(n) asm volatile("s_waitcnt vmcnt(" #n ")" ::: "memory")
; #define PG8_WAIT_L(n) asm volatile("s_waitcnt lgkmcnt(" #n ")" ::: "memory")
; #define PG8_BAR __builtin_amdgcn_s_barrier()
; #define PG8_SCHED __builtin_amdgcn_sched_barrier(0)
; template <class Epi, int GM, int GN, int GK, int LDA, int AMOD, int ASTRIDE, int WG = WGM>
; __device__ __forceinline__ void gemm_phase(LAS unsigned char* lds, const Gemm g, const Epi& E, int wv_) {
;     ...
;             const char* a1 = cA + (size_t)(t + 1) * kstep;
;             const char* a2 = last ? nA : cA + (size_t)(t + 2) * kstep; const char* b2 = last ? nB : cB + (size_t)(t + 2) * kstep;
;             const char* a3 = a2 + kstep; const char* b3 = b2 + kstep;
;             PG8_LDB(B0, 0, 0); PG8_LDB(B1, 0, 1); PG8_SCHED; PG8_LDA(At, 0, 0); PG8_STAGE(PG8_SA(1, 1), a1 + hstepA, voffA);
;             PG8_WAIT_V(8); PG8_WAIT_L(0); PG8_BAR; PG8_MMA(0, 0, At, B0); PG8_MMA(0, 1, At, B1); PG8_BAR; PG8_SCHED;
;             PG8_LDA(At, 0, 1); PG8_STAGE(PG8_SB(0, 0), b2, voffB); PG8_STAGE(PG8_SB(0, 1), b2 + hstepB, voffB); PG8_STAGE(PG8_SA(0, 0), a2, voffA);
;             PG8_WAIT_V(8); PG8_WAIT_L(0); PG8_BAR; PG8_MMA(1, 0, At, B0); PG8_MMA(1, 1, At, B1); PG8_BAR; PG8_SCHED;
.LBB0_38:
	s_add_i32 s52, s10, 2
	s_add_u32 s11, s8, 0xfff80080
	s_addc_u32 s14, s9, -1
	s_add_i32 s53, 0, 0x10000
	s_cmp_eq_u32 s43, s10
	s_cselect_b32 s15, s7, s14
	s_cselect_b32 s14, s21, s11
	v_add_u32_e32 v138, s53, v142
	s_cselect_b32 s11, s23, s51
	s_cselect_b32 s10, s49, s50
	s_add_i32 s56, 0, 0x14000
	ds_read_b128 v[134:137], v138
	ds_read_b128 v[144:147], v138 offset:1024
	ds_read_b128 v[148:151], v138 offset:2048
	ds_read_b128 v[152:155], v138 offset:3072
	v_add_u32_e32 v138, s56, v142
	ds_read_b128 v[156:159], v138
	ds_read_b128 v[174:177], v138 offset:1024
	ds_read_b128 v[178:181], v138 offset:2048
	ds_read_b128 v[182:185], v138 offset:3072
	s_add_i32 m0, s30, 0xc000
	ds_read_b128 v[186:189], v143
	ds_read_b128 v[190:193], v143 offset:1024
	ds_read_b128 v[202:205], v143 offset:2048
	ds_read_b128 v[206:209], v143 offset:3072
	ds_read_b128 v[210:213], v143 offset:4096
	ds_read_b128 v[214:217], v143 offset:5120
	ds_read_b128 v[218:221], v143 offset:6144
	ds_read_b128 v[222:225], v143 offset:7168
	global_load_lds_dwordx4 v130, s[8:9]
	s_add_i32 m0, s30, 0xe000
	s_nop 0
	global_load_lds_dwordx4 v132, s[8:9]
	s_waitcnt vmcnt(8)
	s_waitcnt lgkmcnt(0)
	s_barrier
	s_setprio 1
	s_waitcnt lgkmcnt(0)
	v_mfma_f32_16x16x32_bf16 v[124:127], v[134:137], v[186:189], v[124:127]
	v_mfma_f32_16x16x32_bf16 v[120:123], v[148:151], v[186:189], v[120:123]
	v_mfma_f32_16x16x32_bf16 v[108:111], v[134:137], v[202:205], v[108:111]
	v_mfma_f32_16x16x32_bf16 v[104:107], v[148:151], v[202:205], v[104:107]
	v_mfma_f32_16x16x32_bf16 v[92:95], v[134:137], v[210:213], v[92:95]
	v_mfma_f32_16x16x32_bf16 v[88:91], v[148:151], v[210:213], v[88:91]
	v_mfma_f32_16x16x32_bf16 v[76:79], v[134:137], v[218:221], v[76:79]
	v_mfma_f32_16x16x32_bf16 v[72:75], v[148:151], v[218:221], v[72:75]
	v_mfma_f32_16x16x32_bf16 v[124:127], v[144:147], v[190:193], v[124:127]
	v_mfma_f32_16x16x32_bf16 v[120:123], v[152:155], v[190:193], v[120:123]
	v_mfma_f32_16x16x32_bf16 v[108:111], v[144:147], v[206:209], v[108:111]
	v_mfma_f32_16x16x32_bf16 v[104:107], v[152:155], v[206:209], v[104:107]
	v_mfma_f32_16x16x32_bf16 v[92:95], v[144:147], v[214:217], v[92:95]
	v_mfma_f32_16x16x32_bf16 v[88:91], v[152:155], v[214:217], v[88:91]
	v_mfma_f32_16x16x32_bf16 v[76:79], v[144:147], v[222:225], v[76:79]
	v_mfma_f32_16x16x32_bf16 v[72:75], v[152:155], v[222:225], v[72:75]
	s_setprio 0
	s_setprio 1
	v_mfma_f32_16x16x32_bf16 v[116:119], v[156:159], v[186:189], v[116:119]
	v_mfma_f32_16x16x32_bf16 v[112:115], v[178:181], v[186:189], v[112:115]
	v_mfma_f32_16x16x32_bf16 v[100:103], v[156:159], v[202:205], v[100:103]
	v_mfma_f32_16x16x32_bf16 v[96:99], v[178:181], v[202:205], v[96:99]
	v_mfma_f32_16x16x32_bf16 v[84:87], v[156:159], v[210:213], v[84:87]
	v_mfma_f32_16x16x32_bf16 v[80:83], v[178:181], v[210:213], v[80:83]
	v_mfma_f32_16x16x32_bf16 v[68:71], v[156:159], v[218:221], v[68:71]
	v_mfma_f32_16x16x32_bf16 v[64:67], v[178:181], v[218:221], v[64:67]
	v_mfma_f32_16x16x32_bf16 v[116:119], v[174:177], v[190:193], v[116:119]
	v_mfma_f32_16x16x32_bf16 v[112:115], v[182:185], v[190:193], v[112:115]
	v_mfma_f32_16x16x32_bf16 v[100:103], v[174:177], v[206:209], v[100:103]
	v_mfma_f32_16x16x32_bf16 v[96:99], v[182:185], v[206:209], v[96:99]
	v_mfma_f32_16x16x32_bf16 v[84:87], v[174:177], v[214:217], v[84:87]
	v_mfma_f32_16x16x32_bf16 v[80:83], v[182:185], v[214:217], v[80:83]
	v_mfma_f32_16x16x32_bf16 v[68:71], v[174:177], v[222:225], v[68:71]
	v_mfma_f32_16x16x32_bf16 v[64:67], v[182:185], v[222:225], v[64:67]
	s_setprio 0
	s_barrier
	s_add_i32 s53, s53, s28
	v_lshl_add_u64 v[138:139], s[10:11], 0, v[160:161]
	s_mov_b32 m0, s53
	ds_read_b128 v[186:189], v143 offset:16384
	ds_read_b128 v[190:193], v143 offset:17408
	ds_read_b128 v[202:205], v143 offset:18432
	ds_read_b128 v[206:209], v143 offset:19456
	ds_read_b128 v[210:213], v143 offset:20480
	ds_read_b128 v[214:217], v143 offset:21504
	ds_read_b128 v[218:221], v143 offset:22528
	ds_read_b128 v[222:225], v143 offset:23552
	global_load_lds_dwordx4 v160, s[10:11]
	s_add_i32 m0, s53, 0x2000
	s_add_u32 s54, s10, 0x80000
	v_lshl_add_u64 v[168:169], s[10:11], 0, v[128:129]
	s_addc_u32 s55, s11, 0
	s_add_i32 s53, s56, s28
	global_load_lds_dwordx4 v128, s[10:11]
	s_mov_b32 m0, s53
	v_lshl_add_u64 v[196:197], s[14:15], 0, v[128:129]
	global_load_lds_dwordx4 v160, s[54:55]
	s_add_i32 m0, s53, 0x2000
	s_nop 0
	global_load_lds_dwordx4 v128, s[54:55]
	v_lshl_add_u64 v[170:171], s[14:15], 0, v[160:161]
	s_mov_b32 m0, s30
	s_nop 0
	global_load_lds_dwordx4 v160, s[14:15]
	s_mov_b32 m0, s31
	s_nop 0
	global_load_lds_dwordx4 v128, s[14:15]
	s_waitcnt vmcnt(8)
	s_waitcnt lgkmcnt(0)
	s_barrier
; #define PG8_STAGE(bufoff, gbase, voff) do { _Pragma("unroll") for (int _i = 0; _i < 2; ++_i) \
;         __builtin_amdgcn_global_load_lds((const unsigned*)((const char*)(gbase) + (voff)[_i]), (LAS unsigned*)(lds + (bufoff) + ldsw + _i * 8192), 16, 0, 0); } while (0)
; #define PG8_LDA(dst, b, h) do { _Pragma("unroll") for (int m = 0; m < 4; ++m) _Pragma("unroll") for (int k = 0; k < 2; ++k) dst[m][k] = *(const LAS bf16x8*)(lds + PG8_SA(b, h) + aoff + m * 2048 + k * 1024); } while (0)
; #define PG8_LDB(dst, b, h) do { _Pragma("unroll") for (int n = 0; n < 2; ++n) _Pragma("unroll") for (int k = 0; k < 2; ++k) dst[n][k] = *(const LAS bf16x8*)(lds + PG8_SB(b, h) + boff + n * 2048 + k * 1024); } while (0)
; #define PG8_MMA(ai, bj, At, Bt) do { __builtin_amdgcn_s_setprio(1); _Pragma("unroll") for (int m = 0; m < 4; ++m) _Pragma("unroll") for (int n = 0; n < 2; ++n) _Pragma("unroll") for (int k = 0; k < 2; ++k) \
;         acc[ai][bj][m][n] = __builtin_amdgcn_mfma_f32_16x16x32_bf16(Bt[n][k], At[m][k], acc[ai][bj][m][n], 0, 0, 0); __builtin_amdgcn_s_setprio(0); } while (0)
; #define PG8_WAIT_V(n) asm volatile("s_waitcnt vmcnt(" #n ")" ::: "memory")
; #define PG8_WAIT_L(n) asm volatile("s_waitcnt lgkmcnt(" #n ")" ::: "memory")
; #define PG8_BAR __builtin_amdgcn_s_barrier()
; #define PG8_SCHED __builtin_amdgcn_sched_barrier(0)
; template <class Epi, int GM, int GN, int GK, int LDA, int AMOD, int ASTRIDE, int WG = WGM>
; __device__ __forceinline__ void gemm_phase(LAS unsigned char* lds, const Gemm g, const Epi& E, int wv_) {
;     ...
;             PG8_WAIT_V(8); PG8_WAIT_L(0); PG8_BAR; PG8_MMA(1, 0, At, B0); PG8_MMA(1, 1, At, B1); PG8_BAR; PG8_SCHED;
;             PG8_LDB(B0, 1, 0); PG8_LDB(B1, 1, 1); PG8_SCHED; PG8_LDA(At, 1, 0); PG8_STAGE(PG8_SA(0, 1), a2 + hstepA, voffA);
;             PG8_WAIT_V(8); PG8_WAIT_L(0); PG8_BAR; PG8_MMA(0, 0, At, B0); PG8_MMA(0, 1, At, B1); PG8_BAR; PG8_SCHED;
	s_setprio 1
	s_waitcnt lgkmcnt(0)
	v_mfma_f32_16x16x32_bf16 v[60:63], v[134:137], v[186:189], v[60:63]
	v_mfma_f32_16x16x32_bf16 v[56:59], v[148:151], v[186:189], v[56:59]
	v_mfma_f32_16x16x32_bf16 v[44:47], v[134:137], v[202:205], v[44:47]
	v_mfma_f32_16x16x32_bf16 v[40:43], v[148:151], v[202:205], v[40:43]
	v_mfma_f32_16x16x32_bf16 v[28:31], v[134:137], v[210:213], v[28:31]
	v_mfma_f32_16x16x32_bf16 v[24:27], v[148:151], v[210:213], v[24:27]
	v_mfma_f32_16x16x32_bf16 v[12:15], v[134:137], v[218:221], v[12:15]
	v_mfma_f32_16x16x32_bf16 v[8:11], v[148:151], v[218:221], v[8:11]
	v_mfma_f32_16x16x32_bf16 v[60:63], v[144:147], v[190:193], v[60:63]
	v_mfma_f32_16x16x32_bf16 v[56:59], v[152:155], v[190:193], v[56:59]
	v_mfma_f32_16x16x32_bf16 v[44:47], v[144:147], v[206:209], v[44:47]
	v_mfma_f32_16x16x32_bf16 v[40:43], v[152:155], v[206:209], v[40:43]
	v_mfma_f32_16x16x32_bf16 v[28:31], v[144:147], v[214:217], v[28:31]
	v_mfma_f32_16x16x32_bf16 v[24:27], v[152:155], v[214:217], v[24:27]
	v_mfma_f32_16x16x32_bf16 v[12:15], v[144:147], v[222:225], v[12:15]
	v_mfma_f32_16x16x32_bf16 v[8:11], v[152:155], v[222:225], v[8:11]
	s_setprio 0
	s_setprio 1
	v_mfma_f32_16x16x32_bf16 v[52:55], v[156:159], v[186:189], v[52:55]
	v_mfma_f32_16x16x32_bf16 v[48:51], v[178:181], v[186:189], v[48:51]
	v_mfma_f32_16x16x32_bf16 v[36:39], v[156:159], v[202:205], v[36:39]
	v_mfma_f32_16x16x32_bf16 v[32:35], v[178:181], v[202:205], v[32:35]
	v_mfma_f32_16x16x32_bf16 v[20:23], v[156:159], v[210:213], v[20:23]
	v_mfma_f32_16x16x32_bf16 v[16:19], v[178:181], v[210:213], v[16:19]
	v_mfma_f32_16x16x32_bf16 v[4:7], v[156:159], v[218:221], v[4:7]
	v_mfma_f32_16x16x32_bf16 v[0:3], v[178:181], v[218:221], v[0:3]
	v_mfma_f32_16x16x32_bf16 v[52:55], v[174:177], v[190:193], v[52:55]
	v_mfma_f32_16x16x32_bf16 v[48:51], v[182:185], v[190:193], v[48:51]
	v_mfma_f32_16x16x32_bf16 v[36:39], v[174:177], v[206:209], v[36:39]
	v_mfma_f32_16x16x32_bf16 v[32:35], v[182:185], v[206:209], v[32:35]
	v_mfma_f32_16x16x32_bf16 v[20:23], v[174:177], v[214:217], v[20:23]
	v_mfma_f32_16x16x32_bf16 v[16:19], v[182:185], v[214:217], v[16:19]
	v_mfma_f32_16x16x32_bf16 v[4:7], v[174:177], v[222:225], v[4:7]
	v_mfma_f32_16x16x32_bf16 v[0:3], v[182:185], v[222:225], v[0:3]
	s_setprio 0
	s_barrier
	s_add_i32 s53, 0, 0x18000
	s_add_i32 s54, 0, 0x1c000
	v_add_u32_e32 v152, s53, v142
	v_add_u32_e32 v182, s54, v142
	ds_read_b128 v[134:137], v152
	ds_read_b128 v[144:147], v152 offset:1024
	ds_read_b128 v[148:151], v152 offset:2048
	ds_read_b128 v[152:155], v152 offset:3072
	ds_read_b128 v[156:159], v182
	ds_read_b128 v[174:177], v182 offset:1024
	ds_read_b128 v[178:181], v182 offset:2048
	ds_read_b128 v[182:185], v182 offset:3072
	s_add_u32 s14, s14, 0x80000
	s_addc_u32 s15, s15, 0
	s_mov_b32 m0, s34
	ds_read_b128 v[186:189], v143 offset:32768
	ds_read_b128 v[190:193], v143 offset:33792
	ds_read_b128 v[202:205], v143 offset:34816
	ds_read_b128 v[206:209], v143 offset:35840
	ds_read_b128 v[210:213], v143 offset:36864
	ds_read_b128 v[214:217], v143 offset:37888
	ds_read_b128 v[218:221], v143 offset:38912
	ds_read_b128 v[222:225], v143 offset:39936
	global_load_lds_dwordx4 v160, s[14:15]
	v_lshl_add_u64 v[198:199], s[14:15], 0, v[128:129]
	s_mov_b32 m0, s35
	s_nop 0
	global_load_lds_dwordx4 v128, s[14:15]
	s_waitcnt vmcnt(8)
	s_waitcnt lgkmcnt(0)
	s_barrier
	s_setprio 1
	s_waitcnt lgkmcnt(0)
	v_mfma_f32_16x16x32_bf16 v[124:127], v[134:137], v[186:189], v[124:127]
	v_mfma_f32_16x16x32_bf16 v[120:123], v[148:151], v[186:189], v[120:123]
	v_mfma_f32_16x16x32_bf16 v[108:111], v[134:137], v[202:205], v[108:111]
	v_mfma_f32_16x16x32_bf16 v[104:107], v[148:151], v[202:205], v[104:107]
	v_mfma_f32_16x16x32_bf16 v[92:95], v[134:137], v[210:213], v[92:95]
	v_mfma_f32_16x16x32_bf16 v[88:91], v[148:151], v[210:213], v[88:91]
	v_mfma_f32_16x16x32_bf16 v[76:79], v[134:137], v[218:221], v[76:79]
	v_mfma_f32_16x16x32_bf16 v[72:75], v[148:151], v[218:221], v[72:75]
	v_mfma_f32_16x16x32_bf16 v[124:127], v[144:147], v[190:193], v[124:127]
	v_mfma_f32_16x16x32_bf16 v[120:123], v[152:155], v[190:193], v[120:123]
	v_mfma_f32_16x16x32_bf16 v[108:111], v[144:147], v[206:209], v[108:111]
	v_mfma_f32_16x16x32_bf16 v[104:107], v[152:155], v[206:209], v[104:107]
	v_mfma_f32_16x16x32_bf16 v[92:95], v[144:147], v[214:217], v[92:95]
	v_mfma_f32_16x16x32_bf16 v[88:91], v[152:155], v[214:217], v[88:91]
	v_mfma_f32_16x16x32_bf16 v[76:79], v[144:147], v[222:225], v[76:79]
	v_mfma_f32_16x16x32_bf16 v[72:75], v[152:155], v[222:225], v[72:75]
	s_setprio 0
	s_setprio 1
	v_mfma_f32_16x16x32_bf16 v[116:119], v[156:159], v[186:189], v[116:119]
	v_mfma_f32_16x16x32_bf16 v[112:115], v[178:181], v[186:189], v[112:115]
	v_mfma_f32_16x16x32_bf16 v[100:103], v[156:159], v[202:205], v[100:103]
	v_mfma_f32_16x16x32_bf16 v[96:99], v[178:181], v[202:205], v[96:99]
	v_mfma_f32_16x16x32_bf16 v[84:87], v[156:159], v[210:213], v[84:87]
	v_mfma_f32_16x16x32_bf16 v[80:83], v[178:181], v[210:213], v[80:83]
	v_mfma_f32_16x16x32_bf16 v[68:71], v[156:159], v[218:221], v[68:71]
	v_mfma_f32_16x16x32_bf16 v[64:67], v[178:181], v[218:221], v[64:67]
	v_mfma_f32_16x16x32_bf16 v[116:119], v[174:177], v[190:193], v[116:119]
	v_mfma_f32_16x16x32_bf16 v[112:115], v[182:185], v[190:193], v[112:115]
	v_mfma_f32_16x16x32_bf16 v[100:103], v[174:177], v[206:209], v[100:103]
	v_mfma_f32_16x16x32_bf16 v[96:99], v[182:185], v[206:209], v[96:99]
	v_mfma_f32_16x16x32_bf16 v[84:87], v[174:177], v[214:217], v[84:87]
	v_mfma_f32_16x16x32_bf16 v[80:83], v[182:185], v[214:217], v[80:83]
	v_mfma_f32_16x16x32_bf16 v[68:71], v[174:177], v[222:225], v[68:71]
	v_mfma_f32_16x16x32_bf16 v[64:67], v[182:185], v[222:225], v[64:67]
	s_setprio 0
	s_barrier
; #define PG8_STAGE(bufoff, gbase, voff) do { _Pragma("unroll") for (int _i = 0; _i < 2; ++_i) \
;         __builtin_amdgcn_global_load_lds((const unsigned*)((const char*)(gbase) + (voff)[_i]), (LAS unsigned*)(lds + (bufoff) + ldsw + _i * 8192), 16, 0, 0); } while (0)
; #define PG8_LDA(dst, b, h) do { _Pragma("unroll") for (int m = 0; m < 4; ++m) _Pragma("unroll") for (int k = 0; k < 2; ++k) dst[m][k] = *(const LAS bf16x8*)(lds + PG8_SA(b, h) + aoff + m * 2048 + k * 1024); } while (0)
; #define PG8_MMA(ai, bj, At, Bt) do { __builtin_amdgcn_s_setprio(1); _Pragma("unroll") for (int m = 0; m < 4; ++m) _Pragma("unroll") for (int n = 0; n < 2; ++n) _Pragma("unroll") for (int k = 0; k < 2; ++k) \
;         acc[ai][bj][m][n] = __builtin_amdgcn_mfma_f32_16x16x32_bf16(Bt[n][k], At[m][k], acc[ai][bj][m][n], 0, 0, 0); __builtin_amdgcn_s_setprio(0); } while (0)
; #define PG8_WAIT_V(n) asm volatile("s_waitcnt vmcnt(" #n ")" ::: "memory")
; #define PG8_WAIT_L(n) asm volatile("s_waitcnt lgkmcnt(" #n ")" ::: "memory")
; #define PG8_BAR __builtin_amdgcn_s_barrier()
; #define PG8_SCHED __builtin_amdgcn_sched_barrier(0)
; template <class Epi, int GM, int GN, int GK, int LDA, int AMOD, int ASTRIDE, int WG = WGM>
; __device__ __forceinline__ void gemm_phase(LAS unsigned char* lds, const Gemm g, const Epi& E, int wv_) {
;     ...
;             PG8_LDA(At, 1, 1); PG8_STAGE(PG8_SB(1, 0), b3, voffB); PG8_STAGE(PG8_SB(1, 1), b3 + hstepB, voffB); PG8_STAGE(PG8_SA(1, 0), a3, voffA);
;             PG8_WAIT_V(8); PG8_WAIT_L(0); PG8_BAR; PG8_MMA(1, 0, At, B0); PG8_MMA(1, 1, At, B1); PG8_BAR; PG8_SCHED;
;         }
	s_add_i32 s14, s53, s28
	v_lshl_add_u64 v[138:139], v[138:139], 0, s[70:71]
	s_mov_b32 m0, s14
	ds_read_b128 v[186:189], v143 offset:49152
	ds_read_b128 v[190:193], v143 offset:50176
	ds_read_b128 v[202:205], v143 offset:51200
	ds_read_b128 v[206:209], v143 offset:52224
	ds_read_b128 v[210:213], v143 offset:53248
	ds_read_b128 v[214:217], v143 offset:54272
	ds_read_b128 v[218:221], v143 offset:55296
	ds_read_b128 v[222:225], v143 offset:56320
	global_load_lds_dwordx4 v[138:139], off
	s_add_i32 m0, s14, 0x2000
	s_add_u32 s10, s10, 0x80080
	v_lshl_add_u64 v[138:139], v[168:169], 0, s[70:71]
	s_addc_u32 s11, s11, 0
	s_add_i32 s14, s54, s28
	global_load_lds_dwordx4 v[138:139], off
	s_mov_b32 m0, s14
	s_nop 0
	global_load_lds_dwordx4 v160, s[10:11]
	s_add_i32 m0, s14, 0x2000
	s_nop 0
	global_load_lds_dwordx4 v128, s[10:11]
	v_lshl_add_u64 v[138:139], v[170:171], 0, s[70:71]
	s_mov_b32 m0, s40
	s_nop 0
	global_load_lds_dwordx4 v[138:139], off
	v_lshl_add_u64 v[138:139], v[196:197], 0, s[70:71]
	s_mov_b32 m0, s41
	s_nop 0
	global_load_lds_dwordx4 v[138:139], off
	s_waitcnt vmcnt(8)
	s_waitcnt lgkmcnt(0)
	s_barrier
	s_setprio 1
	s_waitcnt lgkmcnt(0)
	v_mfma_f32_16x16x32_bf16 v[60:63], v[134:137], v[186:189], v[60:63]
	v_mfma_f32_16x16x32_bf16 v[56:59], v[148:151], v[186:189], v[56:59]
	v_mfma_f32_16x16x32_bf16 v[44:47], v[134:137], v[202:205], v[44:47]
	v_mfma_f32_16x16x32_bf16 v[40:43], v[148:151], v[202:205], v[40:43]
	v_mfma_f32_16x16x32_bf16 v[28:31], v[134:137], v[210:213], v[28:31]
	v_mfma_f32_16x16x32_bf16 v[24:27], v[148:151], v[210:213], v[24:27]
	v_mfma_f32_16x16x32_bf16 v[12:15], v[134:137], v[218:221], v[12:15]
	v_mfma_f32_16x16x32_bf16 v[8:11], v[148:151], v[218:221], v[8:11]
	v_mfma_f32_16x16x32_bf16 v[60:63], v[144:147], v[190:193], v[60:63]
	v_mfma_f32_16x16x32_bf16 v[56:59], v[152:155], v[190:193], v[56:59]
	v_mfma_f32_16x16x32_bf16 v[44:47], v[144:147], v[206:209], v[44:47]
	v_mfma_f32_16x16x32_bf16 v[40:43], v[152:155], v[206:209], v[40:43]
	v_mfma_f32_16x16x32_bf16 v[28:31], v[144:147], v[214:217], v[28:31]
	v_mfma_f32_16x16x32_bf16 v[24:27], v[152:155], v[214:217], v[24:27]
	v_mfma_f32_16x16x32_bf16 v[12:15], v[144:147], v[222:225], v[12:15]
	v_mfma_f32_16x16x32_bf16 v[8:11], v[152:155], v[222:225], v[8:11]
	s_setprio 0
	s_setprio 1
	v_mfma_f32_16x16x32_bf16 v[52:55], v[156:159], v[186:189], v[52:55]
	v_mfma_f32_16x16x32_bf16 v[48:51], v[178:181], v[186:189], v[48:51]
	v_mfma_f32_16x16x32_bf16 v[36:39], v[156:159], v[202:205], v[36:39]
	v_mfma_f32_16x16x32_bf16 v[32:35], v[178:181], v[202:205], v[32:35]
	v_mfma_f32_16x16x32_bf16 v[20:23], v[156:159], v[210:213], v[20:23]
	v_mfma_f32_16x16x32_bf16 v[16:19], v[178:181], v[210:213], v[16:19]
	v_mfma_f32_16x16x32_bf16 v[4:7], v[156:159], v[218:221], v[4:7]
	v_mfma_f32_16x16x32_bf16 v[0:3], v[178:181], v[218:221], v[0:3]
	v_mfma_f32_16x16x32_bf16 v[52:55], v[174:177], v[190:193], v[52:55]
	v_mfma_f32_16x16x32_bf16 v[48:51], v[182:185], v[190:193], v[48:51]
	v_mfma_f32_16x16x32_bf16 v[36:39], v[174:177], v[206:209], v[36:39]
	v_mfma_f32_16x16x32_bf16 v[32:35], v[182:185], v[206:209], v[32:35]
	v_mfma_f32_16x16x32_bf16 v[20:23], v[174:177], v[214:217], v[20:23]
	v_mfma_f32_16x16x32_bf16 v[16:19], v[182:185], v[214:217], v[16:19]
	v_mfma_f32_16x16x32_bf16 v[4:7], v[174:177], v[222:225], v[4:7]
	v_mfma_f32_16x16x32_bf16 v[0:3], v[182:185], v[222:225], v[0:3]
	s_setprio 0
	s_barrier
	s_add_u32 s8, s8, 0x100
	s_addc_u32 s9, s9, 0
	s_add_u32 s50, s50, 0x100
	s_addc_u32 s51, s51, 0
	s_cmp_ge_i32 s52, s19
	s_mov_b32 s10, s52
	s_cbranch_scc0 .LBB0_38
	s_and_b64 vcc, exec, s[16:17]
	s_cbranch_vccz .LBB0_41

; #define PG8_STAGE(bufoff, gbase, voff) do { _Pragma("unroll") for (int _i = 0; _i < 2; ++_i) \
;         __builtin_amdgcn_global_load_lds((const unsigned*)((const char*)(gbase) + (voff)[_i]), (LAS unsigned*)(lds + (bufoff) + ldsw + _i * 8192), 16, 0, 0); } while (0)
; #define PG8_WAIT_V(n) asm volatile("s_waitcnt vmcnt(" #n ")" ::: "memory")
; #define PG8_BAR __builtin_amdgcn_s_barrier()
; template <class Epi, int GM, int GN, int GK, int LDA, int AMOD, int ASTRIDE, int WG = WGM>
; __device__ __forceinline__ void gemm_phase(LAS unsigned char* lds, const Gemm g, const Epi& E, int wv_) {
;     ...
;     const char* cA = (const char*)g.A + (size_t)cur.pm * tstepA + PG8_AOFF(cur.pn); const char* cB = (const char*)g.Bt + (size_t)cur.pn * tstepB;
;     PG8_STAGE(PG8_SB(0, 0), cB, voffB); PG8_STAGE(PG8_SB(0, 1), cB + hstepB, voffB); PG8_STAGE(PG8_SA(0, 0), cA, voffA); PG8_STAGE(PG8_SA(0, 1), cA + hstepA, voffA);
;     if (wr == 1) PG8_BAR;
;     PG8_WAIT_V(2); PG8_BAR;
;     PG8_STAGE(PG8_SB(1, 0), cB + kstep, voffB); PG8_STAGE(PG8_SA(1, 0), cA + kstep, voffA); PG8_STAGE(PG8_SB(1, 1), cB + hstepB + kstep, voffB);
;     PG8_WAIT_V(6); PG8_BAR;
.LBB0_65:
	s_and_b64 s[0:1], s[0:1], exec
	v_readlane_b32 s80, v253, 56
	v_readlane_b32 s81, v253, 57
	v_readlane_b32 s82, v253, 58
	v_readlane_b32 s83, v253, 59
	s_movk_i32 s0, 0x2000
	s_cselect_b32 s34, s67, s81
	s_cselect_b32 s35, s66, s80
	s_cselect_b32 s36, 0xa000, s0
	s_cselect_b32 s37, s67, s83
	s_cselect_b32 s40, s66, s82
	s_lshl_b32 s0, s11, 5
	s_and_b32 s42, s0, 0x60
	s_add_i32 m0, s28, 0x18000
	v_lshl_add_u64 v[6:7], v[6:7], 0, s[70:71]
	s_lshl_b32 s41, s14, 6
	s_lshl_b32 s14, s14, 13
	s_lshl_b32 s11, s42, 7
	s_waitcnt vmcnt(2)
	s_barrier
	global_load_lds_dwordx4 v[6:7], off
	v_lshl_add_u64 v[4:5], v[4:5], 0, s[70:71]
	s_add_i32 m0, s28, 0x1a000
	s_add_i32 s43, s28, 0x8000
	s_add_i32 s46, s28, 0xa000
	global_load_lds_dwordx4 v[4:5], off
	v_lshl_add_u64 v[0:1], v[0:1], 0, s[70:71]
	s_mov_b32 m0, s43
	s_add_u32 s0, s8, 0x160080
	global_load_lds_dwordx4 v[0:1], off
	v_lshl_add_u64 v[0:1], v[2:3], 0, s[70:71]
	s_mov_b32 m0, s46
	s_addc_u32 s1, s9, 0
	global_load_lds_dwordx4 v[0:1], off
	s_add_i32 m0, s28, 0x1c000
	s_nop 0
	global_load_lds_dwordx4 v160, s[0:1]
	v_lshl_add_u64 v[0:1], s[0:1], 0, v[128:129]
	s_add_i32 m0, s28, 0x1e000
	v_bfe_u32 v147, v8, 4, 2
	global_load_lds_dwordx4 v128, s[0:1]
	v_and_b32_e32 v146, 15, v8
	v_lshlrev_b32_e32 v0, 4, v147
	v_lshlrev_b32_e32 v1, 2, v8
	v_lshl_or_b32 v0, v146, 6, v0
	v_and_b32_e32 v1, 32, v1
	s_cmp_gt_i32 s19, 0
	v_bitop3_b32 v148, s11, v0, v1 bitop3:0xf6
	s_cselect_b64 s[16:17], -1, 0
	s_add_i32 s48, s19, -2
	s_movk_i32 s11, 0x1600
	v_bitop3_b32 v2, v0, s14, v1 bitop3:0xde
	s_cmpk_lt_u32 s10, 0x100
	v_lshrrev_b32_e32 v1, 1, v14
	v_mul_lo_u32 v0, v13, s11
	s_mov_b32 s10, 0x16000
	v_mad_u64_u32 v[0:1], s[0:1], v1, s10, v[0:1]
	v_or_b32_e32 v0, v0, v15
	s_sext_i32_i8 s52, s15
	v_add_lshl_u32 v0, v0, v16, 1
	v_mov_b32_e32 v1, v161
	s_mov_b64 s[14:15], 0x160080
	v_lshl_add_u64 v[130:131], v[0:1], 0, s[14:15]
	v_lshrrev_b32_e32 v1, 1, v9
	v_mul_lo_u32 v0, v10, s11
	v_mad_u64_u32 v[0:1], s[0:1], v1, s10, v[0:1]
	s_waitcnt vmcnt(6)
	v_or_b32_e32 v0, v0, v11
	v_add_lshl_u32 v0, v0, v12, 1
	v_mov_b32_e32 v1, v161
	s_mov_b32 s47, 0
	s_cselect_b64 s[20:21], -1, 0
	v_lshl_add_u64 v[132:133], v[0:1], 0, s[14:15]
	v_add_u32_e32 v149, 0, v2
	v_readlane_b32 s84, v253, 60
	v_readlane_b32 s85, v253, 61
	v_readlane_b32 s86, v253, 62
	v_readlane_b32 s87, v253, 63
	v_readlane_b32 s88, v254, 0
	v_readlane_b32 s89, v254, 1
	v_readlane_b32 s90, v254, 2
	v_readlane_b32 s91, v254, 3
	v_readlane_b32 s92, v254, 4
	v_readlane_b32 s93, v254, 5
	v_readlane_b32 s94, v254, 6
	v_readlane_b32 s95, v254, 7
	s_barrier
	s_branch .LBB0_68

; #define PG8_STAGE(bufoff, gbase, voff) do { _Pragma("unroll") for (int _i = 0; _i < 2; ++_i) \
;         __builtin_amdgcn_global_load_lds((const unsigned*)((const char*)(gbase) + (voff)[_i]), (LAS unsigned*)(lds + (bufoff) + ldsw + _i * 8192), 16, 0, 0); } while (0)
; #define PG8_LDA(dst, b, h) do { _Pragma("unroll") for (int m = 0; m < 4; ++m) _Pragma("unroll") for (int k = 0; k < 2; ++k) dst[m][k] = *(const LAS bf16x8*)(lds + PG8_SA(b, h) + aoff + m * 2048 + k * 1024); } while (0)
; #define PG8_LDB(dst, b, h) do { _Pragma("unroll") for (int n = 0; n < 2; ++n) _Pragma("unroll") for (int k = 0; k < 2; ++k) dst[n][k] = *(const LAS bf16x8*)(lds + PG8_SB(b, h) + boff + n * 2048 + k * 1024); } while (0)
; #define PG8_MMA(ai, bj, At, Bt) do { __builtin_amdgcn_s_setprio(1); _Pragma("unroll") for (int m = 0; m < 4; ++m) _Pragma("unroll") for (int n = 0; n < 2; ++n) _Pragma("unroll") for (int k = 0; k < 2; ++k) \
;         acc[ai][bj][m][n] = __builtin_amdgcn_mfma_f32_16x16x32_bf16(Bt[n][k], At[m][k], acc[ai][bj][m][n], 0, 0, 0); __builtin_amdgcn_s_setprio(0); } while (0)
; #define PG8_WAIT_V(n) asm volatile("s_waitcnt vmcnt(" #n ")" ::: "memory")
; #define PG8_WAIT_L(n) asm volatile("s_waitcnt lgkmcnt(" #n ")" ::: "memory")
; #define PG8_BAR __builtin_amdgcn_s_barrier()
; #define PG8_SCHED __builtin_amdgcn_sched_barrier(0)
; template <class Epi, int GM, int GN, int GK, int LDA, int AMOD, int ASTRIDE, int WG = WGM>
; __device__ __forceinline__ void gemm_phase(LAS unsigned char* lds, const Gemm g, const Epi& E, int wv_) {
;     ...
;             const char* a1 = cA + (size_t)(t + 1) * kstep;
;             const char* a2 = last ? nA : cA + (size_t)(t + 2) * kstep; const char* b2 = last ? nB : cB + (size_t)(t + 2) * kstep;
;             const char* a3 = a2 + kstep; const char* b3 = b2 + kstep;
;             PG8_LDB(B0, 0, 0); PG8_LDB(B1, 0, 1); PG8_SCHED; PG8_LDA(At, 0, 0); PG8_STAGE(PG8_SA(1, 1), a1 + hstepA, voffA);
;             PG8_WAIT_V(8); PG8_WAIT_L(0); PG8_BAR; PG8_MMA(0, 0, At, B0); PG8_MMA(0, 1, At, B1); PG8_BAR; PG8_SCHED;
;             PG8_LDA(At, 0, 1); PG8_STAGE(PG8_SB(0, 0), b2, voffB); PG8_STAGE(PG8_SB(0, 1), b2 + hstepB, voffB); PG8_STAGE(PG8_SA(0, 0), a2, voffA);
;             PG8_WAIT_V(8); PG8_WAIT_L(0); PG8_BAR; PG8_MMA(1, 0, At, B0); PG8_MMA(1, 1, At, B1); PG8_BAR; PG8_SCHED;
.LBB0_74:
	s_add_i32 s55, s10, 2
	s_add_u32 s8, s6, 0x100
	s_addc_u32 s9, s7, 0
	s_add_i32 s56, 0, 0x10000
	s_cmp_eq_u32 s48, s10
	s_cselect_b32 s15, s1, s9
	s_cselect_b32 s14, s0, s8
	s_cselect_b32 s11, s23, s54
	s_cselect_b32 s10, s22, s53
	s_add_i32 s57, 0, 0x14000
	v_add_u32_e32 v150, s56, v148
	v_add_u32_e32 v158, s57, v148
	ds_read_b128 v[134:137], v150
	ds_read_b128 v[138:141], v150 offset:1024
	ds_read_b128 v[142:145], v150 offset:2048
	ds_read_b128 v[150:153], v150 offset:3072
	ds_read_b128 v[154:157], v158
	ds_read_b128 v[174:177], v158 offset:1024
	ds_read_b128 v[178:181], v158 offset:2048
	ds_read_b128 v[182:185], v158 offset:3072
	s_add_i32 m0, s28, 0xc000
	ds_read_b128 v[186:189], v149
	ds_read_b128 v[190:193], v149 offset:1024
	ds_read_b128 v[202:205], v149 offset:2048
	ds_read_b128 v[206:209], v149 offset:3072
	ds_read_b128 v[210:213], v149 offset:4096
	ds_read_b128 v[214:217], v149 offset:5120
	ds_read_b128 v[218:221], v149 offset:6144
	ds_read_b128 v[222:225], v149 offset:7168
	global_load_lds_dwordx4 v130, s[6:7]
	s_add_i32 m0, s28, 0xe000
	s_nop 0
	global_load_lds_dwordx4 v132, s[6:7]
	s_waitcnt vmcnt(8)
	s_waitcnt lgkmcnt(0)
	s_barrier
	s_setprio 1
	s_waitcnt lgkmcnt(0)
	v_mfma_f32_16x16x32_bf16 v[124:127], v[134:137], v[186:189], v[124:127]
	v_mfma_f32_16x16x32_bf16 v[120:123], v[142:145], v[186:189], v[120:123]
	v_mfma_f32_16x16x32_bf16 v[116:119], v[134:137], v[202:205], v[116:119]
	v_mfma_f32_16x16x32_bf16 v[112:115], v[142:145], v[202:205], v[112:115]
	v_mfma_f32_16x16x32_bf16 v[104:107], v[134:137], v[210:213], v[104:107]
	v_mfma_f32_16x16x32_bf16 v[96:99], v[142:145], v[210:213], v[96:99]
	v_mfma_f32_16x16x32_bf16 v[88:91], v[134:137], v[218:221], v[88:91]
	v_mfma_f32_16x16x32_bf16 v[80:83], v[142:145], v[218:221], v[80:83]
	v_mfma_f32_16x16x32_bf16 v[124:127], v[138:141], v[190:193], v[124:127]
	v_mfma_f32_16x16x32_bf16 v[120:123], v[150:153], v[190:193], v[120:123]
	v_mfma_f32_16x16x32_bf16 v[116:119], v[138:141], v[206:209], v[116:119]
	v_mfma_f32_16x16x32_bf16 v[112:115], v[150:153], v[206:209], v[112:115]
	v_mfma_f32_16x16x32_bf16 v[104:107], v[138:141], v[214:217], v[104:107]
	v_mfma_f32_16x16x32_bf16 v[96:99], v[150:153], v[214:217], v[96:99]
	v_mfma_f32_16x16x32_bf16 v[88:91], v[138:141], v[222:225], v[88:91]
	v_mfma_f32_16x16x32_bf16 v[80:83], v[150:153], v[222:225], v[80:83]
	s_setprio 0
	s_setprio 1
	v_mfma_f32_16x16x32_bf16 v[108:111], v[154:157], v[186:189], v[108:111]
	v_mfma_f32_16x16x32_bf16 v[100:103], v[178:181], v[186:189], v[100:103]
	v_mfma_f32_16x16x32_bf16 v[92:95], v[154:157], v[202:205], v[92:95]
	v_mfma_f32_16x16x32_bf16 v[84:87], v[178:181], v[202:205], v[84:87]
	v_mfma_f32_16x16x32_bf16 v[76:79], v[154:157], v[210:213], v[76:79]
	v_mfma_f32_16x16x32_bf16 v[72:75], v[178:181], v[210:213], v[72:75]
	v_mfma_f32_16x16x32_bf16 v[68:71], v[154:157], v[218:221], v[68:71]
	v_mfma_f32_16x16x32_bf16 v[64:67], v[178:181], v[218:221], v[64:67]
	v_mfma_f32_16x16x32_bf16 v[108:111], v[174:177], v[190:193], v[108:111]
	v_mfma_f32_16x16x32_bf16 v[100:103], v[182:185], v[190:193], v[100:103]
	v_mfma_f32_16x16x32_bf16 v[92:95], v[174:177], v[206:209], v[92:95]
	v_mfma_f32_16x16x32_bf16 v[84:87], v[182:185], v[206:209], v[84:87]
	v_mfma_f32_16x16x32_bf16 v[76:79], v[174:177], v[214:217], v[76:79]
	v_mfma_f32_16x16x32_bf16 v[72:75], v[182:185], v[214:217], v[72:75]
	v_mfma_f32_16x16x32_bf16 v[68:71], v[174:177], v[222:225], v[68:71]
	v_mfma_f32_16x16x32_bf16 v[64:67], v[182:185], v[222:225], v[64:67]
	s_setprio 0
	s_barrier
	s_add_i32 s6, s56, s26
	v_lshl_add_u64 v[158:159], s[10:11], 0, v[160:161]
	s_mov_b32 m0, s6
	ds_read_b128 v[186:189], v149 offset:16384
	ds_read_b128 v[190:193], v149 offset:17408
	ds_read_b128 v[202:205], v149 offset:18432
	ds_read_b128 v[206:209], v149 offset:19456
	ds_read_b128 v[210:213], v149 offset:20480
	ds_read_b128 v[214:217], v149 offset:21504
	ds_read_b128 v[218:221], v149 offset:22528
	ds_read_b128 v[222:225], v149 offset:23552
	global_load_lds_dwordx4 v160, s[10:11]
	s_add_i32 m0, s6, 0x2000
	s_add_u32 s6, s10, 0x160000
	v_lshl_add_u64 v[168:169], s[10:11], 0, v[128:129]
	s_addc_u32 s7, s11, 0
	s_add_i32 s56, s57, s26
	global_load_lds_dwordx4 v128, s[10:11]
	s_mov_b32 m0, s56
	v_lshl_add_u64 v[196:197], s[14:15], 0, v[128:129]
	global_load_lds_dwordx4 v160, s[6:7]
	s_add_i32 m0, s56, 0x2000
	s_nop 0
	global_load_lds_dwordx4 v128, s[6:7]
	v_lshl_add_u64 v[170:171], s[14:15], 0, v[160:161]
	s_mov_b32 m0, s28
	s_nop 0
	global_load_lds_dwordx4 v160, s[14:15]
	s_mov_b32 m0, s29
	s_nop 0
	global_load_lds_dwordx4 v128, s[14:15]
	s_waitcnt vmcnt(8)
	s_waitcnt lgkmcnt(0)
	s_barrier
; #define PG8_STAGE(bufoff, gbase, voff) do { _Pragma("unroll") for (int _i = 0; _i < 2; ++_i) \
;         __builtin_amdgcn_global_load_lds((const unsigned*)((const char*)(gbase) + (voff)[_i]), (LAS unsigned*)(lds + (bufoff) + ldsw + _i * 8192), 16, 0, 0); } while (0)
; #define PG8_LDA(dst, b, h) do { _Pragma("unroll") for (int m = 0; m < 4; ++m) _Pragma("unroll") for (int k = 0; k < 2; ++k) dst[m][k] = *(const LAS bf16x8*)(lds + PG8_SA(b, h) + aoff + m * 2048 + k * 1024); } while (0)
; #define PG8_LDB(dst, b, h) do { _Pragma("unroll") for (int n = 0; n < 2; ++n) _Pragma("unroll") for (int k = 0; k < 2; ++k) dst[n][k] = *(const LAS bf16x8*)(lds + PG8_SB(b, h) + boff + n * 2048 + k * 1024); } while (0)
; #define PG8_MMA(ai, bj, At, Bt) do { __builtin_amdgcn_s_setprio(1); _Pragma("unroll") for (int m = 0; m < 4; ++m) _Pragma("unroll") for (int n = 0; n < 2; ++n) _Pragma("unroll") for (int k = 0; k < 2; ++k) \
;         acc[ai][bj][m][n] = __builtin_amdgcn_mfma_f32_16x16x32_bf16(Bt[n][k], At[m][k], acc[ai][bj][m][n], 0, 0, 0); __builtin_amdgcn_s_setprio(0); } while (0)
; #define PG8_WAIT_V(n) asm volatile("s_waitcnt vmcnt(" #n ")" ::: "memory")
; #define PG8_WAIT_L(n) asm volatile("s_waitcnt lgkmcnt(" #n ")" ::: "memory")
; #define PG8_BAR __builtin_amdgcn_s_barrier()
; #define PG8_SCHED __builtin_amdgcn_sched_barrier(0)
; template <class Epi, int GM, int GN, int GK, int LDA, int AMOD, int ASTRIDE, int WG = WGM>
; __device__ __forceinline__ void gemm_phase(LAS unsigned char* lds, const Gemm g, const Epi& E, int wv_) {
;     ...
;             PG8_WAIT_V(8); PG8_WAIT_L(0); PG8_BAR; PG8_MMA(1, 0, At, B0); PG8_MMA(1, 1, At, B1); PG8_BAR; PG8_SCHED;
;             PG8_LDB(B0, 1, 0); PG8_LDB(B1, 1, 1); PG8_SCHED; PG8_LDA(At, 1, 0); PG8_STAGE(PG8_SA(0, 1), a2 + hstepA, voffA);
;             PG8_WAIT_V(8); PG8_WAIT_L(0); PG8_BAR; PG8_MMA(0, 0, At, B0); PG8_MMA(0, 1, At, B1); PG8_BAR; PG8_SCHED;
	s_setprio 1
	s_waitcnt lgkmcnt(0)
	v_mfma_f32_16x16x32_bf16 v[60:63], v[134:137], v[186:189], v[60:63]
	v_mfma_f32_16x16x32_bf16 v[56:59], v[142:145], v[186:189], v[56:59]
	v_mfma_f32_16x16x32_bf16 v[52:55], v[134:137], v[202:205], v[52:55]
	v_mfma_f32_16x16x32_bf16 v[48:51], v[142:145], v[202:205], v[48:51]
	v_mfma_f32_16x16x32_bf16 v[40:43], v[134:137], v[210:213], v[40:43]
	v_mfma_f32_16x16x32_bf16 v[32:35], v[142:145], v[210:213], v[32:35]
	v_mfma_f32_16x16x32_bf16 v[24:27], v[134:137], v[218:221], v[24:27]
	v_mfma_f32_16x16x32_bf16 v[16:19], v[142:145], v[218:221], v[16:19]
	v_mfma_f32_16x16x32_bf16 v[60:63], v[138:141], v[190:193], v[60:63]
	v_mfma_f32_16x16x32_bf16 v[56:59], v[150:153], v[190:193], v[56:59]
	v_mfma_f32_16x16x32_bf16 v[52:55], v[138:141], v[206:209], v[52:55]
	v_mfma_f32_16x16x32_bf16 v[48:51], v[150:153], v[206:209], v[48:51]
	v_mfma_f32_16x16x32_bf16 v[40:43], v[138:141], v[214:217], v[40:43]
	v_mfma_f32_16x16x32_bf16 v[32:35], v[150:153], v[214:217], v[32:35]
	v_mfma_f32_16x16x32_bf16 v[24:27], v[138:141], v[222:225], v[24:27]
	v_mfma_f32_16x16x32_bf16 v[16:19], v[150:153], v[222:225], v[16:19]
	s_setprio 0
	s_setprio 1
	v_mfma_f32_16x16x32_bf16 v[44:47], v[154:157], v[186:189], v[44:47]
	v_mfma_f32_16x16x32_bf16 v[36:39], v[178:181], v[186:189], v[36:39]
	v_mfma_f32_16x16x32_bf16 v[28:31], v[154:157], v[202:205], v[28:31]
	v_mfma_f32_16x16x32_bf16 v[20:23], v[178:181], v[202:205], v[20:23]
	v_mfma_f32_16x16x32_bf16 v[12:15], v[154:157], v[210:213], v[12:15]
	v_mfma_f32_16x16x32_bf16 v[8:11], v[178:181], v[210:213], v[8:11]
	v_mfma_f32_16x16x32_bf16 v[4:7], v[154:157], v[218:221], v[4:7]
	v_mfma_f32_16x16x32_bf16 v[0:3], v[178:181], v[218:221], v[0:3]
	v_mfma_f32_16x16x32_bf16 v[44:47], v[174:177], v[190:193], v[44:47]
	v_mfma_f32_16x16x32_bf16 v[36:39], v[182:185], v[190:193], v[36:39]
	v_mfma_f32_16x16x32_bf16 v[28:31], v[174:177], v[206:209], v[28:31]
	v_mfma_f32_16x16x32_bf16 v[20:23], v[182:185], v[206:209], v[20:23]
	v_mfma_f32_16x16x32_bf16 v[12:15], v[174:177], v[214:217], v[12:15]
	v_mfma_f32_16x16x32_bf16 v[8:11], v[182:185], v[214:217], v[8:11]
	v_mfma_f32_16x16x32_bf16 v[4:7], v[174:177], v[222:225], v[4:7]
	v_mfma_f32_16x16x32_bf16 v[0:3], v[182:185], v[222:225], v[0:3]
	s_setprio 0
	s_barrier
	s_add_i32 s56, 0, 0x18000
	s_add_i32 s57, 0, 0x1c000
	v_add_u32_e32 v150, s56, v148
	v_add_u32_e32 v182, s57, v148
	ds_read_b128 v[134:137], v150
	ds_read_b128 v[138:141], v150 offset:1024
	ds_read_b128 v[142:145], v150 offset:2048
	ds_read_b128 v[150:153], v150 offset:3072
	ds_read_b128 v[154:157], v182
	ds_read_b128 v[174:177], v182 offset:1024
	ds_read_b128 v[178:181], v182 offset:2048
	ds_read_b128 v[182:185], v182 offset:3072
	s_add_u32 s6, s14, 0x160000
	s_addc_u32 s7, s15, 0
	s_mov_b32 m0, s30
	ds_read_b128 v[186:189], v149 offset:32768
	ds_read_b128 v[190:193], v149 offset:33792
	ds_read_b128 v[202:205], v149 offset:34816
	ds_read_b128 v[206:209], v149 offset:35840
	ds_read_b128 v[210:213], v149 offset:36864
	ds_read_b128 v[214:217], v149 offset:37888
	ds_read_b128 v[218:221], v149 offset:38912
	ds_read_b128 v[222:225], v149 offset:39936
	global_load_lds_dwordx4 v160, s[6:7]
	v_lshl_add_u64 v[198:199], s[6:7], 0, v[128:129]
	s_mov_b32 m0, s31
	s_nop 0
	global_load_lds_dwordx4 v128, s[6:7]
	s_waitcnt vmcnt(8)
	s_waitcnt lgkmcnt(0)
	s_barrier
	s_setprio 1
	s_waitcnt lgkmcnt(0)
	v_mfma_f32_16x16x32_bf16 v[124:127], v[134:137], v[186:189], v[124:127]
	v_mfma_f32_16x16x32_bf16 v[120:123], v[142:145], v[186:189], v[120:123]
	v_mfma_f32_16x16x32_bf16 v[116:119], v[134:137], v[202:205], v[116:119]
	v_mfma_f32_16x16x32_bf16 v[112:115], v[142:145], v[202:205], v[112:115]
	v_mfma_f32_16x16x32_bf16 v[104:107], v[134:137], v[210:213], v[104:107]
	v_mfma_f32_16x16x32_bf16 v[96:99], v[142:145], v[210:213], v[96:99]
	v_mfma_f32_16x16x32_bf16 v[88:91], v[134:137], v[218:221], v[88:91]
	v_mfma_f32_16x16x32_bf16 v[80:83], v[142:145], v[218:221], v[80:83]
	v_mfma_f32_16x16x32_bf16 v[124:127], v[138:141], v[190:193], v[124:127]
	v_mfma_f32_16x16x32_bf16 v[120:123], v[150:153], v[190:193], v[120:123]
	v_mfma_f32_16x16x32_bf16 v[116:119], v[138:141], v[206:209], v[116:119]
	v_mfma_f32_16x16x32_bf16 v[112:115], v[150:153], v[206:209], v[112:115]
	v_mfma_f32_16x16x32_bf16 v[104:107], v[138:141], v[214:217], v[104:107]
	v_mfma_f32_16x16x32_bf16 v[96:99], v[150:153], v[214:217], v[96:99]
	v_mfma_f32_16x16x32_bf16 v[88:91], v[138:141], v[222:225], v[88:91]
	v_mfma_f32_16x16x32_bf16 v[80:83], v[150:153], v[222:225], v[80:83]
	s_setprio 0
	s_setprio 1
	v_mfma_f32_16x16x32_bf16 v[108:111], v[154:157], v[186:189], v[108:111]
	v_mfma_f32_16x16x32_bf16 v[100:103], v[178:181], v[186:189], v[100:103]
	v_mfma_f32_16x16x32_bf16 v[92:95], v[154:157], v[202:205], v[92:95]
	v_mfma_f32_16x16x32_bf16 v[84:87], v[178:181], v[202:205], v[84:87]
	v_mfma_f32_16x16x32_bf16 v[76:79], v[154:157], v[210:213], v[76:79]
	v_mfma_f32_16x16x32_bf16 v[72:75], v[178:181], v[210:213], v[72:75]
	v_mfma_f32_16x16x32_bf16 v[68:71], v[154:157], v[218:221], v[68:71]
	v_mfma_f32_16x16x32_bf16 v[64:67], v[178:181], v[218:221], v[64:67]
	v_mfma_f32_16x16x32_bf16 v[108:111], v[174:177], v[190:193], v[108:111]
	v_mfma_f32_16x16x32_bf16 v[100:103], v[182:185], v[190:193], v[100:103]
	v_mfma_f32_16x16x32_bf16 v[92:95], v[174:177], v[206:209], v[92:95]
	v_mfma_f32_16x16x32_bf16 v[84:87], v[182:185], v[206:209], v[84:87]
	v_mfma_f32_16x16x32_bf16 v[76:79], v[174:177], v[214:217], v[76:79]
	v_mfma_f32_16x16x32_bf16 v[72:75], v[182:185], v[214:217], v[72:75]
	v_mfma_f32_16x16x32_bf16 v[68:71], v[174:177], v[222:225], v[68:71]
	v_mfma_f32_16x16x32_bf16 v[64:67], v[182:185], v[222:225], v[64:67]
	s_setprio 0
	s_barrier
; #define PG8_STAGE(bufoff, gbase, voff) do { _Pragma("unroll") for (int _i = 0; _i < 2; ++_i) \
;         __builtin_amdgcn_global_load_lds((const unsigned*)((const char*)(gbase) + (voff)[_i]), (LAS unsigned*)(lds + (bufoff) + ldsw + _i * 8192), 16, 0, 0); } while (0)
; #define PG8_LDA(dst, b, h) do { _Pragma("unroll") for (int m = 0; m < 4; ++m) _Pragma("unroll") for (int k = 0; k < 2; ++k) dst[m][k] = *(const LAS bf16x8*)(lds + PG8_SA(b, h) + aoff + m * 2048 + k * 1024); } while (0)
; #define PG8_MMA(ai, bj, At, Bt) do { __builtin_amdgcn_s_setprio(1); _Pragma("unroll") for (int m = 0; m < 4; ++m) _Pragma("unroll") for (int n = 0; n < 2; ++n) _Pragma("unroll") for (int k = 0; k < 2; ++k) \
;         acc[ai][bj][m][n] = __builtin_amdgcn_mfma_f32_16x16x32_bf16(Bt[n][k], At[m][k], acc[ai][bj][m][n], 0, 0, 0); __builtin_amdgcn_s_setprio(0); } while (0)
; #define PG8_WAIT_V(n) asm volatile("s_waitcnt vmcnt(" #n ")" ::: "memory")
; #define PG8_WAIT_L(n) asm volatile("s_waitcnt lgkmcnt(" #n ")" ::: "memory")
; #define PG8_BAR __builtin_amdgcn_s_barrier()
; #define PG8_SCHED __builtin_amdgcn_sched_barrier(0)
; template <class Epi, int GM, int GN, int GK, int LDA, int AMOD, int ASTRIDE, int WG = WGM>
; __device__ __forceinline__ void gemm_phase(LAS unsigned char* lds, const Gemm g, const Epi& E, int wv_) {
;     ...
;             PG8_LDA(At, 1, 1); PG8_STAGE(PG8_SB(1, 0), b3, voffB); PG8_STAGE(PG8_SB(1, 1), b3 + hstepB, voffB); PG8_STAGE(PG8_SA(1, 0), a3, voffA);
;             PG8_WAIT_V(8); PG8_WAIT_L(0); PG8_BAR; PG8_MMA(1, 0, At, B0); PG8_MMA(1, 1, At, B1); PG8_BAR; PG8_SCHED;
;         }
	s_add_i32 s6, s56, s26
	v_lshl_add_u64 v[158:159], v[158:159], 0, s[70:71]
	s_mov_b32 m0, s6
	ds_read_b128 v[186:189], v149 offset:49152
	ds_read_b128 v[190:193], v149 offset:50176
	ds_read_b128 v[202:205], v149 offset:51200
	ds_read_b128 v[206:209], v149 offset:52224
	ds_read_b128 v[210:213], v149 offset:53248
	ds_read_b128 v[214:217], v149 offset:54272
	ds_read_b128 v[218:221], v149 offset:55296
	ds_read_b128 v[222:225], v149 offset:56320
	global_load_lds_dwordx4 v[158:159], off
	s_add_i32 m0, s6, 0x2000
	s_add_u32 s6, s10, 0x160080
	v_lshl_add_u64 v[158:159], v[168:169], 0, s[70:71]
	s_addc_u32 s7, s11, 0
	s_add_i32 s10, s57, s26
	global_load_lds_dwordx4 v[158:159], off
	s_mov_b32 m0, s10
	s_nop 0
	global_load_lds_dwordx4 v160, s[6:7]
	s_add_i32 m0, s10, 0x2000
	s_nop 0
	global_load_lds_dwordx4 v128, s[6:7]
	v_lshl_add_u64 v[158:159], v[170:171], 0, s[70:71]
	s_mov_b32 m0, s43
	s_nop 0
	global_load_lds_dwordx4 v[158:159], off
	v_lshl_add_u64 v[158:159], v[196:197], 0, s[70:71]
	s_mov_b32 m0, s46
	s_nop 0
	global_load_lds_dwordx4 v[158:159], off
	s_waitcnt vmcnt(8)
	s_waitcnt lgkmcnt(0)
	s_barrier
	s_setprio 1
	s_waitcnt lgkmcnt(0)
	v_mfma_f32_16x16x32_bf16 v[60:63], v[134:137], v[186:189], v[60:63]
	v_mfma_f32_16x16x32_bf16 v[56:59], v[142:145], v[186:189], v[56:59]
	v_mfma_f32_16x16x32_bf16 v[52:55], v[134:137], v[202:205], v[52:55]
	v_mfma_f32_16x16x32_bf16 v[48:51], v[142:145], v[202:205], v[48:51]
	v_mfma_f32_16x16x32_bf16 v[40:43], v[134:137], v[210:213], v[40:43]
	v_mfma_f32_16x16x32_bf16 v[32:35], v[142:145], v[210:213], v[32:35]
	v_mfma_f32_16x16x32_bf16 v[24:27], v[134:137], v[218:221], v[24:27]
	v_mfma_f32_16x16x32_bf16 v[16:19], v[142:145], v[218:221], v[16:19]
	v_mfma_f32_16x16x32_bf16 v[60:63], v[138:141], v[190:193], v[60:63]
	v_mfma_f32_16x16x32_bf16 v[56:59], v[150:153], v[190:193], v[56:59]
	v_mfma_f32_16x16x32_bf16 v[52:55], v[138:141], v[206:209], v[52:55]
	v_mfma_f32_16x16x32_bf16 v[48:51], v[150:153], v[206:209], v[48:51]
	v_mfma_f32_16x16x32_bf16 v[40:43], v[138:141], v[214:217], v[40:43]
	v_mfma_f32_16x16x32_bf16 v[32:35], v[150:153], v[214:217], v[32:35]
	v_mfma_f32_16x16x32_bf16 v[24:27], v[138:141], v[222:225], v[24:27]
	v_mfma_f32_16x16x32_bf16 v[16:19], v[150:153], v[222:225], v[16:19]
	s_setprio 0
	s_setprio 1
	v_mfma_f32_16x16x32_bf16 v[44:47], v[154:157], v[186:189], v[44:47]
	v_mfma_f32_16x16x32_bf16 v[36:39], v[178:181], v[186:189], v[36:39]
	v_mfma_f32_16x16x32_bf16 v[28:31], v[154:157], v[202:205], v[28:31]
	v_mfma_f32_16x16x32_bf16 v[20:23], v[178:181], v[202:205], v[20:23]
	v_mfma_f32_16x16x32_bf16 v[12:15], v[154:157], v[210:213], v[12:15]
	v_mfma_f32_16x16x32_bf16 v[8:11], v[178:181], v[210:213], v[8:11]
	v_mfma_f32_16x16x32_bf16 v[4:7], v[154:157], v[218:221], v[4:7]
	v_mfma_f32_16x16x32_bf16 v[0:3], v[178:181], v[218:221], v[0:3]
	v_mfma_f32_16x16x32_bf16 v[44:47], v[174:177], v[190:193], v[44:47]
	v_mfma_f32_16x16x32_bf16 v[36:39], v[182:185], v[190:193], v[36:39]
	v_mfma_f32_16x16x32_bf16 v[28:31], v[174:177], v[206:209], v[28:31]
	v_mfma_f32_16x16x32_bf16 v[20:23], v[182:185], v[206:209], v[20:23]
	v_mfma_f32_16x16x32_bf16 v[12:15], v[174:177], v[214:217], v[12:15]
	v_mfma_f32_16x16x32_bf16 v[8:11], v[182:185], v[214:217], v[8:11]
	v_mfma_f32_16x16x32_bf16 v[4:7], v[174:177], v[222:225], v[4:7]
	v_mfma_f32_16x16x32_bf16 v[0:3], v[182:185], v[222:225], v[0:3]
	s_setprio 0
	s_barrier
	s_add_u32 s53, s53, 0x100
	s_addc_u32 s54, s54, 0
	s_cmp_ge_i32 s55, s19
	s_mov_b64 s[6:7], s[8:9]
	s_mov_b32 s10, s55
	s_cbranch_scc0 .LBB0_74
;     __device__ __forceinline__ void operator()(const Acc& acc, const Unit& u, int wr, int wc, int fr, int fq) const {
;     ...
;                 for (int mm = 0; mm < 2; ++mm) { const int m = 2 * mp + mm; const size_t off = (size_t)(ai * HALF + wr * 64 + m * 16 + fr) * DM + col0;
; #pragma unroll
;                     for (int bj = 0; bj < 2; ++bj)
; #pragma unroll
;                         for (int n = 0; n < 2; ++n) *(f32x4*)(ob + off + bj * HALF + n * 16) = bs[mm][bj][n] + acc[ai][bj][m][n] * alpha; }
	v_pk_mul_f32 v[126:127], v[126:127], 0.5 op_sel_hi:[1,0]
	v_pk_mul_f32 v[124:125], v[124:125], 0.5 op_sel_hi:[1,0]
	v_pk_mul_f32 v[122:123], v[122:123], 0.5 op_sel_hi:[1,0]
	v_pk_mul_f32 v[120:121], v[120:121], 0.5 op_sel_hi:[1,0]
	v_pk_mul_f32 v[134:135], v[110:111], 0.5 op_sel_hi:[1,0]
	v_pk_mul_f32 v[136:137], v[108:109], 0.5 op_sel_hi:[1,0]
	v_pk_mul_f32 v[138:139], v[102:103], 0.5 op_sel_hi:[1,0]
	v_pk_mul_f32 v[140:141], v[100:101], 0.5 op_sel_hi:[1,0]
	v_pk_mul_f32 v[108:109], v[118:119], 0.5 op_sel_hi:[1,0]
	v_pk_mul_f32 v[110:111], v[116:117], 0.5 op_sel_hi:[1,0]
	v_pk_mul_f32 v[114:115], v[114:115], 0.5 op_sel_hi:[1,0]
	v_pk_mul_f32 v[112:113], v[112:113], 0.5 op_sel_hi:[1,0]
	v_pk_mul_f32 v[116:117], v[94:95], 0.5 op_sel_hi:[1,0]
	v_pk_mul_f32 v[118:119], v[92:93], 0.5 op_sel_hi:[1,0]
	v_pk_mul_f32 v[142:143], v[86:87], 0.5 op_sel_hi:[1,0]
	v_pk_mul_f32 v[144:145], v[84:85], 0.5 op_sel_hi:[1,0]
	v_pk_mul_f32 v[84:85], v[106:107], 0.5 op_sel_hi:[1,0]
	v_pk_mul_f32 v[86:87], v[104:105], 0.5 op_sel_hi:[1,0]
	v_pk_mul_f32 v[92:93], v[98:99], 0.5 op_sel_hi:[1,0]
	v_pk_mul_f32 v[94:95], v[96:97], 0.5 op_sel_hi:[1,0]
	v_pk_mul_f32 v[96:97], v[78:79], 0.5 op_sel_hi:[1,0]
	v_pk_mul_f32 v[98:99], v[76:77], 0.5 op_sel_hi:[1,0]
	v_pk_mul_f32 v[100:101], v[74:75], 0.5 op_sel_hi:[1,0]
	v_pk_mul_f32 v[102:103], v[72:73], 0.5 op_sel_hi:[1,0]
	v_pk_mul_f32 v[76:77], v[90:91], 0.5 op_sel_hi:[1,0]
	v_pk_mul_f32 v[78:79], v[88:89], 0.5 op_sel_hi:[1,0]
	v_pk_mul_f32 v[82:83], v[82:83], 0.5 op_sel_hi:[1,0]
	v_pk_mul_f32 v[80:81], v[80:81], 0.5 op_sel_hi:[1,0]
	v_pk_mul_f32 v[88:89], v[70:71], 0.5 op_sel_hi:[1,0]
	v_pk_mul_f32 v[90:91], v[68:69], 0.5 op_sel_hi:[1,0]
	v_pk_mul_f32 v[104:105], v[66:67], 0.5 op_sel_hi:[1,0]
	v_pk_mul_f32 v[106:107], v[64:65], 0.5 op_sel_hi:[1,0]
	v_pk_mul_f32 v[62:63], v[62:63], 0.5 op_sel_hi:[1,0]
	v_pk_mul_f32 v[60:61], v[60:61], 0.5 op_sel_hi:[1,0]
	v_pk_mul_f32 v[58:59], v[58:59], 0.5 op_sel_hi:[1,0]
	v_pk_mul_f32 v[56:57], v[56:57], 0.5 op_sel_hi:[1,0]
	v_pk_mul_f32 v[64:65], v[46:47], 0.5 op_sel_hi:[1,0]
	v_pk_mul_f32 v[66:67], v[44:45], 0.5 op_sel_hi:[1,0]
	v_pk_mul_f32 v[68:69], v[38:39], 0.5 op_sel_hi:[1,0]
	v_pk_mul_f32 v[70:71], v[36:37], 0.5 op_sel_hi:[1,0]
	v_pk_mul_f32 v[44:45], v[54:55], 0.5 op_sel_hi:[1,0]
	v_pk_mul_f32 v[46:47], v[52:53], 0.5 op_sel_hi:[1,0]
	v_pk_mul_f32 v[50:51], v[50:51], 0.5 op_sel_hi:[1,0]
	v_pk_mul_f32 v[48:49], v[48:49], 0.5 op_sel_hi:[1,0]
	v_pk_mul_f32 v[52:53], v[30:31], 0.5 op_sel_hi:[1,0]
	v_pk_mul_f32 v[54:55], v[28:29], 0.5 op_sel_hi:[1,0]
	v_pk_mul_f32 v[72:73], v[22:23], 0.5 op_sel_hi:[1,0]
	v_pk_mul_f32 v[74:75], v[20:21], 0.5 op_sel_hi:[1,0]
	v_pk_mul_f32 v[20:21], v[42:43], 0.5 op_sel_hi:[1,0]
	v_pk_mul_f32 v[22:23], v[40:41], 0.5 op_sel_hi:[1,0]
	v_pk_mul_f32 v[28:29], v[34:35], 0.5 op_sel_hi:[1,0]
	v_pk_mul_f32 v[30:31], v[32:33], 0.5 op_sel_hi:[1,0]
	v_pk_mul_f32 v[32:33], v[14:15], 0.5 op_sel_hi:[1,0]
	v_pk_mul_f32 v[34:35], v[12:13], 0.5 op_sel_hi:[1,0]
	v_pk_mul_f32 v[36:37], v[10:11], 0.5 op_sel_hi:[1,0]
	v_pk_mul_f32 v[38:39], v[8:9], 0.5 op_sel_hi:[1,0]
	v_pk_mul_f32 v[14:15], v[26:27], 0.5 op_sel_hi:[1,0]
	v_pk_mul_f32 v[12:13], v[24:25], 0.5 op_sel_hi:[1,0]
	v_pk_mul_f32 v[10:11], v[18:19], 0.5 op_sel_hi:[1,0]
	v_pk_mul_f32 v[8:9], v[16:17], 0.5 op_sel_hi:[1,0]
	v_pk_mul_f32 v[6:7], v[6:7], 0.5 op_sel_hi:[1,0]
	v_pk_mul_f32 v[4:5], v[4:5], 0.5 op_sel_hi:[1,0]
	v_pk_mul_f32 v[2:3], v[2:3], 0.5 op_sel_hi:[1,0]
	v_pk_mul_f32 v[0:1], v[0:1], 0.5 op_sel_hi:[1,0]
	s_and_b64 vcc, exec, s[20:21]
	s_cbranch_vccz .LBB0_77

; #define PG8_STAGE(bufoff, gbase, voff) do { _Pragma("unroll") for (int _i = 0; _i < 2; ++_i) \
;         __builtin_amdgcn_global_load_lds((const unsigned*)((const char*)(gbase) + (voff)[_i]), (LAS unsigned*)(lds + (bufoff) + ldsw + _i * 8192), 16, 0, 0); } while (0)
; #define PG8_WAIT_V(n) asm volatile("s_waitcnt vmcnt(" #n ")" ::: "memory")
; #define PG8_BAR __builtin_amdgcn_s_barrier()
; template <class Epi, int GM, int GN, int GK, int LDA, int AMOD, int ASTRIDE, int WG = WGM>
; __device__ __forceinline__ void gemm_phase(LAS unsigned char* lds, const Gemm g, const Epi& E, int wv_) {
;     ...
;     const char* cA = (const char*)g.A + (size_t)cur.pm * tstepA + PG8_AOFF(cur.pn); const char* cB = (const char*)g.Bt + (size_t)cur.pn * tstepB;
;     PG8_STAGE(PG8_SB(0, 0), cB, voffB); PG8_STAGE(PG8_SB(0, 1), cB + hstepB, voffB); PG8_STAGE(PG8_SA(0, 0), cA, voffA); PG8_STAGE(PG8_SA(0, 1), cA + hstepA, voffA);
;     if (wr == 1) PG8_BAR;
;     PG8_WAIT_V(2); PG8_BAR;
;     PG8_STAGE(PG8_SB(1, 0), cB + kstep, voffB); PG8_STAGE(PG8_SA(1, 0), cA + kstep, voffA); PG8_STAGE(PG8_SB(1, 1), cB + hstepB + kstep, voffB);
;     PG8_WAIT_V(6); PG8_BAR;
.LBB0_97:
	s_lshl_b32 s3, s12, 5
	s_and_b32 s37, s3, 0x60
	s_add_i32 m0, s30, 0x18000
	v_lshl_add_u64 v[6:7], v[6:7], 0, s[70:71]
	s_lshl_b32 s36, s13, 6
	s_lshl_b32 s16, s13, 13
	s_lshl_b32 s17, s37, 7
	s_waitcnt vmcnt(2)
	s_barrier
	global_load_lds_dwordx4 v[6:7], off
	v_lshl_add_u64 v[4:5], v[4:5], 0, s[70:71]
	s_add_i32 m0, s30, 0x1a000
	s_add_i32 s40, s30, 0x8000
	s_add_i32 s41, s30, 0xa000
	global_load_lds_dwordx4 v[4:5], off
	v_lshl_add_u64 v[0:1], v[0:1], 0, s[70:71]
	s_mov_b32 m0, s40
	s_add_u32 s12, s8, 0x80080
	global_load_lds_dwordx4 v[0:1], off
	v_lshl_add_u64 v[0:1], v[2:3], 0, s[70:71]
	s_mov_b32 m0, s41
	s_addc_u32 s13, s9, 0
	global_load_lds_dwordx4 v[0:1], off
	s_add_i32 m0, s30, 0x1c000
	s_nop 0
	global_load_lds_dwordx4 v160, s[12:13]
	v_lshl_add_u64 v[0:1], s[12:13], 0, v[128:129]
	s_add_i32 m0, s30, 0x1e000
	v_bfe_u32 v141, v8, 4, 2
	global_load_lds_dwordx4 v128, s[12:13]
	v_and_b32_e32 v140, 15, v8
	v_lshlrev_b32_e32 v0, 4, v141
	v_lshlrev_b32_e32 v1, 2, v8
	v_lshl_or_b32 v0, v140, 6, v0
	v_and_b32_e32 v1, 32, v1
	v_bitop3_b32 v2, v0, s16, v1 bitop3:0xde
	v_bitop3_b32 v142, s17, v0, v1 bitop3:0xf6
	v_lshlrev_b32_e32 v0, 15, v13
	v_and_b32_e32 v0, 0xffff0000, v0
	v_lshl_add_u32 v0, v12, 12, v0
	v_and_b32_e32 v1, 1, v13
	v_lshl_or_b32 v0, v1, 6, v0
	v_lshl_add_u32 v134, v14, 1, v0
	v_lshlrev_b32_e32 v0, 15, v9
	s_cmp_gt_i32 s15, 0
	v_and_b32_e32 v0, 0xffff0000, v0
	s_waitcnt vmcnt(6)
	s_cselect_b64 s[12:13], -1, 0
	s_add_i32 s43, s15, -2
	v_lshl_add_u32 v0, v10, 12, v0
	v_and_b32_e32 v1, 1, v9
	s_cmpk_lt_u32 s11, 0x100
	v_lshl_or_b32 v0, v1, 6, v0
	s_sext_i32_i16 s3, s10
	s_mov_b32 s42, 0
	s_cselect_b64 s[16:17], -1, 0
	v_mov_b32_e32 v135, v161
	v_lshl_add_u32 v136, v11, 1, v0
	v_mov_b32_e32 v137, v161
	v_add_u32_e32 v143, 0, v2
	s_barrier
	s_branch .LBB0_100

; #define PG8_STAGE(bufoff, gbase, voff) do { _Pragma("unroll") for (int _i = 0; _i < 2; ++_i) \
;         __builtin_amdgcn_global_load_lds((const unsigned*)((const char*)(gbase) + (voff)[_i]), (LAS unsigned*)(lds + (bufoff) + ldsw + _i * 8192), 16, 0, 0); } while (0)
; #define PG8_LDA(dst, b, h) do { _Pragma("unroll") for (int m = 0; m < 4; ++m) _Pragma("unroll") for (int k = 0; k < 2; ++k) dst[m][k] = *(const LAS bf16x8*)(lds + PG8_SA(b, h) + aoff + m * 2048 + k * 1024); } while (0)
; #define PG8_LDB(dst, b, h) do { _Pragma("unroll") for (int n = 0; n < 2; ++n) _Pragma("unroll") for (int k = 0; k < 2; ++k) dst[n][k] = *(const LAS bf16x8*)(lds + PG8_SB(b, h) + boff + n * 2048 + k * 1024); } while (0)
; #define PG8_MMA(ai, bj, At, Bt) do { __builtin_amdgcn_s_setprio(1); _Pragma("unroll") for (int m = 0; m < 4; ++m) _Pragma("unroll") for (int n = 0; n < 2; ++n) _Pragma("unroll") for (int k = 0; k < 2; ++k) \
;         acc[ai][bj][m][n] = __builtin_amdgcn_mfma_f32_16x16x32_bf16(Bt[n][k], At[m][k], acc[ai][bj][m][n], 0, 0, 0); __builtin_amdgcn_s_setprio(0); } while (0)
; #define PG8_WAIT_V(n) asm volatile("s_waitcnt vmcnt(" #n ")" ::: "memory")
; #define PG8_WAIT_L(n) asm volatile("s_waitcnt lgkmcnt(" #n ")" ::: "memory")
; #define PG8_BAR __builtin_amdgcn_s_barrier()
; #define PG8_SCHED __builtin_amdgcn_sched_barrier(0)
; template <class Epi, int GM, int GN, int GK, int LDA, int AMOD, int ASTRIDE, int WG = WGM>
; __device__ __forceinline__ void gemm_phase(LAS unsigned char* lds, const Gemm g, const Epi& E, int wv_) {
;     ...
;             const char* a1 = cA + (size_t)(t + 1) * kstep;
;             const char* a2 = last ? nA : cA + (size_t)(t + 2) * kstep; const char* b2 = last ? nB : cB + (size_t)(t + 2) * kstep;
;             const char* a3 = a2 + kstep; const char* b3 = b2 + kstep;
;             PG8_LDB(B0, 0, 0); PG8_LDB(B1, 0, 1); PG8_SCHED; PG8_LDA(At, 0, 0); PG8_STAGE(PG8_SA(1, 1), a1 + hstepA, voffA);
;             PG8_WAIT_V(8); PG8_WAIT_L(0); PG8_BAR; PG8_MMA(0, 0, At, B0); PG8_MMA(0, 1, At, B1); PG8_BAR; PG8_SCHED;
;             PG8_LDA(At, 0, 1); PG8_STAGE(PG8_SB(0, 0), b2, voffB); PG8_STAGE(PG8_SB(0, 1), b2 + hstepB, voffB); PG8_STAGE(PG8_SA(0, 0), a2, voffA);
;             PG8_WAIT_V(8); PG8_WAIT_L(0); PG8_BAR; PG8_MMA(1, 0, At, B0); PG8_MMA(1, 1, At, B1); PG8_BAR; PG8_SCHED;
.LBB0_104:
	s_add_i32 s48, s8, 2
	s_add_u32 s9, s6, 0xfff80080
	s_addc_u32 s10, s7, -1
	s_add_i32 s49, 0, 0x10000
	s_cmp_eq_u32 s43, s8
	s_cselect_b32 s11, s21, s10
	s_cselect_b32 s10, s23, s9
	v_add_u32_e32 v138, s49, v142
	s_cselect_b32 s9, s44, s47
	s_cselect_b32 s8, s45, s46
	s_add_i32 s52, 0, 0x14000
	ds_read_b128 v[144:147], v138
	ds_read_b128 v[148:151], v138 offset:1024
	ds_read_b128 v[152:155], v138 offset:2048
	ds_read_b128 v[156:159], v138 offset:3072
	v_add_u32_e32 v138, s52, v142
	ds_read_b128 v[174:177], v138
	ds_read_b128 v[178:181], v138 offset:1024
	ds_read_b128 v[182:185], v138 offset:2048
	ds_read_b128 v[186:189], v138 offset:3072
	s_add_i32 m0, s30, 0xc000
	ds_read_b128 v[190:193], v143
	ds_read_b128 v[202:205], v143 offset:1024
	ds_read_b128 v[206:209], v143 offset:2048
	ds_read_b128 v[210:213], v143 offset:3072
	ds_read_b128 v[214:217], v143 offset:4096
	ds_read_b128 v[218:221], v143 offset:5120
	ds_read_b128 v[222:225], v143 offset:6144
	ds_read_b128 v[226:229], v143 offset:7168
	global_load_lds_dwordx4 v134, s[6:7]
	s_add_i32 m0, s30, 0xe000
	s_nop 0
	global_load_lds_dwordx4 v136, s[6:7]
	s_waitcnt vmcnt(8)
	s_waitcnt lgkmcnt(0)
	s_barrier
	s_setprio 1
	s_waitcnt lgkmcnt(0)
	v_mfma_f32_16x16x32_bf16 v[124:127], v[144:147], v[190:193], v[124:127]
	v_mfma_f32_16x16x32_bf16 v[116:119], v[152:155], v[190:193], v[116:119]
	v_mfma_f32_16x16x32_bf16 v[108:111], v[144:147], v[206:209], v[108:111]
	v_mfma_f32_16x16x32_bf16 v[100:103], v[152:155], v[206:209], v[100:103]
	v_mfma_f32_16x16x32_bf16 v[92:95], v[144:147], v[214:217], v[92:95]
	v_mfma_f32_16x16x32_bf16 v[84:87], v[152:155], v[214:217], v[84:87]
	v_mfma_f32_16x16x32_bf16 v[76:79], v[144:147], v[222:225], v[76:79]
	v_mfma_f32_16x16x32_bf16 v[68:71], v[152:155], v[222:225], v[68:71]
	v_mfma_f32_16x16x32_bf16 v[124:127], v[148:151], v[202:205], v[124:127]
	v_mfma_f32_16x16x32_bf16 v[116:119], v[156:159], v[202:205], v[116:119]
	v_mfma_f32_16x16x32_bf16 v[108:111], v[148:151], v[210:213], v[108:111]
	v_mfma_f32_16x16x32_bf16 v[100:103], v[156:159], v[210:213], v[100:103]
	v_mfma_f32_16x16x32_bf16 v[92:95], v[148:151], v[218:221], v[92:95]
	v_mfma_f32_16x16x32_bf16 v[84:87], v[156:159], v[218:221], v[84:87]
	v_mfma_f32_16x16x32_bf16 v[76:79], v[148:151], v[226:229], v[76:79]
	v_mfma_f32_16x16x32_bf16 v[68:71], v[156:159], v[226:229], v[68:71]
	s_setprio 0
	s_setprio 1
	v_mfma_f32_16x16x32_bf16 v[120:123], v[174:177], v[190:193], v[120:123]
	v_mfma_f32_16x16x32_bf16 v[112:115], v[182:185], v[190:193], v[112:115]
	v_mfma_f32_16x16x32_bf16 v[104:107], v[174:177], v[206:209], v[104:107]
	v_mfma_f32_16x16x32_bf16 v[96:99], v[182:185], v[206:209], v[96:99]
	v_mfma_f32_16x16x32_bf16 v[88:91], v[174:177], v[214:217], v[88:91]
	v_mfma_f32_16x16x32_bf16 v[80:83], v[182:185], v[214:217], v[80:83]
	v_mfma_f32_16x16x32_bf16 v[72:75], v[174:177], v[222:225], v[72:75]
	v_mfma_f32_16x16x32_bf16 v[64:67], v[182:185], v[222:225], v[64:67]
	v_mfma_f32_16x16x32_bf16 v[120:123], v[178:181], v[202:205], v[120:123]
	v_mfma_f32_16x16x32_bf16 v[112:115], v[186:189], v[202:205], v[112:115]
	v_mfma_f32_16x16x32_bf16 v[104:107], v[178:181], v[210:213], v[104:107]
	v_mfma_f32_16x16x32_bf16 v[96:99], v[186:189], v[210:213], v[96:99]
	v_mfma_f32_16x16x32_bf16 v[88:91], v[178:181], v[218:221], v[88:91]
	v_mfma_f32_16x16x32_bf16 v[80:83], v[186:189], v[218:221], v[80:83]
	v_mfma_f32_16x16x32_bf16 v[72:75], v[178:181], v[226:229], v[72:75]
	v_mfma_f32_16x16x32_bf16 v[64:67], v[186:189], v[226:229], v[64:67]
	s_setprio 0
	s_barrier
	s_add_i32 s49, s49, s28
	v_lshl_add_u64 v[138:139], s[8:9], 0, v[160:161]
	s_mov_b32 m0, s49
	ds_read_b128 v[190:193], v143 offset:16384
	ds_read_b128 v[202:205], v143 offset:17408
	ds_read_b128 v[206:209], v143 offset:18432
	ds_read_b128 v[210:213], v143 offset:19456
	ds_read_b128 v[214:217], v143 offset:20480
	ds_read_b128 v[218:221], v143 offset:21504
	ds_read_b128 v[222:225], v143 offset:22528
	ds_read_b128 v[226:229], v143 offset:23552
	global_load_lds_dwordx4 v160, s[8:9]
	s_add_i32 m0, s49, 0x2000
	s_add_u32 s50, s8, 0x80000
	v_lshl_add_u64 v[168:169], s[8:9], 0, v[128:129]
	s_addc_u32 s51, s9, 0
	s_add_i32 s49, s52, s28
	global_load_lds_dwordx4 v128, s[8:9]
	s_mov_b32 m0, s49
	v_lshl_add_u64 v[196:197], s[10:11], 0, v[130:131]
	global_load_lds_dwordx4 v160, s[50:51]
	s_add_i32 m0, s49, 0x2000
	s_nop 0
	global_load_lds_dwordx4 v128, s[50:51]
	v_lshl_add_u64 v[170:171], s[10:11], 0, v[132:133]
	s_mov_b32 m0, s30
	s_nop 0
	global_load_lds_dwordx4 v132, s[10:11]
	s_mov_b32 m0, s31
	s_nop 0
	global_load_lds_dwordx4 v130, s[10:11]
	s_waitcnt vmcnt(8)
	s_waitcnt lgkmcnt(0)
	s_barrier
; #define PG8_STAGE(bufoff, gbase, voff) do { _Pragma("unroll") for (int _i = 0; _i < 2; ++_i) \
;         __builtin_amdgcn_global_load_lds((const unsigned*)((const char*)(gbase) + (voff)[_i]), (LAS unsigned*)(lds + (bufoff) + ldsw + _i * 8192), 16, 0, 0); } while (0)
; #define PG8_LDA(dst, b, h) do { _Pragma("unroll") for (int m = 0; m < 4; ++m) _Pragma("unroll") for (int k = 0; k < 2; ++k) dst[m][k] = *(const LAS bf16x8*)(lds + PG8_SA(b, h) + aoff + m * 2048 + k * 1024); } while (0)
; #define PG8_LDB(dst, b, h) do { _Pragma("unroll") for (int n = 0; n < 2; ++n) _Pragma("unroll") for (int k = 0; k < 2; ++k) dst[n][k] = *(const LAS bf16x8*)(lds + PG8_SB(b, h) + boff + n * 2048 + k * 1024); } while (0)
; #define PG8_MMA(ai, bj, At, Bt) do { __builtin_amdgcn_s_setprio(1); _Pragma("unroll") for (int m = 0; m < 4; ++m) _Pragma("unroll") for (int n = 0; n < 2; ++n) _Pragma("unroll") for (int k = 0; k < 2; ++k) \
;         acc[ai][bj][m][n] = __builtin_amdgcn_mfma_f32_16x16x32_bf16(Bt[n][k], At[m][k], acc[ai][bj][m][n], 0, 0, 0); __builtin_amdgcn_s_setprio(0); } while (0)
; #define PG8_WAIT_V(n) asm volatile("s_waitcnt vmcnt(" #n ")" ::: "memory")
; #define PG8_WAIT_L(n) asm volatile("s_waitcnt lgkmcnt(" #n ")" ::: "memory")
; #define PG8_BAR __builtin_amdgcn_s_barrier()
; #define PG8_SCHED __builtin_amdgcn_sched_barrier(0)
; template <class Epi, int GM, int GN, int GK, int LDA, int AMOD, int ASTRIDE, int WG = WGM>
; __device__ __forceinline__ void gemm_phase(LAS unsigned char* lds, const Gemm g, const Epi& E, int wv_) {
;     ...
;             PG8_WAIT_V(8); PG8_WAIT_L(0); PG8_BAR; PG8_MMA(1, 0, At, B0); PG8_MMA(1, 1, At, B1); PG8_BAR; PG8_SCHED;
;             PG8_LDB(B0, 1, 0); PG8_LDB(B1, 1, 1); PG8_SCHED; PG8_LDA(At, 1, 0); PG8_STAGE(PG8_SA(0, 1), a2 + hstepA, voffA);
;             PG8_WAIT_V(8); PG8_WAIT_L(0); PG8_BAR; PG8_MMA(0, 0, At, B0); PG8_MMA(0, 1, At, B1); PG8_BAR; PG8_SCHED;
	s_setprio 1
	s_waitcnt lgkmcnt(0)
	v_mfma_f32_16x16x32_bf16 v[60:63], v[144:147], v[190:193], v[60:63]
	v_mfma_f32_16x16x32_bf16 v[52:55], v[152:155], v[190:193], v[52:55]
	v_mfma_f32_16x16x32_bf16 v[44:47], v[144:147], v[206:209], v[44:47]
	v_mfma_f32_16x16x32_bf16 v[36:39], v[152:155], v[206:209], v[36:39]
	v_mfma_f32_16x16x32_bf16 v[28:31], v[144:147], v[214:217], v[28:31]
	v_mfma_f32_16x16x32_bf16 v[20:23], v[152:155], v[214:217], v[20:23]
	v_mfma_f32_16x16x32_bf16 v[12:15], v[144:147], v[222:225], v[12:15]
	v_mfma_f32_16x16x32_bf16 v[4:7], v[152:155], v[222:225], v[4:7]
	v_mfma_f32_16x16x32_bf16 v[60:63], v[148:151], v[202:205], v[60:63]
	v_mfma_f32_16x16x32_bf16 v[52:55], v[156:159], v[202:205], v[52:55]
	v_mfma_f32_16x16x32_bf16 v[44:47], v[148:151], v[210:213], v[44:47]
	v_mfma_f32_16x16x32_bf16 v[36:39], v[156:159], v[210:213], v[36:39]
	v_mfma_f32_16x16x32_bf16 v[28:31], v[148:151], v[218:221], v[28:31]
	v_mfma_f32_16x16x32_bf16 v[20:23], v[156:159], v[218:221], v[20:23]
	v_mfma_f32_16x16x32_bf16 v[12:15], v[148:151], v[226:229], v[12:15]
	v_mfma_f32_16x16x32_bf16 v[4:7], v[156:159], v[226:229], v[4:7]
	s_setprio 0
	s_setprio 1
	v_mfma_f32_16x16x32_bf16 v[56:59], v[174:177], v[190:193], v[56:59]
	v_mfma_f32_16x16x32_bf16 v[48:51], v[182:185], v[190:193], v[48:51]
	v_mfma_f32_16x16x32_bf16 v[40:43], v[174:177], v[206:209], v[40:43]
	v_mfma_f32_16x16x32_bf16 v[32:35], v[182:185], v[206:209], v[32:35]
	v_mfma_f32_16x16x32_bf16 v[24:27], v[174:177], v[214:217], v[24:27]
	v_mfma_f32_16x16x32_bf16 v[16:19], v[182:185], v[214:217], v[16:19]
	v_mfma_f32_16x16x32_bf16 v[8:11], v[174:177], v[222:225], v[8:11]
	v_mfma_f32_16x16x32_bf16 v[0:3], v[182:185], v[222:225], v[0:3]
	v_mfma_f32_16x16x32_bf16 v[56:59], v[178:181], v[202:205], v[56:59]
	v_mfma_f32_16x16x32_bf16 v[48:51], v[186:189], v[202:205], v[48:51]
	v_mfma_f32_16x16x32_bf16 v[40:43], v[178:181], v[210:213], v[40:43]
	v_mfma_f32_16x16x32_bf16 v[32:35], v[186:189], v[210:213], v[32:35]
	v_mfma_f32_16x16x32_bf16 v[24:27], v[178:181], v[218:221], v[24:27]
	v_mfma_f32_16x16x32_bf16 v[16:19], v[186:189], v[218:221], v[16:19]
	v_mfma_f32_16x16x32_bf16 v[8:11], v[178:181], v[226:229], v[8:11]
	v_mfma_f32_16x16x32_bf16 v[0:3], v[186:189], v[226:229], v[0:3]
	s_setprio 0
	s_barrier
	s_add_i32 s49, 0, 0x18000
	s_add_i32 s50, 0, 0x1c000
	v_add_u32_e32 v156, s49, v142
	v_add_u32_e32 v186, s50, v142
	ds_read_b128 v[144:147], v156
	ds_read_b128 v[148:151], v156 offset:1024
	ds_read_b128 v[152:155], v156 offset:2048
	ds_read_b128 v[156:159], v156 offset:3072
	ds_read_b128 v[174:177], v186
	ds_read_b128 v[178:181], v186 offset:1024
	ds_read_b128 v[182:185], v186 offset:2048
	ds_read_b128 v[186:189], v186 offset:3072
	s_add_u32 s10, s10, 0x80000
	s_addc_u32 s11, s11, 0
	s_mov_b32 m0, s34
	ds_read_b128 v[190:193], v143 offset:32768
	ds_read_b128 v[202:205], v143 offset:33792
	ds_read_b128 v[206:209], v143 offset:34816
	ds_read_b128 v[210:213], v143 offset:35840
	ds_read_b128 v[214:217], v143 offset:36864
	ds_read_b128 v[218:221], v143 offset:37888
	ds_read_b128 v[222:225], v143 offset:38912
	ds_read_b128 v[226:229], v143 offset:39936
	global_load_lds_dwordx4 v132, s[10:11]
	v_lshl_add_u64 v[198:199], s[10:11], 0, v[130:131]
	s_mov_b32 m0, s35
	s_nop 0
	global_load_lds_dwordx4 v130, s[10:11]
	s_waitcnt vmcnt(8)
	s_waitcnt lgkmcnt(0)
	s_barrier
	s_setprio 1
	s_waitcnt lgkmcnt(0)
	v_mfma_f32_16x16x32_bf16 v[124:127], v[144:147], v[190:193], v[124:127]
	v_mfma_f32_16x16x32_bf16 v[116:119], v[152:155], v[190:193], v[116:119]
	v_mfma_f32_16x16x32_bf16 v[108:111], v[144:147], v[206:209], v[108:111]
	v_mfma_f32_16x16x32_bf16 v[100:103], v[152:155], v[206:209], v[100:103]
	v_mfma_f32_16x16x32_bf16 v[92:95], v[144:147], v[214:217], v[92:95]
	v_mfma_f32_16x16x32_bf16 v[84:87], v[152:155], v[214:217], v[84:87]
	v_mfma_f32_16x16x32_bf16 v[76:79], v[144:147], v[222:225], v[76:79]
	v_mfma_f32_16x16x32_bf16 v[68:71], v[152:155], v[222:225], v[68:71]
	v_mfma_f32_16x16x32_bf16 v[124:127], v[148:151], v[202:205], v[124:127]
	v_mfma_f32_16x16x32_bf16 v[116:119], v[156:159], v[202:205], v[116:119]
	v_mfma_f32_16x16x32_bf16 v[108:111], v[148:151], v[210:213], v[108:111]
	v_mfma_f32_16x16x32_bf16 v[100:103], v[156:159], v[210:213], v[100:103]
	v_mfma_f32_16x16x32_bf16 v[92:95], v[148:151], v[218:221], v[92:95]
	v_mfma_f32_16x16x32_bf16 v[84:87], v[156:159], v[218:221], v[84:87]
	v_mfma_f32_16x16x32_bf16 v[76:79], v[148:151], v[226:229], v[76:79]
	v_mfma_f32_16x16x32_bf16 v[68:71], v[156:159], v[226:229], v[68:71]
	s_setprio 0
	s_setprio 1
	v_mfma_f32_16x16x32_bf16 v[120:123], v[174:177], v[190:193], v[120:123]
	v_mfma_f32_16x16x32_bf16 v[112:115], v[182:185], v[190:193], v[112:115]
	v_mfma_f32_16x16x32_bf16 v[104:107], v[174:177], v[206:209], v[104:107]
	v_mfma_f32_16x16x32_bf16 v[96:99], v[182:185], v[206:209], v[96:99]
	v_mfma_f32_16x16x32_bf16 v[88:91], v[174:177], v[214:217], v[88:91]
	v_mfma_f32_16x16x32_bf16 v[80:83], v[182:185], v[214:217], v[80:83]
	v_mfma_f32_16x16x32_bf16 v[72:75], v[174:177], v[222:225], v[72:75]
	v_mfma_f32_16x16x32_bf16 v[64:67], v[182:185], v[222:225], v[64:67]
	v_mfma_f32_16x16x32_bf16 v[120:123], v[178:181], v[202:205], v[120:123]
	v_mfma_f32_16x16x32_bf16 v[112:115], v[186:189], v[202:205], v[112:115]
	v_mfma_f32_16x16x32_bf16 v[104:107], v[178:181], v[210:213], v[104:107]
	v_mfma_f32_16x16x32_bf16 v[96:99], v[186:189], v[210:213], v[96:99]
	v_mfma_f32_16x16x32_bf16 v[88:91], v[178:181], v[218:221], v[88:91]
	v_mfma_f32_16x16x32_bf16 v[80:83], v[186:189], v[218:221], v[80:83]
	v_mfma_f32_16x16x32_bf16 v[72:75], v[178:181], v[226:229], v[72:75]
	v_mfma_f32_16x16x32_bf16 v[64:67], v[186:189], v[226:229], v[64:67]
	s_setprio 0
	s_barrier
; #define PG8_STAGE(bufoff, gbase, voff) do { _Pragma("unroll") for (int _i = 0; _i < 2; ++_i) \
;         __builtin_amdgcn_global_load_lds((const unsigned*)((const char*)(gbase) + (voff)[_i]), (LAS unsigned*)(lds + (bufoff) + ldsw + _i * 8192), 16, 0, 0); } while (0)
; #define PG8_LDA(dst, b, h) do { _Pragma("unroll") for (int m = 0; m < 4; ++m) _Pragma("unroll") for (int k = 0; k < 2; ++k) dst[m][k] = *(const LAS bf16x8*)(lds + PG8_SA(b, h) + aoff + m * 2048 + k * 1024); } while (0)
; #define PG8_MMA(ai, bj, At, Bt) do { __builtin_amdgcn_s_setprio(1); _Pragma("unroll") for (int m = 0; m < 4; ++m) _Pragma("unroll") for (int n = 0; n < 2; ++n) _Pragma("unroll") for (int k = 0; k < 2; ++k) \
;         acc[ai][bj][m][n] = __builtin_amdgcn_mfma_f32_16x16x32_bf16(Bt[n][k], At[m][k], acc[ai][bj][m][n], 0, 0, 0); __builtin_amdgcn_s_setprio(0); } while (0)
; #define PG8_WAIT_V(n) asm volatile("s_waitcnt vmcnt(" #n ")" ::: "memory")
; #define PG8_WAIT_L(n) asm volatile("s_waitcnt lgkmcnt(" #n ")" ::: "memory")
; #define PG8_BAR __builtin_amdgcn_s_barrier()
; #define PG8_SCHED __builtin_amdgcn_sched_barrier(0)
; template <class Epi, int GM, int GN, int GK, int LDA, int AMOD, int ASTRIDE, int WG = WGM>
; __device__ __forceinline__ void gemm_phase(LAS unsigned char* lds, const Gemm g, const Epi& E, int wv_) {
;     ...
;             PG8_LDA(At, 1, 1); PG8_STAGE(PG8_SB(1, 0), b3, voffB); PG8_STAGE(PG8_SB(1, 1), b3 + hstepB, voffB); PG8_STAGE(PG8_SA(1, 0), a3, voffA);
;             PG8_WAIT_V(8); PG8_WAIT_L(0); PG8_BAR; PG8_MMA(1, 0, At, B0); PG8_MMA(1, 1, At, B1); PG8_BAR; PG8_SCHED;
;         }
	s_add_i32 s10, s49, s28
	v_lshl_add_u64 v[138:139], v[138:139], 0, s[70:71]
	s_mov_b32 m0, s10
	ds_read_b128 v[190:193], v143 offset:49152
	ds_read_b128 v[202:205], v143 offset:50176
	ds_read_b128 v[206:209], v143 offset:51200
	ds_read_b128 v[210:213], v143 offset:52224
	ds_read_b128 v[214:217], v143 offset:53248
	ds_read_b128 v[218:221], v143 offset:54272
	ds_read_b128 v[222:225], v143 offset:55296
	ds_read_b128 v[226:229], v143 offset:56320
	global_load_lds_dwordx4 v[138:139], off
	s_add_i32 m0, s10, 0x2000
	s_add_u32 s8, s8, 0x80080
	v_lshl_add_u64 v[138:139], v[168:169], 0, s[70:71]
	s_addc_u32 s9, s9, 0
	s_add_i32 s10, s50, s28
	global_load_lds_dwordx4 v[138:139], off
	s_mov_b32 m0, s10
	s_nop 0
	global_load_lds_dwordx4 v160, s[8:9]
	s_add_i32 m0, s10, 0x2000
	s_nop 0
	global_load_lds_dwordx4 v128, s[8:9]
	v_lshl_add_u64 v[138:139], v[170:171], 0, s[70:71]
	s_mov_b32 m0, s40
	s_nop 0
	global_load_lds_dwordx4 v[138:139], off
	v_lshl_add_u64 v[138:139], v[196:197], 0, s[70:71]
	s_mov_b32 m0, s41
	s_nop 0
	global_load_lds_dwordx4 v[138:139], off
	s_waitcnt vmcnt(8)
	s_waitcnt lgkmcnt(0)
	s_barrier
	s_setprio 1
	s_waitcnt lgkmcnt(0)
	v_mfma_f32_16x16x32_bf16 v[60:63], v[144:147], v[190:193], v[60:63]
	v_mfma_f32_16x16x32_bf16 v[52:55], v[152:155], v[190:193], v[52:55]
	v_mfma_f32_16x16x32_bf16 v[44:47], v[144:147], v[206:209], v[44:47]
	v_mfma_f32_16x16x32_bf16 v[36:39], v[152:155], v[206:209], v[36:39]
	v_mfma_f32_16x16x32_bf16 v[28:31], v[144:147], v[214:217], v[28:31]
	v_mfma_f32_16x16x32_bf16 v[20:23], v[152:155], v[214:217], v[20:23]
	v_mfma_f32_16x16x32_bf16 v[12:15], v[144:147], v[222:225], v[12:15]
	v_mfma_f32_16x16x32_bf16 v[4:7], v[152:155], v[222:225], v[4:7]
	v_mfma_f32_16x16x32_bf16 v[60:63], v[148:151], v[202:205], v[60:63]
	v_mfma_f32_16x16x32_bf16 v[52:55], v[156:159], v[202:205], v[52:55]
	v_mfma_f32_16x16x32_bf16 v[44:47], v[148:151], v[210:213], v[44:47]
	v_mfma_f32_16x16x32_bf16 v[36:39], v[156:159], v[210:213], v[36:39]
	v_mfma_f32_16x16x32_bf16 v[28:31], v[148:151], v[218:221], v[28:31]
	v_mfma_f32_16x16x32_bf16 v[20:23], v[156:159], v[218:221], v[20:23]
	v_mfma_f32_16x16x32_bf16 v[12:15], v[148:151], v[226:229], v[12:15]
	v_mfma_f32_16x16x32_bf16 v[4:7], v[156:159], v[226:229], v[4:7]
	s_setprio 0
	s_setprio 1
	v_mfma_f32_16x16x32_bf16 v[56:59], v[174:177], v[190:193], v[56:59]
	v_mfma_f32_16x16x32_bf16 v[48:51], v[182:185], v[190:193], v[48:51]
	v_mfma_f32_16x16x32_bf16 v[40:43], v[174:177], v[206:209], v[40:43]
	v_mfma_f32_16x16x32_bf16 v[32:35], v[182:185], v[206:209], v[32:35]
	v_mfma_f32_16x16x32_bf16 v[24:27], v[174:177], v[214:217], v[24:27]
	v_mfma_f32_16x16x32_bf16 v[16:19], v[182:185], v[214:217], v[16:19]
	v_mfma_f32_16x16x32_bf16 v[8:11], v[174:177], v[222:225], v[8:11]
	v_mfma_f32_16x16x32_bf16 v[0:3], v[182:185], v[222:225], v[0:3]
	v_mfma_f32_16x16x32_bf16 v[56:59], v[178:181], v[202:205], v[56:59]
	v_mfma_f32_16x16x32_bf16 v[48:51], v[186:189], v[202:205], v[48:51]
	v_mfma_f32_16x16x32_bf16 v[40:43], v[178:181], v[210:213], v[40:43]
	v_mfma_f32_16x16x32_bf16 v[32:35], v[186:189], v[210:213], v[32:35]
	v_mfma_f32_16x16x32_bf16 v[24:27], v[178:181], v[218:221], v[24:27]
	v_mfma_f32_16x16x32_bf16 v[16:19], v[186:189], v[218:221], v[16:19]
	v_mfma_f32_16x16x32_bf16 v[8:11], v[178:181], v[226:229], v[8:11]
	v_mfma_f32_16x16x32_bf16 v[0:3], v[186:189], v[226:229], v[0:3]
	s_setprio 0
	s_barrier
	s_add_u32 s6, s6, 0x100
	s_addc_u32 s7, s7, 0
	s_add_u32 s46, s46, 0x100
	s_addc_u32 s47, s47, 0
	s_cmp_ge_i32 s48, s15
	s_mov_b32 s8, s48
	s_cbranch_scc0 .LBB0_104
	s_and_b64 vcc, exec, s[16:17]
	s_cbranch_vccz .LBB0_107

; #define PG8_STAGE(bufoff, gbase, voff) do { _Pragma("unroll") for (int _i = 0; _i < 2; ++_i) \
;         __builtin_amdgcn_global_load_lds((const unsigned*)((const char*)(gbase) + (voff)[_i]), (LAS unsigned*)(lds + (bufoff) + ldsw + _i * 8192), 16, 0, 0); } while (0)
; #define PG8_WAIT_V(n) asm volatile("s_waitcnt vmcnt(" #n ")" ::: "memory")
; #define PG8_BAR __builtin_amdgcn_s_barrier()
; template <class Epi, int GM, int GN, int GK, int LDA, int AMOD, int ASTRIDE, int WG = WGM>
; __device__ __forceinline__ void gemm_phase(LAS unsigned char* lds, const Gemm g, const Epi& E, int wv_) {
;     ...
;     const char* cA = (const char*)g.A + (size_t)cur.pm * tstepA + PG8_AOFF(cur.pn); const char* cB = (const char*)g.Bt + (size_t)cur.pn * tstepB;
;     PG8_STAGE(PG8_SB(0, 0), cB, voffB); PG8_STAGE(PG8_SB(0, 1), cB + hstepB, voffB); PG8_STAGE(PG8_SA(0, 0), cA, voffA); PG8_STAGE(PG8_SA(0, 1), cA + hstepA, voffA);
;     if (wr == 1) PG8_BAR;
;     PG8_WAIT_V(2); PG8_BAR;
;     PG8_STAGE(PG8_SB(1, 0), cB + kstep, voffB); PG8_STAGE(PG8_SA(1, 0), cA + kstep, voffA); PG8_STAGE(PG8_SB(1, 1), cB + hstepB + kstep, voffB);
;     PG8_WAIT_V(6); PG8_BAR;
.LBB0_125:
	v_readlane_b32 s6, v254, 41
	v_readlane_b32 s7, v254, 42
	s_mov_b32 s14, s6
	s_ashr_i32 s15, s6, 31
	v_writelane_b32 v254, s6, 41
	v_lshl_add_u64 v[6:7], v[6:7], 0, s[70:71]
	s_waitcnt vmcnt(2)
	s_barrier
	v_writelane_b32 v254, s7, 42
	s_lshl_b64 s[6:7], s[14:15], 25
	v_readlane_b32 s14, v251, 5
	v_readlane_b32 s15, v251, 6
	s_add_u32 s44, s14, s6
	s_addc_u32 s45, s15, s7
	s_lshl_b32 s24, s4, 6
	s_lshl_b32 s6, s4, 13
	s_lshl_b32 s4, s5, 5
	s_and_b32 s25, s4, 0x60
	s_add_i32 m0, s20, 0x18000
	s_lshl_b32 s7, s25, 7
	global_load_lds_dwordx4 v[6:7], off
	v_lshl_add_u64 v[4:5], v[4:5], 0, s[70:71]
	s_add_i32 m0, s20, 0x1a000
	s_add_i32 s26, s20, 0x8000
	s_add_i32 s27, s20, 0xa000
	global_load_lds_dwordx4 v[4:5], off
	v_lshl_add_u64 v[0:1], v[0:1], 0, s[70:71]
	s_mov_b32 m0, s26
	s_add_u32 s4, s12, 0x80080
	global_load_lds_dwordx4 v[0:1], off
	v_lshl_add_u64 v[0:1], v[2:3], 0, s[70:71]
	s_mov_b32 m0, s27
	s_addc_u32 s5, s13, 0
	global_load_lds_dwordx4 v[0:1], off
	s_add_i32 m0, s20, 0x1c000
	s_nop 0
	global_load_lds_dwordx4 v160, s[4:5]
	v_lshl_add_u64 v[0:1], s[4:5], 0, v[132:133]
	s_add_i32 m0, s20, 0x1e000
	v_bfe_u32 v151, v8, 4, 2
	global_load_lds_dwordx4 v132, s[4:5]
	v_and_b32_e32 v150, 15, v8
	v_lshlrev_b32_e32 v0, 4, v151
	v_lshlrev_b32_e32 v1, 2, v8
	v_lshl_or_b32 v0, v150, 6, v0
	v_and_b32_e32 v1, 32, v1
	v_bitop3_b32 v2, v0, s6, v1 bitop3:0xde
	v_bitop3_b32 v152, s7, v0, v1 bitop3:0xf6
	v_lshlrev_b32_e32 v0, 15, v9
	v_and_b32_e32 v0, 0xffff0000, v0
	v_lshl_add_u32 v0, v10, 12, v0
	v_and_b32_e32 v1, 1, v9
	v_lshl_or_b32 v0, v1, 6, v0
	v_lshl_add_u32 v134, v11, 1, v0
	v_lshlrev_b32_e32 v0, 15, v12
	s_cmp_gt_i32 s17, 0
	v_and_b32_e32 v0, 0xffff0000, v0
	s_waitcnt vmcnt(6)
	s_cselect_b64 s[46:47], -1, 0
	s_add_i32 s29, s17, -2
	v_lshl_add_u32 v0, v13, 12, v0
	v_and_b32_e32 v1, 1, v12
	s_cmpk_lt_u32 s3, 0x100
	v_lshl_or_b32 v0, v1, 6, v0
	s_sext_i32_i8 s9, s2
	s_mov_b32 s28, 0
	s_cselect_b64 s[2:3], -1, 0
	v_mov_b32_e32 v135, v161
	v_lshl_add_u32 v136, v14, 1, v0
	v_mov_b32_e32 v137, v161
	v_add_u32_e32 v153, 0, v2
	s_barrier
	s_branch .LBB0_128

; #define PG8_STAGE(bufoff, gbase, voff) do { _Pragma("unroll") for (int _i = 0; _i < 2; ++_i) \
;         __builtin_amdgcn_global_load_lds((const unsigned*)((const char*)(gbase) + (voff)[_i]), (LAS unsigned*)(lds + (bufoff) + ldsw + _i * 8192), 16, 0, 0); } while (0)
; #define PG8_LDA(dst, b, h) do { _Pragma("unroll") for (int m = 0; m < 4; ++m) _Pragma("unroll") for (int k = 0; k < 2; ++k) dst[m][k] = *(const LAS bf16x8*)(lds + PG8_SA(b, h) + aoff + m * 2048 + k * 1024); } while (0)
; #define PG8_LDB(dst, b, h) do { _Pragma("unroll") for (int n = 0; n < 2; ++n) _Pragma("unroll") for (int k = 0; k < 2; ++k) dst[n][k] = *(const LAS bf16x8*)(lds + PG8_SB(b, h) + boff + n * 2048 + k * 1024); } while (0)
; #define PG8_MMA(ai, bj, At, Bt) do { __builtin_amdgcn_s_setprio(1); _Pragma("unroll") for (int m = 0; m < 4; ++m) _Pragma("unroll") for (int n = 0; n < 2; ++n) _Pragma("unroll") for (int k = 0; k < 2; ++k) \
;         acc[ai][bj][m][n] = __builtin_amdgcn_mfma_f32_16x16x32_bf16(Bt[n][k], At[m][k], acc[ai][bj][m][n], 0, 0, 0); __builtin_amdgcn_s_setprio(0); } while (0)
; #define PG8_WAIT_V(n) asm volatile("s_waitcnt vmcnt(" #n ")" ::: "memory")
; #define PG8_WAIT_L(n) asm volatile("s_waitcnt lgkmcnt(" #n ")" ::: "memory")
; #define PG8_BAR __builtin_amdgcn_s_barrier()
; #define PG8_SCHED __builtin_amdgcn_sched_barrier(0)
; template <class Epi, int GM, int GN, int GK, int LDA, int AMOD, int ASTRIDE, int WG = WGM>
; __device__ __forceinline__ void gemm_phase(LAS unsigned char* lds, const Gemm g, const Epi& E, int wv_) {
;     ...
;             const char* a1 = cA + (size_t)(t + 1) * kstep;
;             const char* a2 = last ? nA : cA + (size_t)(t + 2) * kstep; const char* b2 = last ? nB : cB + (size_t)(t + 2) * kstep;
;             const char* a3 = a2 + kstep; const char* b3 = b2 + kstep;
;             PG8_LDB(B0, 0, 0); PG8_LDB(B1, 0, 1); PG8_SCHED; PG8_LDA(At, 0, 0); PG8_STAGE(PG8_SA(1, 1), a1 + hstepA, voffA);
;             PG8_WAIT_V(8); PG8_WAIT_L(0); PG8_BAR; PG8_MMA(0, 0, At, B0); PG8_MMA(0, 1, At, B1); PG8_BAR; PG8_SCHED;
;             PG8_LDA(At, 0, 1); PG8_STAGE(PG8_SB(0, 0), b2, voffB); PG8_STAGE(PG8_SB(0, 1), b2 + hstepB, voffB); PG8_STAGE(PG8_SA(0, 0), a2, voffA);
;             PG8_WAIT_V(8); PG8_WAIT_L(0); PG8_BAR; PG8_MMA(1, 0, At, B0); PG8_MMA(1, 1, At, B1); PG8_BAR; PG8_SCHED;
.LBB0_136:
	s_add_i32 s37, s12, 2
	s_add_u32 s13, s10, 0xfff80080
	s_addc_u32 s14, s11, -1
	s_add_i32 s40, 0, 0x10000
	s_cmp_eq_u32 s29, s12
	s_cselect_b32 s15, s5, s14
	s_cselect_b32 s14, s30, s13
	s_cselect_b32 s13, s31, s36
	s_cselect_b32 s12, s34, s35
	s_add_i32 s42, 0, 0x14000
	v_add_u32_e32 v154, s40, v152
	v_add_u32_e32 v158, s42, v152
	ds_read_b128 v[138:141], v154
	ds_read_b128 v[142:145], v154 offset:1024
	ds_read_b128 v[146:149], v154 offset:2048
	ds_read_b128 v[154:157], v154 offset:3072
	ds_read_b128 v[168:171], v158
	ds_read_b128 v[174:177], v158 offset:1024
	ds_read_b128 v[178:181], v158 offset:2048
	ds_read_b128 v[182:185], v158 offset:3072
	s_add_i32 m0, s20, 0xc000
	ds_read_b128 v[186:189], v153
	ds_read_b128 v[190:193], v153 offset:1024
	ds_read_b128 v[196:199], v153 offset:2048
	ds_read_b128 v[202:205], v153 offset:3072
	ds_read_b128 v[206:209], v153 offset:4096
	ds_read_b128 v[210:213], v153 offset:5120
	ds_read_b128 v[214:217], v153 offset:6144
	ds_read_b128 v[218:221], v153 offset:7168
	global_load_lds_dwordx4 v134, s[10:11]
	s_add_i32 m0, s20, 0xe000
	s_nop 0
	global_load_lds_dwordx4 v136, s[10:11]
	s_waitcnt vmcnt(8)
	s_waitcnt lgkmcnt(0)
	s_barrier
	s_setprio 1
	s_waitcnt lgkmcnt(0)
	v_mfma_f32_16x16x32_bf16 v[124:127], v[138:141], v[186:189], v[124:127]
	v_mfma_f32_16x16x32_bf16 v[120:123], v[146:149], v[186:189], v[120:123]
	v_mfma_f32_16x16x32_bf16 v[108:111], v[138:141], v[196:199], v[108:111]
	v_mfma_f32_16x16x32_bf16 v[104:107], v[146:149], v[196:199], v[104:107]
	v_mfma_f32_16x16x32_bf16 v[92:95], v[138:141], v[206:209], v[92:95]
	v_mfma_f32_16x16x32_bf16 v[88:91], v[146:149], v[206:209], v[88:91]
	v_mfma_f32_16x16x32_bf16 v[76:79], v[138:141], v[214:217], v[76:79]
	v_mfma_f32_16x16x32_bf16 v[72:75], v[146:149], v[214:217], v[72:75]
	v_mfma_f32_16x16x32_bf16 v[124:127], v[142:145], v[190:193], v[124:127]
	v_mfma_f32_16x16x32_bf16 v[120:123], v[154:157], v[190:193], v[120:123]
	v_mfma_f32_16x16x32_bf16 v[108:111], v[142:145], v[202:205], v[108:111]
	v_mfma_f32_16x16x32_bf16 v[104:107], v[154:157], v[202:205], v[104:107]
	v_mfma_f32_16x16x32_bf16 v[92:95], v[142:145], v[210:213], v[92:95]
	v_mfma_f32_16x16x32_bf16 v[88:91], v[154:157], v[210:213], v[88:91]
	v_mfma_f32_16x16x32_bf16 v[76:79], v[142:145], v[218:221], v[76:79]
	v_mfma_f32_16x16x32_bf16 v[72:75], v[154:157], v[218:221], v[72:75]
	s_setprio 0
	s_setprio 1
	v_mfma_f32_16x16x32_bf16 v[116:119], v[168:171], v[186:189], v[116:119]
	v_mfma_f32_16x16x32_bf16 v[112:115], v[178:181], v[186:189], v[112:115]
	v_mfma_f32_16x16x32_bf16 v[100:103], v[168:171], v[196:199], v[100:103]
	v_mfma_f32_16x16x32_bf16 v[96:99], v[178:181], v[196:199], v[96:99]
	v_mfma_f32_16x16x32_bf16 v[84:87], v[168:171], v[206:209], v[84:87]
	v_mfma_f32_16x16x32_bf16 v[80:83], v[178:181], v[206:209], v[80:83]
	v_mfma_f32_16x16x32_bf16 v[68:71], v[168:171], v[214:217], v[68:71]
	v_mfma_f32_16x16x32_bf16 v[64:67], v[178:181], v[214:217], v[64:67]
	v_mfma_f32_16x16x32_bf16 v[116:119], v[174:177], v[190:193], v[116:119]
	v_mfma_f32_16x16x32_bf16 v[112:115], v[182:185], v[190:193], v[112:115]
	v_mfma_f32_16x16x32_bf16 v[100:103], v[174:177], v[202:205], v[100:103]
	v_mfma_f32_16x16x32_bf16 v[96:99], v[182:185], v[202:205], v[96:99]
	v_mfma_f32_16x16x32_bf16 v[84:87], v[174:177], v[210:213], v[84:87]
	v_mfma_f32_16x16x32_bf16 v[80:83], v[182:185], v[210:213], v[80:83]
	v_mfma_f32_16x16x32_bf16 v[68:71], v[174:177], v[218:221], v[68:71]
	v_mfma_f32_16x16x32_bf16 v[64:67], v[182:185], v[218:221], v[64:67]
	s_setprio 0
	s_barrier
	s_add_i32 s40, s40, s19
	v_lshl_add_u64 v[158:159], s[12:13], 0, v[160:161]
	s_mov_b32 m0, s40
	ds_read_b128 v[186:189], v153 offset:16384
	ds_read_b128 v[190:193], v153 offset:17408
	ds_read_b128 v[196:199], v153 offset:18432
	ds_read_b128 v[202:205], v153 offset:19456
	ds_read_b128 v[206:209], v153 offset:20480
	ds_read_b128 v[210:213], v153 offset:21504
	ds_read_b128 v[214:217], v153 offset:22528
	ds_read_b128 v[218:221], v153 offset:23552
	global_load_lds_dwordx4 v160, s[12:13]
	s_add_i32 m0, s40, 0x2000
	s_add_u32 s40, s12, 0x80000
	v_lshl_add_u64 v[222:223], s[12:13], 0, v[132:133]
	s_addc_u32 s41, s13, 0
	s_add_i32 s42, s42, s19
	global_load_lds_dwordx4 v132, s[12:13]
	s_mov_b32 m0, s42
	v_lshl_add_u64 v[226:227], s[14:15], 0, v[130:131]
	global_load_lds_dwordx4 v160, s[40:41]
	s_add_i32 m0, s42, 0x2000
	s_nop 0
	global_load_lds_dwordx4 v132, s[40:41]
	v_lshl_add_u64 v[224:225], s[14:15], 0, v[128:129]
	s_mov_b32 m0, s20
	s_nop 0
	global_load_lds_dwordx4 v128, s[14:15]
	s_mov_b32 m0, s21
	s_nop 0
	global_load_lds_dwordx4 v130, s[14:15]
	s_waitcnt vmcnt(8)
	s_waitcnt lgkmcnt(0)
	s_barrier
; #define PG8_STAGE(bufoff, gbase, voff) do { _Pragma("unroll") for (int _i = 0; _i < 2; ++_i) \
;         __builtin_amdgcn_global_load_lds((const unsigned*)((const char*)(gbase) + (voff)[_i]), (LAS unsigned*)(lds + (bufoff) + ldsw + _i * 8192), 16, 0, 0); } while (0)
; #define PG8_LDA(dst, b, h) do { _Pragma("unroll") for (int m = 0; m < 4; ++m) _Pragma("unroll") for (int k = 0; k < 2; ++k) dst[m][k] = *(const LAS bf16x8*)(lds + PG8_SA(b, h) + aoff + m * 2048 + k * 1024); } while (0)
; #define PG8_LDB(dst, b, h) do { _Pragma("unroll") for (int n = 0; n < 2; ++n) _Pragma("unroll") for (int k = 0; k < 2; ++k) dst[n][k] = *(const LAS bf16x8*)(lds + PG8_SB(b, h) + boff + n * 2048 + k * 1024); } while (0)
; #define PG8_MMA(ai, bj, At, Bt) do { __builtin_amdgcn_s_setprio(1); _Pragma("unroll") for (int m = 0; m < 4; ++m) _Pragma("unroll") for (int n = 0; n < 2; ++n) _Pragma("unroll") for (int k = 0; k < 2; ++k) \
;         acc[ai][bj][m][n] = __builtin_amdgcn_mfma_f32_16x16x32_bf16(Bt[n][k], At[m][k], acc[ai][bj][m][n], 0, 0, 0); __builtin_amdgcn_s_setprio(0); } while (0)
; #define PG8_WAIT_V(n) asm volatile("s_waitcnt vmcnt(" #n ")" ::: "memory")
; #define PG8_WAIT_L(n) asm volatile("s_waitcnt lgkmcnt(" #n ")" ::: "memory")
; #define PG8_BAR __builtin_amdgcn_s_barrier()
; #define PG8_SCHED __builtin_amdgcn_sched_barrier(0)
; template <class Epi, int GM, int GN, int GK, int LDA, int AMOD, int ASTRIDE, int WG = WGM>
; __device__ __forceinline__ void gemm_phase(LAS unsigned char* lds, const Gemm g, const Epi& E, int wv_) {
;     ...
;             PG8_WAIT_V(8); PG8_WAIT_L(0); PG8_BAR; PG8_MMA(1, 0, At, B0); PG8_MMA(1, 1, At, B1); PG8_BAR; PG8_SCHED;
;             PG8_LDB(B0, 1, 0); PG8_LDB(B1, 1, 1); PG8_SCHED; PG8_LDA(At, 1, 0); PG8_STAGE(PG8_SA(0, 1), a2 + hstepA, voffA);
;             PG8_WAIT_V(8); PG8_WAIT_L(0); PG8_BAR; PG8_MMA(0, 0, At, B0); PG8_MMA(0, 1, At, B1); PG8_BAR; PG8_SCHED;
	s_setprio 1
	s_waitcnt lgkmcnt(0)
	v_mfma_f32_16x16x32_bf16 v[60:63], v[138:141], v[186:189], v[60:63]
	v_mfma_f32_16x16x32_bf16 v[56:59], v[146:149], v[186:189], v[56:59]
	v_mfma_f32_16x16x32_bf16 v[44:47], v[138:141], v[196:199], v[44:47]
	v_mfma_f32_16x16x32_bf16 v[40:43], v[146:149], v[196:199], v[40:43]
	v_mfma_f32_16x16x32_bf16 v[28:31], v[138:141], v[206:209], v[28:31]
	v_mfma_f32_16x16x32_bf16 v[24:27], v[146:149], v[206:209], v[24:27]
	v_mfma_f32_16x16x32_bf16 v[12:15], v[138:141], v[214:217], v[12:15]
	v_mfma_f32_16x16x32_bf16 v[8:11], v[146:149], v[214:217], v[8:11]
	v_mfma_f32_16x16x32_bf16 v[60:63], v[142:145], v[190:193], v[60:63]
	v_mfma_f32_16x16x32_bf16 v[56:59], v[154:157], v[190:193], v[56:59]
	v_mfma_f32_16x16x32_bf16 v[44:47], v[142:145], v[202:205], v[44:47]
	v_mfma_f32_16x16x32_bf16 v[40:43], v[154:157], v[202:205], v[40:43]
	v_mfma_f32_16x16x32_bf16 v[28:31], v[142:145], v[210:213], v[28:31]
	v_mfma_f32_16x16x32_bf16 v[24:27], v[154:157], v[210:213], v[24:27]
	v_mfma_f32_16x16x32_bf16 v[12:15], v[142:145], v[218:221], v[12:15]
	v_mfma_f32_16x16x32_bf16 v[8:11], v[154:157], v[218:221], v[8:11]
	s_setprio 0
	s_setprio 1
	v_mfma_f32_16x16x32_bf16 v[52:55], v[168:171], v[186:189], v[52:55]
	v_mfma_f32_16x16x32_bf16 v[48:51], v[178:181], v[186:189], v[48:51]
	v_mfma_f32_16x16x32_bf16 v[36:39], v[168:171], v[196:199], v[36:39]
	v_mfma_f32_16x16x32_bf16 v[32:35], v[178:181], v[196:199], v[32:35]
	v_mfma_f32_16x16x32_bf16 v[20:23], v[168:171], v[206:209], v[20:23]
	v_mfma_f32_16x16x32_bf16 v[16:19], v[178:181], v[206:209], v[16:19]
	v_mfma_f32_16x16x32_bf16 v[4:7], v[168:171], v[214:217], v[4:7]
	v_mfma_f32_16x16x32_bf16 v[0:3], v[178:181], v[214:217], v[0:3]
	v_mfma_f32_16x16x32_bf16 v[52:55], v[174:177], v[190:193], v[52:55]
	v_mfma_f32_16x16x32_bf16 v[48:51], v[182:185], v[190:193], v[48:51]
	v_mfma_f32_16x16x32_bf16 v[36:39], v[174:177], v[202:205], v[36:39]
	v_mfma_f32_16x16x32_bf16 v[32:35], v[182:185], v[202:205], v[32:35]
	v_mfma_f32_16x16x32_bf16 v[20:23], v[174:177], v[210:213], v[20:23]
	v_mfma_f32_16x16x32_bf16 v[16:19], v[182:185], v[210:213], v[16:19]
	v_mfma_f32_16x16x32_bf16 v[4:7], v[174:177], v[218:221], v[4:7]
	v_mfma_f32_16x16x32_bf16 v[0:3], v[182:185], v[218:221], v[0:3]
	s_setprio 0
	s_barrier
	s_add_i32 s40, 0, 0x18000
	s_add_i32 s41, 0, 0x1c000
	v_add_u32_e32 v154, s40, v152
	v_add_u32_e32 v172, s41, v152
	ds_read_b128 v[138:141], v154
	ds_read_b128 v[142:145], v154 offset:1024
	ds_read_b128 v[146:149], v154 offset:2048
	ds_read_b128 v[154:157], v154 offset:3072
	ds_read_b128 v[168:171], v172
	ds_read_b128 v[174:177], v172 offset:1024
	ds_read_b128 v[178:181], v172 offset:2048
	ds_read_b128 v[182:185], v172 offset:3072
	s_add_u32 s14, s14, 0x80000
	s_addc_u32 s15, s15, 0
	s_mov_b32 m0, s22
	ds_read_b128 v[186:189], v153 offset:32768
	ds_read_b128 v[190:193], v153 offset:33792
	ds_read_b128 v[196:199], v153 offset:34816
	ds_read_b128 v[202:205], v153 offset:35840
	ds_read_b128 v[206:209], v153 offset:36864
	ds_read_b128 v[210:213], v153 offset:37888
	ds_read_b128 v[214:217], v153 offset:38912
	ds_read_b128 v[218:221], v153 offset:39936
	global_load_lds_dwordx4 v128, s[14:15]
	v_lshl_add_u64 v[228:229], s[14:15], 0, v[130:131]
	s_mov_b32 m0, s23
	s_nop 0
	global_load_lds_dwordx4 v130, s[14:15]
	s_waitcnt vmcnt(8)
	s_waitcnt lgkmcnt(0)
	s_barrier
	s_setprio 1
	s_waitcnt lgkmcnt(0)
	v_mfma_f32_16x16x32_bf16 v[124:127], v[138:141], v[186:189], v[124:127]
	v_mfma_f32_16x16x32_bf16 v[120:123], v[146:149], v[186:189], v[120:123]
	v_mfma_f32_16x16x32_bf16 v[108:111], v[138:141], v[196:199], v[108:111]
	v_mfma_f32_16x16x32_bf16 v[104:107], v[146:149], v[196:199], v[104:107]
	v_mfma_f32_16x16x32_bf16 v[92:95], v[138:141], v[206:209], v[92:95]
	v_mfma_f32_16x16x32_bf16 v[88:91], v[146:149], v[206:209], v[88:91]
	v_mfma_f32_16x16x32_bf16 v[76:79], v[138:141], v[214:217], v[76:79]
	v_mfma_f32_16x16x32_bf16 v[72:75], v[146:149], v[214:217], v[72:75]
	v_mfma_f32_16x16x32_bf16 v[124:127], v[142:145], v[190:193], v[124:127]
	v_mfma_f32_16x16x32_bf16 v[120:123], v[154:157], v[190:193], v[120:123]
	v_mfma_f32_16x16x32_bf16 v[108:111], v[142:145], v[202:205], v[108:111]
	v_mfma_f32_16x16x32_bf16 v[104:107], v[154:157], v[202:205], v[104:107]
	v_mfma_f32_16x16x32_bf16 v[92:95], v[142:145], v[210:213], v[92:95]
	v_mfma_f32_16x16x32_bf16 v[88:91], v[154:157], v[210:213], v[88:91]
	v_mfma_f32_16x16x32_bf16 v[76:79], v[142:145], v[218:221], v[76:79]
	v_mfma_f32_16x16x32_bf16 v[72:75], v[154:157], v[218:221], v[72:75]
	s_setprio 0
	s_setprio 1
	v_mfma_f32_16x16x32_bf16 v[116:119], v[168:171], v[186:189], v[116:119]
	v_mfma_f32_16x16x32_bf16 v[112:115], v[178:181], v[186:189], v[112:115]
	v_mfma_f32_16x16x32_bf16 v[100:103], v[168:171], v[196:199], v[100:103]
	v_mfma_f32_16x16x32_bf16 v[96:99], v[178:181], v[196:199], v[96:99]
	v_mfma_f32_16x16x32_bf16 v[84:87], v[168:171], v[206:209], v[84:87]
	v_mfma_f32_16x16x32_bf16 v[80:83], v[178:181], v[206:209], v[80:83]
	v_mfma_f32_16x16x32_bf16 v[68:71], v[168:171], v[214:217], v[68:71]
	v_mfma_f32_16x16x32_bf16 v[64:67], v[178:181], v[214:217], v[64:67]
	v_mfma_f32_16x16x32_bf16 v[116:119], v[174:177], v[190:193], v[116:119]
	v_mfma_f32_16x16x32_bf16 v[112:115], v[182:185], v[190:193], v[112:115]
	v_mfma_f32_16x16x32_bf16 v[100:103], v[174:177], v[202:205], v[100:103]
	v_mfma_f32_16x16x32_bf16 v[96:99], v[182:185], v[202:205], v[96:99]
	v_mfma_f32_16x16x32_bf16 v[84:87], v[174:177], v[210:213], v[84:87]
	v_mfma_f32_16x16x32_bf16 v[80:83], v[182:185], v[210:213], v[80:83]
	v_mfma_f32_16x16x32_bf16 v[68:71], v[174:177], v[218:221], v[68:71]
	v_mfma_f32_16x16x32_bf16 v[64:67], v[182:185], v[218:221], v[64:67]
	s_setprio 0
	s_barrier
; #define PG8_STAGE(bufoff, gbase, voff) do { _Pragma("unroll") for (int _i = 0; _i < 2; ++_i) \
;         __builtin_amdgcn_global_load_lds((const unsigned*)((const char*)(gbase) + (voff)[_i]), (LAS unsigned*)(lds + (bufoff) + ldsw + _i * 8192), 16, 0, 0); } while (0)
; #define PG8_LDA(dst, b, h) do { _Pragma("unroll") for (int m = 0; m < 4; ++m) _Pragma("unroll") for (int k = 0; k < 2; ++k) dst[m][k] = *(const LAS bf16x8*)(lds + PG8_SA(b, h) + aoff + m * 2048 + k * 1024); } while (0)
; #define PG8_MMA(ai, bj, At, Bt) do { __builtin_amdgcn_s_setprio(1); _Pragma("unroll") for (int m = 0; m < 4; ++m) _Pragma("unroll") for (int n = 0; n < 2; ++n) _Pragma("unroll") for (int k = 0; k < 2; ++k) \
;         acc[ai][bj][m][n] = __builtin_amdgcn_mfma_f32_16x16x32_bf16(Bt[n][k], At[m][k], acc[ai][bj][m][n], 0, 0, 0); __builtin_amdgcn_s_setprio(0); } while (0)
; #define PG8_WAIT_V(n) asm volatile("s_waitcnt vmcnt(" #n ")" ::: "memory")
; #define PG8_WAIT_L(n) asm volatile("s_waitcnt lgkmcnt(" #n ")" ::: "memory")
; #define PG8_BAR __builtin_amdgcn_s_barrier()
; #define PG8_SCHED __builtin_amdgcn_sched_barrier(0)
; template <class Epi, int GM, int GN, int GK, int LDA, int AMOD, int ASTRIDE, int WG = WGM>
; __device__ __forceinline__ void gemm_phase(LAS unsigned char* lds, const Gemm g, const Epi& E, int wv_) {
;     ...
;             PG8_LDA(At, 1, 1); PG8_STAGE(PG8_SB(1, 0), b3, voffB); PG8_STAGE(PG8_SB(1, 1), b3 + hstepB, voffB); PG8_STAGE(PG8_SA(1, 0), a3, voffA);
;             PG8_WAIT_V(8); PG8_WAIT_L(0); PG8_BAR; PG8_MMA(1, 0, At, B0); PG8_MMA(1, 1, At, B1); PG8_BAR; PG8_SCHED;
;         }
	s_add_i32 s14, s40, s19
	v_lshl_add_u64 v[158:159], v[158:159], 0, s[70:71]
	s_mov_b32 m0, s14
	ds_read_b128 v[186:189], v153 offset:49152
	ds_read_b128 v[190:193], v153 offset:50176
	ds_read_b128 v[196:199], v153 offset:51200
	ds_read_b128 v[202:205], v153 offset:52224
	ds_read_b128 v[206:209], v153 offset:53248
	ds_read_b128 v[210:213], v153 offset:54272
	ds_read_b128 v[214:217], v153 offset:55296
	ds_read_b128 v[218:221], v153 offset:56320
	global_load_lds_dwordx4 v[158:159], off
	s_add_i32 m0, s14, 0x2000
	s_add_u32 s12, s12, 0x80080
	v_lshl_add_u64 v[158:159], v[222:223], 0, s[70:71]
	s_addc_u32 s13, s13, 0
	s_add_i32 s14, s41, s19
	global_load_lds_dwordx4 v[158:159], off
	s_mov_b32 m0, s14
	s_nop 0
	global_load_lds_dwordx4 v160, s[12:13]
	s_add_i32 m0, s14, 0x2000
	s_nop 0
	global_load_lds_dwordx4 v132, s[12:13]
	v_lshl_add_u64 v[158:159], v[224:225], 0, s[70:71]
	s_mov_b32 m0, s26
	s_nop 0
	global_load_lds_dwordx4 v[158:159], off
	v_lshl_add_u64 v[158:159], v[226:227], 0, s[70:71]
	s_mov_b32 m0, s27
	s_nop 0
	global_load_lds_dwordx4 v[158:159], off
	s_waitcnt vmcnt(8)
	s_waitcnt lgkmcnt(0)
	s_barrier
	s_setprio 1
	s_waitcnt lgkmcnt(0)
	v_mfma_f32_16x16x32_bf16 v[60:63], v[138:141], v[186:189], v[60:63]
	v_mfma_f32_16x16x32_bf16 v[56:59], v[146:149], v[186:189], v[56:59]
	v_mfma_f32_16x16x32_bf16 v[44:47], v[138:141], v[196:199], v[44:47]
	v_mfma_f32_16x16x32_bf16 v[40:43], v[146:149], v[196:199], v[40:43]
	v_mfma_f32_16x16x32_bf16 v[28:31], v[138:141], v[206:209], v[28:31]
	v_mfma_f32_16x16x32_bf16 v[24:27], v[146:149], v[206:209], v[24:27]
	v_mfma_f32_16x16x32_bf16 v[12:15], v[138:141], v[214:217], v[12:15]
	v_mfma_f32_16x16x32_bf16 v[8:11], v[146:149], v[214:217], v[8:11]
	v_mfma_f32_16x16x32_bf16 v[60:63], v[142:145], v[190:193], v[60:63]
	v_mfma_f32_16x16x32_bf16 v[56:59], v[154:157], v[190:193], v[56:59]
	v_mfma_f32_16x16x32_bf16 v[44:47], v[142:145], v[202:205], v[44:47]
	v_mfma_f32_16x16x32_bf16 v[40:43], v[154:157], v[202:205], v[40:43]
	v_mfma_f32_16x16x32_bf16 v[28:31], v[142:145], v[210:213], v[28:31]
	v_mfma_f32_16x16x32_bf16 v[24:27], v[154:157], v[210:213], v[24:27]
	v_mfma_f32_16x16x32_bf16 v[12:15], v[142:145], v[218:221], v[12:15]
	v_mfma_f32_16x16x32_bf16 v[8:11], v[154:157], v[218:221], v[8:11]
	s_setprio 0
	s_setprio 1
	v_mfma_f32_16x16x32_bf16 v[52:55], v[168:171], v[186:189], v[52:55]
	v_mfma_f32_16x16x32_bf16 v[48:51], v[178:181], v[186:189], v[48:51]
	v_mfma_f32_16x16x32_bf16 v[36:39], v[168:171], v[196:199], v[36:39]
	v_mfma_f32_16x16x32_bf16 v[32:35], v[178:181], v[196:199], v[32:35]
	v_mfma_f32_16x16x32_bf16 v[20:23], v[168:171], v[206:209], v[20:23]
	v_mfma_f32_16x16x32_bf16 v[16:19], v[178:181], v[206:209], v[16:19]
	v_mfma_f32_16x16x32_bf16 v[4:7], v[168:171], v[214:217], v[4:7]
	v_mfma_f32_16x16x32_bf16 v[0:3], v[178:181], v[214:217], v[0:3]
	v_mfma_f32_16x16x32_bf16 v[52:55], v[174:177], v[190:193], v[52:55]
	v_mfma_f32_16x16x32_bf16 v[48:51], v[182:185], v[190:193], v[48:51]
	v_mfma_f32_16x16x32_bf16 v[36:39], v[174:177], v[202:205], v[36:39]
	v_mfma_f32_16x16x32_bf16 v[32:35], v[182:185], v[202:205], v[32:35]
	v_mfma_f32_16x16x32_bf16 v[20:23], v[174:177], v[210:213], v[20:23]
	v_mfma_f32_16x16x32_bf16 v[16:19], v[182:185], v[210:213], v[16:19]
	v_mfma_f32_16x16x32_bf16 v[4:7], v[174:177], v[218:221], v[4:7]
	v_mfma_f32_16x16x32_bf16 v[0:3], v[182:185], v[218:221], v[0:3]
	s_setprio 0
	s_barrier
	s_add_u32 s10, s10, 0x100
	s_addc_u32 s11, s11, 0
	s_add_u32 s35, s35, 0x100
	s_addc_u32 s36, s36, 0
	s_cmp_ge_i32 s37, s17
	s_mov_b32 s12, s37
	s_cbranch_scc0 .LBB0_136
	s_and_b64 vcc, exec, s[2:3]
	s_cbranch_vccz .LBB0_139

; #define PG8_STAGE(bufoff, gbase, voff) do { _Pragma("unroll") for (int _i = 0; _i < 2; ++_i) \
;         __builtin_amdgcn_global_load_lds((const unsigned*)((const char*)(gbase) + (voff)[_i]), (LAS unsigned*)(lds + (bufoff) + ldsw + _i * 8192), 16, 0, 0); } while (0)
; #define PG8_WAIT_V(n) asm volatile("s_waitcnt vmcnt(" #n ")" ::: "memory")
; #define PG8_BAR __builtin_amdgcn_s_barrier()
; template <class Epi, int GM, int GN, int GK, int LDA, int AMOD, int ASTRIDE, int WG = WGM>
; __device__ __forceinline__ void gemm_phase(LAS unsigned char* lds, const Gemm g, const Epi& E, int wv_) {
;     ...
;     const char* cA = (const char*)g.A + (size_t)cur.pm * tstepA + PG8_AOFF(cur.pn); const char* cB = (const char*)g.Bt + (size_t)cur.pn * tstepB;
;     PG8_STAGE(PG8_SB(0, 0), cB, voffB); PG8_STAGE(PG8_SB(0, 1), cB + hstepB, voffB); PG8_STAGE(PG8_SA(0, 0), cA, voffA); PG8_STAGE(PG8_SA(0, 1), cA + hstepA, voffA);
;     if (wr == 1) PG8_BAR;
;     PG8_WAIT_V(2); PG8_BAR;
;     PG8_STAGE(PG8_SB(1, 0), cB + kstep, voffB); PG8_STAGE(PG8_SA(1, 0), cA + kstep, voffA); PG8_STAGE(PG8_SB(1, 1), cB + hstepB + kstep, voffB);
;     PG8_WAIT_V(6); PG8_BAR;
.LBB0_176:
	s_lshl_b32 s22, s4, 6
	s_lshl_b32 s12, s4, 13
	s_lshl_b32 s4, s5, 5
	s_and_b32 s23, s4, 0x60
	s_add_i32 m0, s18, 0x18000
	v_lshl_add_u64 v[6:7], v[6:7], 0, s[70:71]
	s_lshl_b32 s13, s23, 7
	s_waitcnt vmcnt(2)
	s_barrier
	global_load_lds_dwordx4 v[6:7], off
	v_lshl_add_u64 v[4:5], v[4:5], 0, s[70:71]
	s_add_i32 m0, s18, 0x1a000
	s_add_i32 s24, s18, 0x8000
	s_add_i32 s25, s18, 0xa000
	global_load_lds_dwordx4 v[4:5], off
	v_lshl_add_u64 v[0:1], v[0:1], 0, s[70:71]
	s_mov_b32 m0, s24
	s_add_u32 s4, s10, 0x80080
	global_load_lds_dwordx4 v[0:1], off
	v_lshl_add_u64 v[0:1], v[2:3], 0, s[70:71]
	s_mov_b32 m0, s25
	s_addc_u32 s5, s11, 0
	global_load_lds_dwordx4 v[0:1], off
	s_add_i32 m0, s18, 0x1c000
	s_nop 0
	global_load_lds_dwordx4 v160, s[4:5]
	v_lshl_add_u64 v[0:1], s[4:5], 0, v[132:133]
	s_add_i32 m0, s18, 0x1e000
	v_bfe_u32 v149, v8, 4, 2
	global_load_lds_dwordx4 v132, s[4:5]
	v_and_b32_e32 v148, 15, v8
	v_lshlrev_b32_e32 v0, 4, v149
	v_lshlrev_b32_e32 v1, 2, v8
	v_lshl_or_b32 v0, v148, 6, v0
	v_and_b32_e32 v1, 32, v1
	v_bitop3_b32 v2, v0, s12, v1 bitop3:0xde
	v_bitop3_b32 v150, s13, v0, v1 bitop3:0xf6
	v_lshlrev_b32_e32 v0, 15, v9
	v_and_b32_e32 v0, 0xffff0000, v0
	v_lshl_add_u32 v0, v10, 12, v0
	v_and_b32_e32 v1, 1, v9
	v_lshl_or_b32 v0, v1, 6, v0
	v_lshl_add_u32 v134, v11, 1, v0
	v_lshlrev_b32_e32 v0, 15, v12
	s_cmp_gt_i32 s15, 0
	v_and_b32_e32 v0, 0xffff0000, v0
	s_waitcnt vmcnt(6)
	s_cselect_b64 s[44:45], -1, 0
	s_add_i32 s27, s15, -2
	v_lshl_add_u32 v0, v13, 12, v0
	v_and_b32_e32 v1, 1, v12
	s_cmpk_lt_u32 s3, 0x100
	v_lshl_or_b32 v0, v1, 6, v0
	s_sext_i32_i8 s7, s2
	s_mov_b32 s26, 0
	s_cselect_b64 s[46:47], -1, 0
	v_mov_b32_e32 v135, v161
	v_lshl_add_u32 v136, v14, 1, v0
	v_mov_b32_e32 v137, v161
	v_add_u32_e32 v151, 0, v2
	s_barrier
	s_branch .LBB0_179

; #define PG8_STAGE(bufoff, gbase, voff) do { _Pragma("unroll") for (int _i = 0; _i < 2; ++_i) \
;         __builtin_amdgcn_global_load_lds((const unsigned*)((const char*)(gbase) + (voff)[_i]), (LAS unsigned*)(lds + (bufoff) + ldsw + _i * 8192), 16, 0, 0); } while (0)
; #define PG8_LDA(dst, b, h) do { _Pragma("unroll") for (int m = 0; m < 4; ++m) _Pragma("unroll") for (int k = 0; k < 2; ++k) dst[m][k] = *(const LAS bf16x8*)(lds + PG8_SA(b, h) + aoff + m * 2048 + k * 1024); } while (0)
; #define PG8_LDB(dst, b, h) do { _Pragma("unroll") for (int n = 0; n < 2; ++n) _Pragma("unroll") for (int k = 0; k < 2; ++k) dst[n][k] = *(const LAS bf16x8*)(lds + PG8_SB(b, h) + boff + n * 2048 + k * 1024); } while (0)
; #define PG8_MMA(ai, bj, At, Bt) do { __builtin_amdgcn_s_setprio(1); _Pragma("unroll") for (int m = 0; m < 4; ++m) _Pragma("unroll") for (int n = 0; n < 2; ++n) _Pragma("unroll") for (int k = 0; k < 2; ++k) \
;         acc[ai][bj][m][n] = __builtin_amdgcn_mfma_f32_16x16x32_bf16(Bt[n][k], At[m][k], acc[ai][bj][m][n], 0, 0, 0); __builtin_amdgcn_s_setprio(0); } while (0)
; #define PG8_WAIT_V(n) asm volatile("s_waitcnt vmcnt(" #n ")" ::: "memory")
; #define PG8_WAIT_L(n) asm volatile("s_waitcnt lgkmcnt(" #n ")" ::: "memory")
; #define PG8_BAR __builtin_amdgcn_s_barrier()
; #define PG8_SCHED __builtin_amdgcn_sched_barrier(0)
; template <class Epi, int GM, int GN, int GK, int LDA, int AMOD, int ASTRIDE, int WG = WGM>
; __device__ __forceinline__ void gemm_phase(LAS unsigned char* lds, const Gemm g, const Epi& E, int wv_) {
;     ...
;             const char* a1 = cA + (size_t)(t + 1) * kstep;
;             const char* a2 = last ? nA : cA + (size_t)(t + 2) * kstep; const char* b2 = last ? nB : cB + (size_t)(t + 2) * kstep;
;             const char* a3 = a2 + kstep; const char* b3 = b2 + kstep;
;             PG8_LDB(B0, 0, 0); PG8_LDB(B1, 0, 1); PG8_SCHED; PG8_LDA(At, 0, 0); PG8_STAGE(PG8_SA(1, 1), a1 + hstepA, voffA);
;             PG8_WAIT_V(8); PG8_WAIT_L(0); PG8_BAR; PG8_MMA(0, 0, At, B0); PG8_MMA(0, 1, At, B1); PG8_BAR; PG8_SCHED;
;             PG8_LDA(At, 0, 1); PG8_STAGE(PG8_SB(0, 0), b2, voffB); PG8_STAGE(PG8_SB(0, 1), b2 + hstepB, voffB); PG8_STAGE(PG8_SA(0, 0), a2, voffA);
;             PG8_WAIT_V(8); PG8_WAIT_L(0); PG8_BAR; PG8_MMA(1, 0, At, B0); PG8_MMA(1, 1, At, B1); PG8_BAR; PG8_SCHED;
.LBB0_187:
	s_add_i32 s34, s10, 2
	s_add_u32 s11, s8, 0xfff80080
	s_addc_u32 s12, s9, -1
	s_add_i32 s35, 0, 0x10000
	s_cmp_eq_u32 s27, s10
	s_cselect_b32 s13, s3, s12
	s_cselect_b32 s12, s5, s11
	v_add_u32_e32 v146, s35, v150
	s_cselect_b32 s11, s28, s31
	s_cselect_b32 s10, s29, s30
	s_add_i32 s40, 0, 0x14000
	ds_read_b128 v[138:141], v146
	ds_read_b128 v[142:145], v146 offset:1024
	ds_read_b128 v[152:155], v146 offset:2048
	ds_read_b128 v[156:159], v146 offset:3072
	v_add_u32_e32 v146, s40, v150
	ds_read_b128 v[168:171], v146
	ds_read_b128 v[174:177], v146 offset:1024
	ds_read_b128 v[178:181], v146 offset:2048
	ds_read_b128 v[182:185], v146 offset:3072
	s_add_i32 m0, s18, 0xc000
	ds_read_b128 v[186:189], v151
	ds_read_b128 v[190:193], v151 offset:1024
	ds_read_b128 v[196:199], v151 offset:2048
	ds_read_b128 v[202:205], v151 offset:3072
	ds_read_b128 v[206:209], v151 offset:4096
	ds_read_b128 v[210:213], v151 offset:5120
	ds_read_b128 v[214:217], v151 offset:6144
	ds_read_b128 v[218:221], v151 offset:7168
	global_load_lds_dwordx4 v134, s[8:9]
	s_add_i32 m0, s18, 0xe000
	s_nop 0
	global_load_lds_dwordx4 v136, s[8:9]
	s_waitcnt vmcnt(8)
	s_waitcnt lgkmcnt(0)
	s_barrier
	s_setprio 1
	s_waitcnt lgkmcnt(0)
	v_mfma_f32_16x16x32_bf16 v[124:127], v[138:141], v[186:189], v[124:127]
	v_mfma_f32_16x16x32_bf16 v[120:123], v[152:155], v[186:189], v[120:123]
	v_mfma_f32_16x16x32_bf16 v[108:111], v[138:141], v[196:199], v[108:111]
	v_mfma_f32_16x16x32_bf16 v[104:107], v[152:155], v[196:199], v[104:107]
	v_mfma_f32_16x16x32_bf16 v[92:95], v[138:141], v[206:209], v[92:95]
	v_mfma_f32_16x16x32_bf16 v[88:91], v[152:155], v[206:209], v[88:91]
	v_mfma_f32_16x16x32_bf16 v[76:79], v[138:141], v[214:217], v[76:79]
	v_mfma_f32_16x16x32_bf16 v[72:75], v[152:155], v[214:217], v[72:75]
	v_mfma_f32_16x16x32_bf16 v[124:127], v[142:145], v[190:193], v[124:127]
	v_mfma_f32_16x16x32_bf16 v[120:123], v[156:159], v[190:193], v[120:123]
	v_mfma_f32_16x16x32_bf16 v[108:111], v[142:145], v[202:205], v[108:111]
	v_mfma_f32_16x16x32_bf16 v[104:107], v[156:159], v[202:205], v[104:107]
	v_mfma_f32_16x16x32_bf16 v[92:95], v[142:145], v[210:213], v[92:95]
	v_mfma_f32_16x16x32_bf16 v[88:91], v[156:159], v[210:213], v[88:91]
	v_mfma_f32_16x16x32_bf16 v[76:79], v[142:145], v[218:221], v[76:79]
	v_mfma_f32_16x16x32_bf16 v[72:75], v[156:159], v[218:221], v[72:75]
	s_setprio 0
	s_setprio 1
	v_mfma_f32_16x16x32_bf16 v[116:119], v[168:171], v[186:189], v[116:119]
	v_mfma_f32_16x16x32_bf16 v[112:115], v[178:181], v[186:189], v[112:115]
	v_mfma_f32_16x16x32_bf16 v[100:103], v[168:171], v[196:199], v[100:103]
	v_mfma_f32_16x16x32_bf16 v[96:99], v[178:181], v[196:199], v[96:99]
	v_mfma_f32_16x16x32_bf16 v[84:87], v[168:171], v[206:209], v[84:87]
	v_mfma_f32_16x16x32_bf16 v[80:83], v[178:181], v[206:209], v[80:83]
	v_mfma_f32_16x16x32_bf16 v[68:71], v[168:171], v[214:217], v[68:71]
	v_mfma_f32_16x16x32_bf16 v[64:67], v[178:181], v[214:217], v[64:67]
	v_mfma_f32_16x16x32_bf16 v[116:119], v[174:177], v[190:193], v[116:119]
	v_mfma_f32_16x16x32_bf16 v[112:115], v[182:185], v[190:193], v[112:115]
	v_mfma_f32_16x16x32_bf16 v[100:103], v[174:177], v[202:205], v[100:103]
	v_mfma_f32_16x16x32_bf16 v[96:99], v[182:185], v[202:205], v[96:99]
	v_mfma_f32_16x16x32_bf16 v[84:87], v[174:177], v[210:213], v[84:87]
	v_mfma_f32_16x16x32_bf16 v[80:83], v[182:185], v[210:213], v[80:83]
	v_mfma_f32_16x16x32_bf16 v[68:71], v[174:177], v[218:221], v[68:71]
	v_mfma_f32_16x16x32_bf16 v[64:67], v[182:185], v[218:221], v[64:67]
	s_setprio 0
	s_barrier
	s_add_i32 s35, s35, s17
	v_lshl_add_u64 v[146:147], s[10:11], 0, v[160:161]
	s_mov_b32 m0, s35
	ds_read_b128 v[186:189], v151 offset:16384
	ds_read_b128 v[190:193], v151 offset:17408
	ds_read_b128 v[196:199], v151 offset:18432
	ds_read_b128 v[202:205], v151 offset:19456
	ds_read_b128 v[206:209], v151 offset:20480
	ds_read_b128 v[210:213], v151 offset:21504
	ds_read_b128 v[214:217], v151 offset:22528
	ds_read_b128 v[218:221], v151 offset:23552
	global_load_lds_dwordx4 v160, s[10:11]
	s_add_i32 m0, s35, 0x2000
	s_add_u32 s36, s10, 0x80000
	v_lshl_add_u64 v[222:223], s[10:11], 0, v[132:133]
	s_addc_u32 s37, s11, 0
	s_add_i32 s35, s40, s17
	global_load_lds_dwordx4 v132, s[10:11]
	s_mov_b32 m0, s35
	v_lshl_add_u64 v[226:227], s[12:13], 0, v[130:131]
	global_load_lds_dwordx4 v160, s[36:37]
	s_add_i32 m0, s35, 0x2000
	s_nop 0
	global_load_lds_dwordx4 v132, s[36:37]
	v_lshl_add_u64 v[224:225], s[12:13], 0, v[128:129]
	s_mov_b32 m0, s18
	s_nop 0
	global_load_lds_dwordx4 v128, s[12:13]
	s_mov_b32 m0, s19
	s_nop 0
	global_load_lds_dwordx4 v130, s[12:13]
	s_waitcnt vmcnt(8)
	s_waitcnt lgkmcnt(0)
	s_barrier
; #define PG8_STAGE(bufoff, gbase, voff) do { _Pragma("unroll") for (int _i = 0; _i < 2; ++_i) \
;         __builtin_amdgcn_global_load_lds((const unsigned*)((const char*)(gbase) + (voff)[_i]), (LAS unsigned*)(lds + (bufoff) + ldsw + _i * 8192), 16, 0, 0); } while (0)
; #define PG8_LDA(dst, b, h) do { _Pragma("unroll") for (int m = 0; m < 4; ++m) _Pragma("unroll") for (int k = 0; k < 2; ++k) dst[m][k] = *(const LAS bf16x8*)(lds + PG8_SA(b, h) + aoff + m * 2048 + k * 1024); } while (0)
; #define PG8_LDB(dst, b, h) do { _Pragma("unroll") for (int n = 0; n < 2; ++n) _Pragma("unroll") for (int k = 0; k < 2; ++k) dst[n][k] = *(const LAS bf16x8*)(lds + PG8_SB(b, h) + boff + n * 2048 + k * 1024); } while (0)
; #define PG8_MMA(ai, bj, At, Bt) do { __builtin_amdgcn_s_setprio(1); _Pragma("unroll") for (int m = 0; m < 4; ++m) _Pragma("unroll") for (int n = 0; n < 2; ++n) _Pragma("unroll") for (int k = 0; k < 2; ++k) \
;         acc[ai][bj][m][n] = __builtin_amdgcn_mfma_f32_16x16x32_bf16(Bt[n][k], At[m][k], acc[ai][bj][m][n], 0, 0, 0); __builtin_amdgcn_s_setprio(0); } while (0)
; #define PG8_WAIT_V(n) asm volatile("s_waitcnt vmcnt(" #n ")" ::: "memory")
; #define PG8_WAIT_L(n) asm volatile("s_waitcnt lgkmcnt(" #n ")" ::: "memory")
; #define PG8_BAR __builtin_amdgcn_s_barrier()
; #define PG8_SCHED __builtin_amdgcn_sched_barrier(0)
; template <class Epi, int GM, int GN, int GK, int LDA, int AMOD, int ASTRIDE, int WG = WGM>
; __device__ __forceinline__ void gemm_phase(LAS unsigned char* lds, const Gemm g, const Epi& E, int wv_) {
;     ...
;             PG8_WAIT_V(8); PG8_WAIT_L(0); PG8_BAR; PG8_MMA(1, 0, At, B0); PG8_MMA(1, 1, At, B1); PG8_BAR; PG8_SCHED;
;             PG8_LDB(B0, 1, 0); PG8_LDB(B1, 1, 1); PG8_SCHED; PG8_LDA(At, 1, 0); PG8_STAGE(PG8_SA(0, 1), a2 + hstepA, voffA);
;             PG8_WAIT_V(8); PG8_WAIT_L(0); PG8_BAR; PG8_MMA(0, 0, At, B0); PG8_MMA(0, 1, At, B1); PG8_BAR; PG8_SCHED;
	s_setprio 1
	s_waitcnt lgkmcnt(0)
	v_mfma_f32_16x16x32_bf16 v[60:63], v[138:141], v[186:189], v[60:63]
	v_mfma_f32_16x16x32_bf16 v[56:59], v[152:155], v[186:189], v[56:59]
	v_mfma_f32_16x16x32_bf16 v[44:47], v[138:141], v[196:199], v[44:47]
	v_mfma_f32_16x16x32_bf16 v[40:43], v[152:155], v[196:199], v[40:43]
	v_mfma_f32_16x16x32_bf16 v[28:31], v[138:141], v[206:209], v[28:31]
	v_mfma_f32_16x16x32_bf16 v[24:27], v[152:155], v[206:209], v[24:27]
	v_mfma_f32_16x16x32_bf16 v[12:15], v[138:141], v[214:217], v[12:15]
	v_mfma_f32_16x16x32_bf16 v[8:11], v[152:155], v[214:217], v[8:11]
	v_mfma_f32_16x16x32_bf16 v[60:63], v[142:145], v[190:193], v[60:63]
	v_mfma_f32_16x16x32_bf16 v[56:59], v[156:159], v[190:193], v[56:59]
	v_mfma_f32_16x16x32_bf16 v[44:47], v[142:145], v[202:205], v[44:47]
	v_mfma_f32_16x16x32_bf16 v[40:43], v[156:159], v[202:205], v[40:43]
	v_mfma_f32_16x16x32_bf16 v[28:31], v[142:145], v[210:213], v[28:31]
	v_mfma_f32_16x16x32_bf16 v[24:27], v[156:159], v[210:213], v[24:27]
	v_mfma_f32_16x16x32_bf16 v[12:15], v[142:145], v[218:221], v[12:15]
	v_mfma_f32_16x16x32_bf16 v[8:11], v[156:159], v[218:221], v[8:11]
	s_setprio 0
	s_setprio 1
	v_mfma_f32_16x16x32_bf16 v[52:55], v[168:171], v[186:189], v[52:55]
	v_mfma_f32_16x16x32_bf16 v[48:51], v[178:181], v[186:189], v[48:51]
	v_mfma_f32_16x16x32_bf16 v[36:39], v[168:171], v[196:199], v[36:39]
	v_mfma_f32_16x16x32_bf16 v[32:35], v[178:181], v[196:199], v[32:35]
	v_mfma_f32_16x16x32_bf16 v[20:23], v[168:171], v[206:209], v[20:23]
	v_mfma_f32_16x16x32_bf16 v[16:19], v[178:181], v[206:209], v[16:19]
	v_mfma_f32_16x16x32_bf16 v[4:7], v[168:171], v[214:217], v[4:7]
	v_mfma_f32_16x16x32_bf16 v[0:3], v[178:181], v[214:217], v[0:3]
	v_mfma_f32_16x16x32_bf16 v[52:55], v[174:177], v[190:193], v[52:55]
	v_mfma_f32_16x16x32_bf16 v[48:51], v[182:185], v[190:193], v[48:51]
	v_mfma_f32_16x16x32_bf16 v[36:39], v[174:177], v[202:205], v[36:39]
	v_mfma_f32_16x16x32_bf16 v[32:35], v[182:185], v[202:205], v[32:35]
	v_mfma_f32_16x16x32_bf16 v[20:23], v[174:177], v[210:213], v[20:23]
	v_mfma_f32_16x16x32_bf16 v[16:19], v[182:185], v[210:213], v[16:19]
	v_mfma_f32_16x16x32_bf16 v[4:7], v[174:177], v[218:221], v[4:7]
	v_mfma_f32_16x16x32_bf16 v[0:3], v[182:185], v[218:221], v[0:3]
	s_setprio 0
	s_barrier
	s_add_i32 s35, 0, 0x18000
	s_add_i32 s36, 0, 0x1c000
	v_add_u32_e32 v156, s35, v150
	v_add_u32_e32 v172, s36, v150
	ds_read_b128 v[138:141], v156
	ds_read_b128 v[142:145], v156 offset:1024
	ds_read_b128 v[152:155], v156 offset:2048
	ds_read_b128 v[156:159], v156 offset:3072
	ds_read_b128 v[168:171], v172
	ds_read_b128 v[174:177], v172 offset:1024
	ds_read_b128 v[178:181], v172 offset:2048
	ds_read_b128 v[182:185], v172 offset:3072
	s_add_u32 s12, s12, 0x80000
	s_addc_u32 s13, s13, 0
	s_mov_b32 m0, s20
	ds_read_b128 v[186:189], v151 offset:32768
	ds_read_b128 v[190:193], v151 offset:33792
	ds_read_b128 v[196:199], v151 offset:34816
	ds_read_b128 v[202:205], v151 offset:35840
	ds_read_b128 v[206:209], v151 offset:36864
	ds_read_b128 v[210:213], v151 offset:37888
	ds_read_b128 v[214:217], v151 offset:38912
	ds_read_b128 v[218:221], v151 offset:39936
	global_load_lds_dwordx4 v128, s[12:13]
	v_lshl_add_u64 v[228:229], s[12:13], 0, v[130:131]
	s_mov_b32 m0, s21
	s_nop 0
	global_load_lds_dwordx4 v130, s[12:13]
	s_waitcnt vmcnt(8)
	s_waitcnt lgkmcnt(0)
	s_barrier
	s_setprio 1
	s_waitcnt lgkmcnt(0)
	v_mfma_f32_16x16x32_bf16 v[124:127], v[138:141], v[186:189], v[124:127]
	v_mfma_f32_16x16x32_bf16 v[120:123], v[152:155], v[186:189], v[120:123]
	v_mfma_f32_16x16x32_bf16 v[108:111], v[138:141], v[196:199], v[108:111]
	v_mfma_f32_16x16x32_bf16 v[104:107], v[152:155], v[196:199], v[104:107]
	v_mfma_f32_16x16x32_bf16 v[92:95], v[138:141], v[206:209], v[92:95]
	v_mfma_f32_16x16x32_bf16 v[88:91], v[152:155], v[206:209], v[88:91]
	v_mfma_f32_16x16x32_bf16 v[76:79], v[138:141], v[214:217], v[76:79]
	v_mfma_f32_16x16x32_bf16 v[72:75], v[152:155], v[214:217], v[72:75]
	v_mfma_f32_16x16x32_bf16 v[124:127], v[142:145], v[190:193], v[124:127]
	v_mfma_f32_16x16x32_bf16 v[120:123], v[156:159], v[190:193], v[120:123]
	v_mfma_f32_16x16x32_bf16 v[108:111], v[142:145], v[202:205], v[108:111]
	v_mfma_f32_16x16x32_bf16 v[104:107], v[156:159], v[202:205], v[104:107]
	v_mfma_f32_16x16x32_bf16 v[92:95], v[142:145], v[210:213], v[92:95]
	v_mfma_f32_16x16x32_bf16 v[88:91], v[156:159], v[210:213], v[88:91]
	v_mfma_f32_16x16x32_bf16 v[76:79], v[142:145], v[218:221], v[76:79]
	v_mfma_f32_16x16x32_bf16 v[72:75], v[156:159], v[218:221], v[72:75]
	s_setprio 0
	s_setprio 1
	v_mfma_f32_16x16x32_bf16 v[116:119], v[168:171], v[186:189], v[116:119]
	v_mfma_f32_16x16x32_bf16 v[112:115], v[178:181], v[186:189], v[112:115]
	v_mfma_f32_16x16x32_bf16 v[100:103], v[168:171], v[196:199], v[100:103]
	v_mfma_f32_16x16x32_bf16 v[96:99], v[178:181], v[196:199], v[96:99]
	v_mfma_f32_16x16x32_bf16 v[84:87], v[168:171], v[206:209], v[84:87]
	v_mfma_f32_16x16x32_bf16 v[80:83], v[178:181], v[206:209], v[80:83]
	v_mfma_f32_16x16x32_bf16 v[68:71], v[168:171], v[214:217], v[68:71]
	v_mfma_f32_16x16x32_bf16 v[64:67], v[178:181], v[214:217], v[64:67]
	v_mfma_f32_16x16x32_bf16 v[116:119], v[174:177], v[190:193], v[116:119]
	v_mfma_f32_16x16x32_bf16 v[112:115], v[182:185], v[190:193], v[112:115]
	v_mfma_f32_16x16x32_bf16 v[100:103], v[174:177], v[202:205], v[100:103]
	v_mfma_f32_16x16x32_bf16 v[96:99], v[182:185], v[202:205], v[96:99]
	v_mfma_f32_16x16x32_bf16 v[84:87], v[174:177], v[210:213], v[84:87]
	v_mfma_f32_16x16x32_bf16 v[80:83], v[182:185], v[210:213], v[80:83]
	v_mfma_f32_16x16x32_bf16 v[68:71], v[174:177], v[218:221], v[68:71]
	v_mfma_f32_16x16x32_bf16 v[64:67], v[182:185], v[218:221], v[64:67]
	s_setprio 0
	s_barrier
; #define PG8_STAGE(bufoff, gbase, voff) do { _Pragma("unroll") for (int _i = 0; _i < 2; ++_i) \
;         __builtin_amdgcn_global_load_lds((const unsigned*)((const char*)(gbase) + (voff)[_i]), (LAS unsigned*)(lds + (bufoff) + ldsw + _i * 8192), 16, 0, 0); } while (0)
; #define PG8_LDA(dst, b, h) do { _Pragma("unroll") for (int m = 0; m < 4; ++m) _Pragma("unroll") for (int k = 0; k < 2; ++k) dst[m][k] = *(const LAS bf16x8*)(lds + PG8_SA(b, h) + aoff + m * 2048 + k * 1024); } while (0)
; #define PG8_MMA(ai, bj, At, Bt) do { __builtin_amdgcn_s_setprio(1); _Pragma("unroll") for (int m = 0; m < 4; ++m) _Pragma("unroll") for (int n = 0; n < 2; ++n) _Pragma("unroll") for (int k = 0; k < 2; ++k) \
;         acc[ai][bj][m][n] = __builtin_amdgcn_mfma_f32_16x16x32_bf16(Bt[n][k], At[m][k], acc[ai][bj][m][n], 0, 0, 0); __builtin_amdgcn_s_setprio(0); } while (0)
; #define PG8_WAIT_V(n) asm volatile("s_waitcnt vmcnt(" #n ")" ::: "memory")
; #define PG8_WAIT_L(n) asm volatile("s_waitcnt lgkmcnt(" #n ")" ::: "memory")
; #define PG8_BAR __builtin_amdgcn_s_barrier()
; #define PG8_SCHED __builtin_amdgcn_sched_barrier(0)
; template <class Epi, int GM, int GN, int GK, int LDA, int AMOD, int ASTRIDE, int WG = WGM>
; __device__ __forceinline__ void gemm_phase(LAS unsigned char* lds, const Gemm g, const Epi& E, int wv_) {
;     ...
;             PG8_LDA(At, 1, 1); PG8_STAGE(PG8_SB(1, 0), b3, voffB); PG8_STAGE(PG8_SB(1, 1), b3 + hstepB, voffB); PG8_STAGE(PG8_SA(1, 0), a3, voffA);
;             PG8_WAIT_V(8); PG8_WAIT_L(0); PG8_BAR; PG8_MMA(1, 0, At, B0); PG8_MMA(1, 1, At, B1); PG8_BAR; PG8_SCHED;
;         }
	s_add_i32 s12, s35, s17
	v_lshl_add_u64 v[146:147], v[146:147], 0, s[70:71]
	s_mov_b32 m0, s12
	ds_read_b128 v[186:189], v151 offset:49152
	ds_read_b128 v[190:193], v151 offset:50176
	ds_read_b128 v[196:199], v151 offset:51200
	ds_read_b128 v[202:205], v151 offset:52224
	ds_read_b128 v[206:209], v151 offset:53248
	ds_read_b128 v[210:213], v151 offset:54272
	ds_read_b128 v[214:217], v151 offset:55296
	ds_read_b128 v[218:221], v151 offset:56320
	global_load_lds_dwordx4 v[146:147], off
	s_add_i32 m0, s12, 0x2000
	s_add_u32 s10, s10, 0x80080
	v_lshl_add_u64 v[146:147], v[222:223], 0, s[70:71]
	s_addc_u32 s11, s11, 0
	s_add_i32 s12, s36, s17
	global_load_lds_dwordx4 v[146:147], off
	s_mov_b32 m0, s12
	s_nop 0
	global_load_lds_dwordx4 v160, s[10:11]
	s_add_i32 m0, s12, 0x2000
	s_nop 0
	global_load_lds_dwordx4 v132, s[10:11]
	v_lshl_add_u64 v[146:147], v[224:225], 0, s[70:71]
	s_mov_b32 m0, s24
	s_nop 0
	global_load_lds_dwordx4 v[146:147], off
	v_lshl_add_u64 v[146:147], v[226:227], 0, s[70:71]
	s_mov_b32 m0, s25
	s_nop 0
	global_load_lds_dwordx4 v[146:147], off
	s_waitcnt vmcnt(8)
	s_waitcnt lgkmcnt(0)
	s_barrier
	s_setprio 1
	s_waitcnt lgkmcnt(0)
	v_mfma_f32_16x16x32_bf16 v[60:63], v[138:141], v[186:189], v[60:63]
	v_mfma_f32_16x16x32_bf16 v[56:59], v[152:155], v[186:189], v[56:59]
	v_mfma_f32_16x16x32_bf16 v[44:47], v[138:141], v[196:199], v[44:47]
	v_mfma_f32_16x16x32_bf16 v[40:43], v[152:155], v[196:199], v[40:43]
	v_mfma_f32_16x16x32_bf16 v[28:31], v[138:141], v[206:209], v[28:31]
	v_mfma_f32_16x16x32_bf16 v[24:27], v[152:155], v[206:209], v[24:27]
	v_mfma_f32_16x16x32_bf16 v[12:15], v[138:141], v[214:217], v[12:15]
	v_mfma_f32_16x16x32_bf16 v[8:11], v[152:155], v[214:217], v[8:11]
	v_mfma_f32_16x16x32_bf16 v[60:63], v[142:145], v[190:193], v[60:63]
	v_mfma_f32_16x16x32_bf16 v[56:59], v[156:159], v[190:193], v[56:59]
	v_mfma_f32_16x16x32_bf16 v[44:47], v[142:145], v[202:205], v[44:47]
	v_mfma_f32_16x16x32_bf16 v[40:43], v[156:159], v[202:205], v[40:43]
	v_mfma_f32_16x16x32_bf16 v[28:31], v[142:145], v[210:213], v[28:31]
	v_mfma_f32_16x16x32_bf16 v[24:27], v[156:159], v[210:213], v[24:27]
	v_mfma_f32_16x16x32_bf16 v[12:15], v[142:145], v[218:221], v[12:15]
	v_mfma_f32_16x16x32_bf16 v[8:11], v[156:159], v[218:221], v[8:11]
	s_setprio 0
	s_setprio 1
	v_mfma_f32_16x16x32_bf16 v[52:55], v[168:171], v[186:189], v[52:55]
	v_mfma_f32_16x16x32_bf16 v[48:51], v[178:181], v[186:189], v[48:51]
	v_mfma_f32_16x16x32_bf16 v[36:39], v[168:171], v[196:199], v[36:39]
	v_mfma_f32_16x16x32_bf16 v[32:35], v[178:181], v[196:199], v[32:35]
	v_mfma_f32_16x16x32_bf16 v[20:23], v[168:171], v[206:209], v[20:23]
	v_mfma_f32_16x16x32_bf16 v[16:19], v[178:181], v[206:209], v[16:19]
	v_mfma_f32_16x16x32_bf16 v[4:7], v[168:171], v[214:217], v[4:7]
	v_mfma_f32_16x16x32_bf16 v[0:3], v[178:181], v[214:217], v[0:3]
	v_mfma_f32_16x16x32_bf16 v[52:55], v[174:177], v[190:193], v[52:55]
	v_mfma_f32_16x16x32_bf16 v[48:51], v[182:185], v[190:193], v[48:51]
	v_mfma_f32_16x16x32_bf16 v[36:39], v[174:177], v[202:205], v[36:39]
	v_mfma_f32_16x16x32_bf16 v[32:35], v[182:185], v[202:205], v[32:35]
	v_mfma_f32_16x16x32_bf16 v[20:23], v[174:177], v[210:213], v[20:23]
	v_mfma_f32_16x16x32_bf16 v[16:19], v[182:185], v[210:213], v[16:19]
	v_mfma_f32_16x16x32_bf16 v[4:7], v[174:177], v[218:221], v[4:7]
	v_mfma_f32_16x16x32_bf16 v[0:3], v[182:185], v[218:221], v[0:3]
	s_setprio 0
	s_barrier
	s_add_u32 s8, s8, 0x100
	s_addc_u32 s9, s9, 0
	s_add_u32 s30, s30, 0x100
	s_addc_u32 s31, s31, 0
	s_cmp_ge_i32 s34, s15
	s_mov_b32 s10, s34
	s_cbranch_scc0 .LBB0_187
	s_and_b64 vcc, exec, s[46:47]
	s_cbranch_vccz .LBB0_190

; #define PG8_STAGE(bufoff, gbase, voff) do { _Pragma("unroll") for (int _i = 0; _i < 2; ++_i) \
;         __builtin_amdgcn_global_load_lds((const unsigned*)((const char*)(gbase) + (voff)[_i]), (LAS unsigned*)(lds + (bufoff) + ldsw + _i * 8192), 16, 0, 0); } while (0)
; #define PG8_WAIT_V(n) asm volatile("s_waitcnt vmcnt(" #n ")" ::: "memory")
; #define PG8_BAR __builtin_amdgcn_s_barrier()
; template <class Epi, int GM, int GN, int GK, int LDA, int AMOD, int ASTRIDE, int WG = WGM>
; __device__ __forceinline__ void gemm_phase(LAS unsigned char* lds, const Gemm g, const Epi& E, int wv_) {
;     ...
;     for (int i = 0; i < 2; ++i) { int R, C; stage_rc(tid * 16 + i * 8192, R, C); const int Rb = Epi::PERM ? ((R & ~31) + perm32(R & 31)) : R;
;         voffA[i] = (unsigned)(R * lda + C) * 2u; voffB[i] = (unsigned)(Rb * K + C) * 2u; }
;     const size_t kstep = (size_t)(BK * 2);
;     const size_t hstepA = (size_t)HALF * lda * 2, tstepA = 2 * hstepA;
;     const size_t hstepB = (size_t)HALF * K * 2, tstepB = 2 * hstepB;
;     const unsigned ldsw = (unsigned)wid * 1024u;
;     const int aoff = lds_byte(wr * 64 + fr, fq * 8), boff = lds_byte(wc * 32 + fr, fq * 8);
;     ...
;     PG8_STAGE(PG8_SB(0, 0), cB, voffB); PG8_STAGE(PG8_SB(0, 1), cB + hstepB, voffB); PG8_STAGE(PG8_SA(0, 0), cA, voffA); PG8_STAGE(PG8_SA(0, 1), cA + hstepA, voffA);
;     if (wr == 1) PG8_BAR;
;     PG8_WAIT_V(2); PG8_BAR;
;     PG8_STAGE(PG8_SB(1, 0), cB + kstep, voffB); PG8_STAGE(PG8_SA(1, 0), cA + kstep, voffA); PG8_STAGE(PG8_SB(1, 1), cB + hstepB + kstep, voffB);
;     PG8_WAIT_V(6); PG8_BAR;
.LBB0_212:
	s_lshl_b32 s4, s4, 5
	s_and_b32 s26, s4, 0x60
	s_add_i32 m0, s9, 0x18000
	v_lshl_add_u64 v[6:7], v[6:7], 0, s[70:71]
	s_lshl_b32 s25, s3, 6
	s_lshl_b32 s3, s3, 13
	s_lshl_b32 s7, s26, 7
	s_waitcnt vmcnt(2)
	s_barrier
	global_load_lds_dwordx4 v[6:7], off
	v_lshl_add_u64 v[4:5], v[4:5], 0, s[70:71]
	s_add_i32 m0, s9, 0x1a000
	s_add_i32 s27, s9, 0x8000
	s_add_i32 s28, s9, 0xa000
	global_load_lds_dwordx4 v[4:5], off
	v_lshl_add_u64 v[0:1], v[0:1], 0, s[70:71]
	s_mov_b32 m0, s27
	s_add_u32 s4, s12, 0x20080
	global_load_lds_dwordx4 v[0:1], off
	v_lshl_add_u64 v[0:1], v[2:3], 0, s[70:71]
	s_mov_b32 m0, s28
	s_addc_u32 s5, s13, 0
	global_load_lds_dwordx4 v[0:1], off
	s_add_i32 m0, s9, 0x1c000
	s_nop 0
	global_load_lds_dwordx4 v160, s[4:5]
	v_lshl_add_u64 v[0:1], s[4:5], 0, v[132:133]
	s_add_i32 m0, s9, 0x1e000
	v_bfe_u32 v149, v8, 4, 2
	global_load_lds_dwordx4 v132, s[4:5]
	v_and_b32_e32 v148, 15, v8
	v_lshlrev_b32_e32 v0, 4, v149
	v_lshlrev_b32_e32 v1, 2, v8
	v_lshl_or_b32 v0, v148, 6, v0
	v_and_b32_e32 v1, 32, v1
	v_bitop3_b32 v2, v0, s3, v1 bitop3:0xde
	v_bitop3_b32 v150, s7, v0, v1 bitop3:0xf6
	v_lshlrev_b32_e32 v0, 13, v9
	v_and_b32_e32 v0, 0xffffc000, v0
	v_lshl_add_u32 v0, v10, 10, v0
	v_and_b32_e32 v1, 1, v9
	v_lshl_or_b32 v0, v1, 6, v0
	v_lshl_add_u32 v134, v11, 1, v0
	v_lshlrev_b32_e32 v0, 13, v12
	s_cmp_gt_i32 s19, 0
	v_and_b32_e32 v0, 0xffffc000, v0
	s_waitcnt vmcnt(6)
	s_cselect_b64 s[44:45], -1, 0
	s_add_i32 s30, s19, -2
	v_lshl_add_u32 v0, v13, 10, v0
	v_and_b32_e32 v1, 1, v12
	s_cmpk_lt_u32 s2, 0x100
	v_lshl_or_b32 v0, v1, 6, v0
	s_mov_b32 s29, 0
	s_cselect_b64 s[46:47], -1, 0
	v_mov_b32_e32 v135, v161
	v_lshl_add_u32 v136, v14, 1, v0
	v_mov_b32_e32 v137, v161
	v_add_u32_e32 v151, 0, v2
	s_barrier
	s_branch .LBB0_241

; #define PG8_STAGE(bufoff, gbase, voff) do { _Pragma("unroll") for (int _i = 0; _i < 2; ++_i) \
;         __builtin_amdgcn_global_load_lds((const unsigned*)((const char*)(gbase) + (voff)[_i]), (LAS unsigned*)(lds + (bufoff) + ldsw + _i * 8192), 16, 0, 0); } while (0)
; #define PG8_LDA(dst, b, h) do { _Pragma("unroll") for (int m = 0; m < 4; ++m) _Pragma("unroll") for (int k = 0; k < 2; ++k) dst[m][k] = *(const LAS bf16x8*)(lds + PG8_SA(b, h) + aoff + m * 2048 + k * 1024); } while (0)
; #define PG8_LDB(dst, b, h) do { _Pragma("unroll") for (int n = 0; n < 2; ++n) _Pragma("unroll") for (int k = 0; k < 2; ++k) dst[n][k] = *(const LAS bf16x8*)(lds + PG8_SB(b, h) + boff + n * 2048 + k * 1024); } while (0)
; #define PG8_MMA(ai, bj, At, Bt) do { __builtin_amdgcn_s_setprio(1); _Pragma("unroll") for (int m = 0; m < 4; ++m) _Pragma("unroll") for (int n = 0; n < 2; ++n) _Pragma("unroll") for (int k = 0; k < 2; ++k) \
;         acc[ai][bj][m][n] = __builtin_amdgcn_mfma_f32_16x16x32_bf16(Bt[n][k], At[m][k], acc[ai][bj][m][n], 0, 0, 0); __builtin_amdgcn_s_setprio(0); } while (0)
; #define PG8_WAIT_V(n) asm volatile("s_waitcnt vmcnt(" #n ")" ::: "memory")
; #define PG8_WAIT_L(n) asm volatile("s_waitcnt lgkmcnt(" #n ")" ::: "memory")
; #define PG8_BAR __builtin_amdgcn_s_barrier()
; #define PG8_SCHED __builtin_amdgcn_sched_barrier(0)
; template <class Epi, int GM, int GN, int GK, int LDA, int AMOD, int ASTRIDE, int WG = WGM>
; __device__ __forceinline__ void gemm_phase(LAS unsigned char* lds, const Gemm g, const Epi& E, int wv_) {
;     ...
;             PG8_LDB(B0, 0, 0); PG8_LDB(B1, 0, 1); PG8_SCHED; PG8_LDA(At, 0, 0); PG8_STAGE(PG8_SA(1, 1), a1 + hstepA, voffA);
;             PG8_WAIT_V(8); PG8_WAIT_L(0); PG8_BAR; PG8_MMA(0, 0, At, B0); PG8_MMA(0, 1, At, B1); PG8_BAR; PG8_SCHED;
;             PG8_LDA(At, 0, 1); PG8_STAGE(PG8_SB(0, 0), b2, voffB); PG8_STAGE(PG8_SB(0, 1), b2 + hstepB, voffB); PG8_STAGE(PG8_SA(0, 0), a2, voffA);
;             PG8_WAIT_V(8); PG8_WAIT_L(0); PG8_BAR; PG8_MMA(1, 0, At, B0); PG8_MMA(1, 1, At, B1); PG8_BAR; PG8_SCHED;
.LBB0_245:
	s_add_i32 s36, s12, 2
	s_add_u32 s13, s10, 0xfffe0080
	s_addc_u32 s14, s11, -1
	s_add_i32 s37, 0, 0x10000
	s_cmp_eq_u32 s30, s12
	s_cselect_b32 s15, s3, s14
	s_cselect_b32 s14, s5, s13
	v_add_u32_e32 v146, s37, v150
	s_cselect_b32 s13, s7, s35
	s_cselect_b32 s12, s31, s34
	s_add_i32 s42, 0, 0x14000
	ds_read_b128 v[138:141], v146
	ds_read_b128 v[142:145], v146 offset:1024
	ds_read_b128 v[152:155], v146 offset:2048
	ds_read_b128 v[156:159], v146 offset:3072
	v_add_u32_e32 v146, s42, v150
	ds_read_b128 v[174:177], v146
	ds_read_b128 v[178:181], v146 offset:1024
	ds_read_b128 v[182:185], v146 offset:2048
	ds_read_b128 v[186:189], v146 offset:3072
	s_add_i32 m0, s9, 0xc000
	ds_read_b128 v[190:193], v151
	ds_read_b128 v[202:205], v151 offset:1024
	ds_read_b128 v[206:209], v151 offset:2048
	ds_read_b128 v[210:213], v151 offset:3072
	ds_read_b128 v[214:217], v151 offset:4096
	ds_read_b128 v[218:221], v151 offset:5120
	ds_read_b128 v[222:225], v151 offset:6144
	ds_read_b128 v[226:229], v151 offset:7168
	global_load_lds_dwordx4 v134, s[10:11]
	s_add_i32 m0, s9, 0xe000
	s_nop 0
	global_load_lds_dwordx4 v136, s[10:11]
	s_waitcnt vmcnt(8)
	s_waitcnt lgkmcnt(0)
	s_barrier
	s_setprio 1
	s_waitcnt lgkmcnt(0)
	v_mfma_f32_16x16x32_bf16 v[124:127], v[138:141], v[190:193], v[124:127]
	v_mfma_f32_16x16x32_bf16 v[120:123], v[152:155], v[190:193], v[120:123]
	v_mfma_f32_16x16x32_bf16 v[116:119], v[138:141], v[206:209], v[116:119]
	v_mfma_f32_16x16x32_bf16 v[112:115], v[152:155], v[206:209], v[112:115]
	v_mfma_f32_16x16x32_bf16 v[108:111], v[138:141], v[214:217], v[108:111]
	v_mfma_f32_16x16x32_bf16 v[104:107], v[152:155], v[214:217], v[104:107]
	v_mfma_f32_16x16x32_bf16 v[100:103], v[138:141], v[222:225], v[100:103]
	v_mfma_f32_16x16x32_bf16 v[96:99], v[152:155], v[222:225], v[96:99]
	v_mfma_f32_16x16x32_bf16 v[124:127], v[142:145], v[202:205], v[124:127]
	v_mfma_f32_16x16x32_bf16 v[120:123], v[156:159], v[202:205], v[120:123]
	v_mfma_f32_16x16x32_bf16 v[116:119], v[142:145], v[210:213], v[116:119]
	v_mfma_f32_16x16x32_bf16 v[112:115], v[156:159], v[210:213], v[112:115]
	v_mfma_f32_16x16x32_bf16 v[108:111], v[142:145], v[218:221], v[108:111]
	v_mfma_f32_16x16x32_bf16 v[104:107], v[156:159], v[218:221], v[104:107]
	v_mfma_f32_16x16x32_bf16 v[100:103], v[142:145], v[226:229], v[100:103]
	v_mfma_f32_16x16x32_bf16 v[96:99], v[156:159], v[226:229], v[96:99]
	s_setprio 0
	s_setprio 1
	v_mfma_f32_16x16x32_bf16 v[60:63], v[174:177], v[190:193], v[60:63]
	v_mfma_f32_16x16x32_bf16 v[56:59], v[182:185], v[190:193], v[56:59]
	v_mfma_f32_16x16x32_bf16 v[52:55], v[174:177], v[206:209], v[52:55]
	v_mfma_f32_16x16x32_bf16 v[48:51], v[182:185], v[206:209], v[48:51]
	v_mfma_f32_16x16x32_bf16 v[44:47], v[174:177], v[214:217], v[44:47]
	v_mfma_f32_16x16x32_bf16 v[40:43], v[182:185], v[214:217], v[40:43]
	v_mfma_f32_16x16x32_bf16 v[36:39], v[174:177], v[222:225], v[36:39]
	v_mfma_f32_16x16x32_bf16 v[32:35], v[182:185], v[222:225], v[32:35]
	v_mfma_f32_16x16x32_bf16 v[60:63], v[178:181], v[202:205], v[60:63]
	v_mfma_f32_16x16x32_bf16 v[56:59], v[186:189], v[202:205], v[56:59]
	v_mfma_f32_16x16x32_bf16 v[52:55], v[178:181], v[210:213], v[52:55]
	v_mfma_f32_16x16x32_bf16 v[48:51], v[186:189], v[210:213], v[48:51]
	v_mfma_f32_16x16x32_bf16 v[44:47], v[178:181], v[218:221], v[44:47]
	v_mfma_f32_16x16x32_bf16 v[40:43], v[186:189], v[218:221], v[40:43]
	v_mfma_f32_16x16x32_bf16 v[36:39], v[178:181], v[226:229], v[36:39]
	v_mfma_f32_16x16x32_bf16 v[32:35], v[186:189], v[226:229], v[32:35]
	s_setprio 0
	s_barrier
	s_add_i32 s37, s37, s21
	v_lshl_add_u64 v[146:147], s[12:13], 0, v[160:161]
	s_mov_b32 m0, s37
	ds_read_b128 v[190:193], v151 offset:16384
	ds_read_b128 v[202:205], v151 offset:17408
	ds_read_b128 v[206:209], v151 offset:18432
	ds_read_b128 v[210:213], v151 offset:19456
	ds_read_b128 v[214:217], v151 offset:20480
	ds_read_b128 v[218:221], v151 offset:21504
	ds_read_b128 v[222:225], v151 offset:22528
	ds_read_b128 v[226:229], v151 offset:23552
	global_load_lds_dwordx4 v160, s[12:13]
	s_add_i32 m0, s37, 0x2000
	s_add_u32 s40, s12, 0x20000
	v_lshl_add_u64 v[168:169], s[12:13], 0, v[132:133]
	s_addc_u32 s41, s13, 0
	s_add_i32 s37, s42, s21
	global_load_lds_dwordx4 v132, s[12:13]
	s_mov_b32 m0, s37
	v_lshl_add_u64 v[196:197], s[14:15], 0, v[130:131]
	global_load_lds_dwordx4 v160, s[40:41]
	s_add_i32 m0, s37, 0x2000
	s_nop 0
	global_load_lds_dwordx4 v132, s[40:41]
	v_lshl_add_u64 v[170:171], s[14:15], 0, v[128:129]
	s_mov_b32 m0, s9
	s_nop 0
	global_load_lds_dwordx4 v128, s[14:15]
	s_mov_b32 m0, s22
	s_nop 0
	global_load_lds_dwordx4 v130, s[14:15]
	s_waitcnt vmcnt(8)
	s_waitcnt lgkmcnt(0)
	s_barrier
; #define PG8_STAGE(bufoff, gbase, voff) do { _Pragma("unroll") for (int _i = 0; _i < 2; ++_i) \
;         __builtin_amdgcn_global_load_lds((const unsigned*)((const char*)(gbase) + (voff)[_i]), (LAS unsigned*)(lds + (bufoff) + ldsw + _i * 8192), 16, 0, 0); } while (0)
; #define PG8_LDA(dst, b, h) do { _Pragma("unroll") for (int m = 0; m < 4; ++m) _Pragma("unroll") for (int k = 0; k < 2; ++k) dst[m][k] = *(const LAS bf16x8*)(lds + PG8_SA(b, h) + aoff + m * 2048 + k * 1024); } while (0)
; #define PG8_LDB(dst, b, h) do { _Pragma("unroll") for (int n = 0; n < 2; ++n) _Pragma("unroll") for (int k = 0; k < 2; ++k) dst[n][k] = *(const LAS bf16x8*)(lds + PG8_SB(b, h) + boff + n * 2048 + k * 1024); } while (0)
; #define PG8_MMA(ai, bj, At, Bt) do { __builtin_amdgcn_s_setprio(1); _Pragma("unroll") for (int m = 0; m < 4; ++m) _Pragma("unroll") for (int n = 0; n < 2; ++n) _Pragma("unroll") for (int k = 0; k < 2; ++k) \
;         acc[ai][bj][m][n] = __builtin_amdgcn_mfma_f32_16x16x32_bf16(Bt[n][k], At[m][k], acc[ai][bj][m][n], 0, 0, 0); __builtin_amdgcn_s_setprio(0); } while (0)
; #define PG8_WAIT_V(n) asm volatile("s_waitcnt vmcnt(" #n ")" ::: "memory")
; #define PG8_WAIT_L(n) asm volatile("s_waitcnt lgkmcnt(" #n ")" ::: "memory")
; #define PG8_BAR __builtin_amdgcn_s_barrier()
; #define PG8_SCHED __builtin_amdgcn_sched_barrier(0)
; template <class Epi, int GM, int GN, int GK, int LDA, int AMOD, int ASTRIDE, int WG = WGM>
; __device__ __forceinline__ void gemm_phase(LAS unsigned char* lds, const Gemm g, const Epi& E, int wv_) {
;     ...
;             PG8_WAIT_V(8); PG8_WAIT_L(0); PG8_BAR; PG8_MMA(1, 0, At, B0); PG8_MMA(1, 1, At, B1); PG8_BAR; PG8_SCHED;
;             PG8_LDB(B0, 1, 0); PG8_LDB(B1, 1, 1); PG8_SCHED; PG8_LDA(At, 1, 0); PG8_STAGE(PG8_SA(0, 1), a2 + hstepA, voffA);
;             PG8_WAIT_V(8); PG8_WAIT_L(0); PG8_BAR; PG8_MMA(0, 0, At, B0); PG8_MMA(0, 1, At, B1); PG8_BAR; PG8_SCHED;
	s_setprio 1
	s_waitcnt lgkmcnt(0)
	v_mfma_f32_16x16x32_bf16 v[92:95], v[138:141], v[190:193], v[92:95]
	v_mfma_f32_16x16x32_bf16 v[88:91], v[152:155], v[190:193], v[88:91]
	v_mfma_f32_16x16x32_bf16 v[84:87], v[138:141], v[206:209], v[84:87]
	v_mfma_f32_16x16x32_bf16 v[80:83], v[152:155], v[206:209], v[80:83]
	v_mfma_f32_16x16x32_bf16 v[76:79], v[138:141], v[214:217], v[76:79]
	v_mfma_f32_16x16x32_bf16 v[72:75], v[152:155], v[214:217], v[72:75]
	v_mfma_f32_16x16x32_bf16 v[68:71], v[138:141], v[222:225], v[68:71]
	v_mfma_f32_16x16x32_bf16 v[64:67], v[152:155], v[222:225], v[64:67]
	v_mfma_f32_16x16x32_bf16 v[92:95], v[142:145], v[202:205], v[92:95]
	v_mfma_f32_16x16x32_bf16 v[88:91], v[156:159], v[202:205], v[88:91]
	v_mfma_f32_16x16x32_bf16 v[84:87], v[142:145], v[210:213], v[84:87]
	v_mfma_f32_16x16x32_bf16 v[80:83], v[156:159], v[210:213], v[80:83]
	v_mfma_f32_16x16x32_bf16 v[76:79], v[142:145], v[218:221], v[76:79]
	v_mfma_f32_16x16x32_bf16 v[72:75], v[156:159], v[218:221], v[72:75]
	v_mfma_f32_16x16x32_bf16 v[68:71], v[142:145], v[226:229], v[68:71]
	v_mfma_f32_16x16x32_bf16 v[64:67], v[156:159], v[226:229], v[64:67]
	s_setprio 0
	s_setprio 1
	v_mfma_f32_16x16x32_bf16 v[28:31], v[174:177], v[190:193], v[28:31]
	v_mfma_f32_16x16x32_bf16 v[24:27], v[182:185], v[190:193], v[24:27]
	v_mfma_f32_16x16x32_bf16 v[20:23], v[174:177], v[206:209], v[20:23]
	v_mfma_f32_16x16x32_bf16 v[16:19], v[182:185], v[206:209], v[16:19]
	v_mfma_f32_16x16x32_bf16 v[12:15], v[174:177], v[214:217], v[12:15]
	v_mfma_f32_16x16x32_bf16 v[8:11], v[182:185], v[214:217], v[8:11]
	v_mfma_f32_16x16x32_bf16 v[4:7], v[174:177], v[222:225], v[4:7]
	v_mfma_f32_16x16x32_bf16 v[0:3], v[182:185], v[222:225], v[0:3]
	v_mfma_f32_16x16x32_bf16 v[28:31], v[178:181], v[202:205], v[28:31]
	v_mfma_f32_16x16x32_bf16 v[24:27], v[186:189], v[202:205], v[24:27]
	v_mfma_f32_16x16x32_bf16 v[20:23], v[178:181], v[210:213], v[20:23]
	v_mfma_f32_16x16x32_bf16 v[16:19], v[186:189], v[210:213], v[16:19]
	v_mfma_f32_16x16x32_bf16 v[12:15], v[178:181], v[218:221], v[12:15]
	v_mfma_f32_16x16x32_bf16 v[8:11], v[186:189], v[218:221], v[8:11]
	v_mfma_f32_16x16x32_bf16 v[4:7], v[178:181], v[226:229], v[4:7]
	v_mfma_f32_16x16x32_bf16 v[0:3], v[186:189], v[226:229], v[0:3]
	s_setprio 0
	s_barrier
	s_add_i32 s37, 0, 0x18000
	s_add_i32 s40, 0, 0x1c000
	v_add_u32_e32 v156, s37, v150
	v_add_u32_e32 v186, s40, v150
	ds_read_b128 v[138:141], v156
	ds_read_b128 v[142:145], v156 offset:1024
	ds_read_b128 v[152:155], v156 offset:2048
	ds_read_b128 v[156:159], v156 offset:3072
	ds_read_b128 v[174:177], v186
	ds_read_b128 v[178:181], v186 offset:1024
	ds_read_b128 v[182:185], v186 offset:2048
	ds_read_b128 v[186:189], v186 offset:3072
	s_add_u32 s14, s14, 0x20000
	s_addc_u32 s15, s15, 0
	s_mov_b32 m0, s23
	ds_read_b128 v[190:193], v151 offset:32768
	ds_read_b128 v[202:205], v151 offset:33792
	ds_read_b128 v[206:209], v151 offset:34816
	ds_read_b128 v[210:213], v151 offset:35840
	ds_read_b128 v[214:217], v151 offset:36864
	ds_read_b128 v[218:221], v151 offset:37888
	ds_read_b128 v[222:225], v151 offset:38912
	ds_read_b128 v[226:229], v151 offset:39936
	global_load_lds_dwordx4 v128, s[14:15]
	v_lshl_add_u64 v[198:199], s[14:15], 0, v[130:131]
	s_mov_b32 m0, s24
	s_nop 0
	global_load_lds_dwordx4 v130, s[14:15]
	s_waitcnt vmcnt(8)
	s_waitcnt lgkmcnt(0)
	s_barrier
	s_setprio 1
	s_waitcnt lgkmcnt(0)
	v_mfma_f32_16x16x32_bf16 v[124:127], v[138:141], v[190:193], v[124:127]
	v_mfma_f32_16x16x32_bf16 v[120:123], v[152:155], v[190:193], v[120:123]
	v_mfma_f32_16x16x32_bf16 v[116:119], v[138:141], v[206:209], v[116:119]
	v_mfma_f32_16x16x32_bf16 v[112:115], v[152:155], v[206:209], v[112:115]
	v_mfma_f32_16x16x32_bf16 v[108:111], v[138:141], v[214:217], v[108:111]
	v_mfma_f32_16x16x32_bf16 v[104:107], v[152:155], v[214:217], v[104:107]
	v_mfma_f32_16x16x32_bf16 v[100:103], v[138:141], v[222:225], v[100:103]
	v_mfma_f32_16x16x32_bf16 v[96:99], v[152:155], v[222:225], v[96:99]
	v_mfma_f32_16x16x32_bf16 v[124:127], v[142:145], v[202:205], v[124:127]
	v_mfma_f32_16x16x32_bf16 v[120:123], v[156:159], v[202:205], v[120:123]
	v_mfma_f32_16x16x32_bf16 v[116:119], v[142:145], v[210:213], v[116:119]
	v_mfma_f32_16x16x32_bf16 v[112:115], v[156:159], v[210:213], v[112:115]
	v_mfma_f32_16x16x32_bf16 v[108:111], v[142:145], v[218:221], v[108:111]
	v_mfma_f32_16x16x32_bf16 v[104:107], v[156:159], v[218:221], v[104:107]
	v_mfma_f32_16x16x32_bf16 v[100:103], v[142:145], v[226:229], v[100:103]
	v_mfma_f32_16x16x32_bf16 v[96:99], v[156:159], v[226:229], v[96:99]
	s_setprio 0
	s_setprio 1
	v_mfma_f32_16x16x32_bf16 v[60:63], v[174:177], v[190:193], v[60:63]
	v_mfma_f32_16x16x32_bf16 v[56:59], v[182:185], v[190:193], v[56:59]
	v_mfma_f32_16x16x32_bf16 v[52:55], v[174:177], v[206:209], v[52:55]
	v_mfma_f32_16x16x32_bf16 v[48:51], v[182:185], v[206:209], v[48:51]
	v_mfma_f32_16x16x32_bf16 v[44:47], v[174:177], v[214:217], v[44:47]
	v_mfma_f32_16x16x32_bf16 v[40:43], v[182:185], v[214:217], v[40:43]
	v_mfma_f32_16x16x32_bf16 v[36:39], v[174:177], v[222:225], v[36:39]
	v_mfma_f32_16x16x32_bf16 v[32:35], v[182:185], v[222:225], v[32:35]
	v_mfma_f32_16x16x32_bf16 v[60:63], v[178:181], v[202:205], v[60:63]
	v_mfma_f32_16x16x32_bf16 v[56:59], v[186:189], v[202:205], v[56:59]
	v_mfma_f32_16x16x32_bf16 v[52:55], v[178:181], v[210:213], v[52:55]
	v_mfma_f32_16x16x32_bf16 v[48:51], v[186:189], v[210:213], v[48:51]
	v_mfma_f32_16x16x32_bf16 v[44:47], v[178:181], v[218:221], v[44:47]
	v_mfma_f32_16x16x32_bf16 v[40:43], v[186:189], v[218:221], v[40:43]
	v_mfma_f32_16x16x32_bf16 v[36:39], v[178:181], v[226:229], v[36:39]
	v_mfma_f32_16x16x32_bf16 v[32:35], v[186:189], v[226:229], v[32:35]
	s_setprio 0
	s_barrier
; #define PG8_STAGE(bufoff, gbase, voff) do { _Pragma("unroll") for (int _i = 0; _i < 2; ++_i) \
;         __builtin_amdgcn_global_load_lds((const unsigned*)((const char*)(gbase) + (voff)[_i]), (LAS unsigned*)(lds + (bufoff) + ldsw + _i * 8192), 16, 0, 0); } while (0)
; #define PG8_LDA(dst, b, h) do { _Pragma("unroll") for (int m = 0; m < 4; ++m) _Pragma("unroll") for (int k = 0; k < 2; ++k) dst[m][k] = *(const LAS bf16x8*)(lds + PG8_SA(b, h) + aoff + m * 2048 + k * 1024); } while (0)
; #define PG8_MMA(ai, bj, At, Bt) do { __builtin_amdgcn_s_setprio(1); _Pragma("unroll") for (int m = 0; m < 4; ++m) _Pragma("unroll") for (int n = 0; n < 2; ++n) _Pragma("unroll") for (int k = 0; k < 2; ++k) \
;         acc[ai][bj][m][n] = __builtin_amdgcn_mfma_f32_16x16x32_bf16(Bt[n][k], At[m][k], acc[ai][bj][m][n], 0, 0, 0); __builtin_amdgcn_s_setprio(0); } while (0)
; #define PG8_WAIT_V(n) asm volatile("s_waitcnt vmcnt(" #n ")" ::: "memory")
; #define PG8_WAIT_L(n) asm volatile("s_waitcnt lgkmcnt(" #n ")" ::: "memory")
; #define PG8_BAR __builtin_amdgcn_s_barrier()
; #define PG8_SCHED __builtin_amdgcn_sched_barrier(0)
; template <class Epi, int GM, int GN, int GK, int LDA, int AMOD, int ASTRIDE, int WG = WGM>
; __device__ __forceinline__ void gemm_phase(LAS unsigned char* lds, const Gemm g, const Epi& E, int wv_) {
;     ...
;             PG8_LDA(At, 1, 1); PG8_STAGE(PG8_SB(1, 0), b3, voffB); PG8_STAGE(PG8_SB(1, 1), b3 + hstepB, voffB); PG8_STAGE(PG8_SA(1, 0), a3, voffA);
;             PG8_WAIT_V(8); PG8_WAIT_L(0); PG8_BAR; PG8_MMA(1, 0, At, B0); PG8_MMA(1, 1, At, B1); PG8_BAR; PG8_SCHED;
;         }
	s_add_i32 s14, s37, s21
	v_lshl_add_u64 v[146:147], v[146:147], 0, s[70:71]
	s_mov_b32 m0, s14
	ds_read_b128 v[190:193], v151 offset:49152
	ds_read_b128 v[202:205], v151 offset:50176
	ds_read_b128 v[206:209], v151 offset:51200
	ds_read_b128 v[210:213], v151 offset:52224
	ds_read_b128 v[214:217], v151 offset:53248
	ds_read_b128 v[218:221], v151 offset:54272
	ds_read_b128 v[222:225], v151 offset:55296
	ds_read_b128 v[226:229], v151 offset:56320
	global_load_lds_dwordx4 v[146:147], off
	s_add_i32 m0, s14, 0x2000
	s_add_u32 s12, s12, 0x20080
	v_lshl_add_u64 v[146:147], v[168:169], 0, s[70:71]
	s_addc_u32 s13, s13, 0
	s_add_i32 s14, s40, s21
	global_load_lds_dwordx4 v[146:147], off
	s_mov_b32 m0, s14
	s_nop 0
	global_load_lds_dwordx4 v160, s[12:13]
	s_add_i32 m0, s14, 0x2000
	s_nop 0
	global_load_lds_dwordx4 v132, s[12:13]
	v_lshl_add_u64 v[146:147], v[170:171], 0, s[70:71]
	s_mov_b32 m0, s27
	s_nop 0
	global_load_lds_dwordx4 v[146:147], off
	v_lshl_add_u64 v[146:147], v[196:197], 0, s[70:71]
	s_mov_b32 m0, s28
	s_nop 0
	global_load_lds_dwordx4 v[146:147], off
	s_waitcnt vmcnt(8)
	s_waitcnt lgkmcnt(0)
	s_barrier
	s_setprio 1
	s_waitcnt lgkmcnt(0)
	v_mfma_f32_16x16x32_bf16 v[92:95], v[138:141], v[190:193], v[92:95]
	v_mfma_f32_16x16x32_bf16 v[88:91], v[152:155], v[190:193], v[88:91]
	v_mfma_f32_16x16x32_bf16 v[84:87], v[138:141], v[206:209], v[84:87]
	v_mfma_f32_16x16x32_bf16 v[80:83], v[152:155], v[206:209], v[80:83]
	v_mfma_f32_16x16x32_bf16 v[76:79], v[138:141], v[214:217], v[76:79]
	v_mfma_f32_16x16x32_bf16 v[72:75], v[152:155], v[214:217], v[72:75]
	v_mfma_f32_16x16x32_bf16 v[68:71], v[138:141], v[222:225], v[68:71]
	v_mfma_f32_16x16x32_bf16 v[64:67], v[152:155], v[222:225], v[64:67]
	v_mfma_f32_16x16x32_bf16 v[92:95], v[142:145], v[202:205], v[92:95]
	v_mfma_f32_16x16x32_bf16 v[88:91], v[156:159], v[202:205], v[88:91]
	v_mfma_f32_16x16x32_bf16 v[84:87], v[142:145], v[210:213], v[84:87]
	v_mfma_f32_16x16x32_bf16 v[80:83], v[156:159], v[210:213], v[80:83]
	v_mfma_f32_16x16x32_bf16 v[76:79], v[142:145], v[218:221], v[76:79]
	v_mfma_f32_16x16x32_bf16 v[72:75], v[156:159], v[218:221], v[72:75]
	v_mfma_f32_16x16x32_bf16 v[68:71], v[142:145], v[226:229], v[68:71]
	v_mfma_f32_16x16x32_bf16 v[64:67], v[156:159], v[226:229], v[64:67]
	s_setprio 0
	s_setprio 1
	v_mfma_f32_16x16x32_bf16 v[28:31], v[174:177], v[190:193], v[28:31]
	v_mfma_f32_16x16x32_bf16 v[24:27], v[182:185], v[190:193], v[24:27]
	v_mfma_f32_16x16x32_bf16 v[20:23], v[174:177], v[206:209], v[20:23]
	v_mfma_f32_16x16x32_bf16 v[16:19], v[182:185], v[206:209], v[16:19]
	v_mfma_f32_16x16x32_bf16 v[12:15], v[174:177], v[214:217], v[12:15]
	v_mfma_f32_16x16x32_bf16 v[8:11], v[182:185], v[214:217], v[8:11]
	v_mfma_f32_16x16x32_bf16 v[4:7], v[174:177], v[222:225], v[4:7]
	v_mfma_f32_16x16x32_bf16 v[0:3], v[182:185], v[222:225], v[0:3]
	v_mfma_f32_16x16x32_bf16 v[28:31], v[178:181], v[202:205], v[28:31]
	v_mfma_f32_16x16x32_bf16 v[24:27], v[186:189], v[202:205], v[24:27]
	v_mfma_f32_16x16x32_bf16 v[20:23], v[178:181], v[210:213], v[20:23]
	v_mfma_f32_16x16x32_bf16 v[16:19], v[186:189], v[210:213], v[16:19]
	v_mfma_f32_16x16x32_bf16 v[12:15], v[178:181], v[218:221], v[12:15]
	v_mfma_f32_16x16x32_bf16 v[8:11], v[186:189], v[218:221], v[8:11]
	v_mfma_f32_16x16x32_bf16 v[4:7], v[178:181], v[226:229], v[4:7]
	v_mfma_f32_16x16x32_bf16 v[0:3], v[186:189], v[226:229], v[0:3]
	s_setprio 0
	s_barrier
	s_add_u32 s10, s10, 0x100
	s_addc_u32 s11, s11, 0
	s_add_u32 s34, s34, 0x100
	s_addc_u32 s35, s35, 0
	s_cmp_ge_i32 s36, s19
	s_mov_b32 s12, s36
	s_cbranch_scc0 .LBB0_245
	s_and_b64 vcc, exec, s[46:47]
	s_cbranch_vccz .LBB0_248

; #define PG8_STAGE(bufoff, gbase, voff) do { _Pragma("unroll") for (int _i = 0; _i < 2; ++_i) \
;         __builtin_amdgcn_global_load_lds((const unsigned*)((const char*)(gbase) + (voff)[_i]), (LAS unsigned*)(lds + (bufoff) + ldsw + _i * 8192), 16, 0, 0); } while (0)
; #define PG8_WAIT_V(n) asm volatile("s_waitcnt vmcnt(" #n ")" ::: "memory")
; #define PG8_BAR __builtin_amdgcn_s_barrier()
; template <class Epi, int GM, int GN, int GK, int LDA, int AMOD, int ASTRIDE, int WG = WGM>
; __device__ __forceinline__ void gemm_phase(LAS unsigned char* lds, const Gemm g, const Epi& E, int wv_) {
;     ...
;     for (int i = 0; i < 2; ++i) { int R, C; stage_rc(tid * 16 + i * 8192, R, C); const int Rb = Epi::PERM ? ((R & ~31) + perm32(R & 31)) : R;
;         voffA[i] = (unsigned)(R * lda + C) * 2u; voffB[i] = (unsigned)(Rb * K + C) * 2u; }
;     const size_t kstep = (size_t)(BK * 2);
;     const size_t hstepA = (size_t)HALF * lda * 2, tstepA = 2 * hstepA;
;     const size_t hstepB = (size_t)HALF * K * 2, tstepB = 2 * hstepB;
;     const unsigned ldsw = (unsigned)wid * 1024u;
;     const int aoff = lds_byte(wr * 64 + fr, fq * 8), boff = lds_byte(wc * 32 + fr, fq * 8);
;     ...
;     PG8_STAGE(PG8_SB(0, 0), cB, voffB); PG8_STAGE(PG8_SB(0, 1), cB + hstepB, voffB); PG8_STAGE(PG8_SA(0, 0), cA, voffA); PG8_STAGE(PG8_SA(0, 1), cA + hstepA, voffA);
;     if (wr == 1) PG8_BAR;
;     PG8_WAIT_V(2); PG8_BAR;
;     PG8_STAGE(PG8_SB(1, 0), cB + kstep, voffB); PG8_STAGE(PG8_SA(1, 0), cA + kstep, voffA); PG8_STAGE(PG8_SB(1, 1), cB + hstepB + kstep, voffB);
;     PG8_WAIT_V(6); PG8_BAR;
.LBB0_292:
	s_lshl_b32 s5, s5, 5
	s_and_b32 s31, s5, 0x60
	s_add_i32 m0, s26, 0x18000
	v_lshl_add_u64 v[6:7], v[6:7], 0, s[70:71]
	s_lshl_b32 s30, s3, 6
	s_lshl_b32 s3, s3, 13
	s_lshl_b32 s5, s31, 7
	s_waitcnt vmcnt(2)
	s_barrier
	global_load_lds_dwordx4 v[6:7], off
	v_lshl_add_u64 v[4:5], v[4:5], 0, s[70:71]
	s_add_i32 m0, s26, 0x1a000
	s_add_i32 s34, s26, 0x8000
	s_add_i32 s35, s26, 0xa000
	global_load_lds_dwordx4 v[4:5], off
	v_lshl_add_u64 v[0:1], v[0:1], 0, s[70:71]
	s_mov_b32 m0, s34
	s_add_u32 s6, s18, 0x20080
	global_load_lds_dwordx4 v[0:1], off
	v_lshl_add_u64 v[0:1], v[2:3], 0, s[70:71]
	s_mov_b32 m0, s35
	s_addc_u32 s7, s19, 0
	global_load_lds_dwordx4 v[0:1], off
	s_add_i32 m0, s26, 0x1c000
	s_nop 0
	global_load_lds_dwordx4 v160, s[6:7]
	v_lshl_add_u64 v[0:1], s[6:7], 0, v[132:133]
	s_add_i32 m0, s26, 0x1e000
	v_bfe_u32 v139, v8, 4, 2
	global_load_lds_dwordx4 v132, s[6:7]
	v_and_b32_e32 v138, 15, v8
	v_lshlrev_b32_e32 v0, 4, v139
	v_lshlrev_b32_e32 v1, 2, v8
	v_lshl_or_b32 v0, v138, 6, v0
	v_and_b32_e32 v1, 32, v1
	v_bitop3_b32 v2, v0, s3, v1 bitop3:0xde
	v_bitop3_b32 v140, s5, v0, v1 bitop3:0xf6
	v_lshlrev_b32_e32 v0, 13, v9
	v_and_b32_e32 v0, 0xffffc000, v0
	v_lshl_add_u32 v0, v10, 10, v0
	v_and_b32_e32 v1, 1, v9
	v_lshl_or_b32 v0, v1, 6, v0
	v_lshl_add_u32 v134, v11, 1, v0
	v_lshlrev_b32_e32 v0, 13, v12
	s_cmp_gt_i32 s23, 0
	v_and_b32_e32 v0, 0xffffc000, v0
	s_sext_i32_i8 s11, s2
	s_waitcnt vmcnt(6)
	s_cselect_b64 s[2:3], -1, 0
	s_add_i32 s37, s23, -2
	v_lshl_add_u32 v0, v13, 10, v0
	v_and_b32_e32 v1, 1, v12
	s_cmpk_lt_u32 s4, 0x100
	v_lshl_or_b32 v0, v1, 6, v0
	s_mov_b32 s36, 0
	s_cselect_b64 s[4:5], -1, 0
	v_mov_b32_e32 v135, v161
	v_lshl_add_u32 v136, v14, 1, v0
	v_mov_b32_e32 v137, v161
	v_add_u32_e32 v141, 0, v2
	s_barrier
	s_branch .LBB0_295

; #define PG8_STAGE(bufoff, gbase, voff) do { _Pragma("unroll") for (int _i = 0; _i < 2; ++_i) \
;         __builtin_amdgcn_global_load_lds((const unsigned*)((const char*)(gbase) + (voff)[_i]), (LAS unsigned*)(lds + (bufoff) + ldsw + _i * 8192), 16, 0, 0); } while (0)
; #define PG8_LDA(dst, b, h) do { _Pragma("unroll") for (int m = 0; m < 4; ++m) _Pragma("unroll") for (int k = 0; k < 2; ++k) dst[m][k] = *(const LAS bf16x8*)(lds + PG8_SA(b, h) + aoff + m * 2048 + k * 1024); } while (0)
; #define PG8_LDB(dst, b, h) do { _Pragma("unroll") for (int n = 0; n < 2; ++n) _Pragma("unroll") for (int k = 0; k < 2; ++k) dst[n][k] = *(const LAS bf16x8*)(lds + PG8_SB(b, h) + boff + n * 2048 + k * 1024); } while (0)
; #define PG8_MMA(ai, bj, At, Bt) do { __builtin_amdgcn_s_setprio(1); _Pragma("unroll") for (int m = 0; m < 4; ++m) _Pragma("unroll") for (int n = 0; n < 2; ++n) _Pragma("unroll") for (int k = 0; k < 2; ++k) \
;         acc[ai][bj][m][n] = __builtin_amdgcn_mfma_f32_16x16x32_bf16(Bt[n][k], At[m][k], acc[ai][bj][m][n], 0, 0, 0); __builtin_amdgcn_s_setprio(0); } while (0)
; #define PG8_WAIT_V(n) asm volatile("s_waitcnt vmcnt(" #n ")" ::: "memory")
; #define PG8_WAIT_L(n) asm volatile("s_waitcnt lgkmcnt(" #n ")" ::: "memory")
; #define PG8_BAR __builtin_amdgcn_s_barrier()
; #define PG8_SCHED __builtin_amdgcn_sched_barrier(0)
; template <class Epi, int GM, int GN, int GK, int LDA, int AMOD, int ASTRIDE, int WG = WGM>
; __device__ __forceinline__ void gemm_phase(LAS unsigned char* lds, const Gemm g, const Epi& E, int wv_) {
;     ...
;             PG8_LDB(B0, 0, 0); PG8_LDB(B1, 0, 1); PG8_SCHED; PG8_LDA(At, 0, 0); PG8_STAGE(PG8_SA(1, 1), a1 + hstepA, voffA);
;             PG8_WAIT_V(8); PG8_WAIT_L(0); PG8_BAR; PG8_MMA(0, 0, At, B0); PG8_MMA(0, 1, At, B1); PG8_BAR; PG8_SCHED;
;             PG8_LDA(At, 0, 1); PG8_STAGE(PG8_SB(0, 0), b2, voffB); PG8_STAGE(PG8_SB(0, 1), b2 + hstepB, voffB); PG8_STAGE(PG8_SA(0, 0), a2, voffA);
;             PG8_WAIT_V(8); PG8_WAIT_L(0); PG8_BAR; PG8_MMA(1, 0, At, B0); PG8_MMA(1, 1, At, B1); PG8_BAR; PG8_SCHED;
.LBB0_303:
	s_add_i32 s44, s18, 2
	s_add_u32 s19, s16, 0xfffe0080
	s_addc_u32 s20, s17, -1
	s_add_i32 s45, 0, 0x10000
	s_cmp_eq_u32 s37, s18
	s_cselect_b32 s21, s7, s20
	s_cselect_b32 s20, s9, s19
	s_cselect_b32 s19, s40, s43
	s_cselect_b32 s18, s41, s42
	s_add_i32 s48, 0, 0x14000
	v_add_u32_e32 v154, s45, v140
	v_add_u32_e32 v158, s48, v140
	ds_read_b128 v[142:145], v154
	ds_read_b128 v[146:149], v154 offset:1024
	ds_read_b128 v[150:153], v154 offset:2048
	ds_read_b128 v[154:157], v154 offset:3072
	ds_read_b128 v[174:177], v158
	ds_read_b128 v[178:181], v158 offset:1024
	ds_read_b128 v[182:185], v158 offset:2048
	ds_read_b128 v[186:189], v158 offset:3072
	s_add_i32 m0, s26, 0xc000
	ds_read_b128 v[190:193], v141
	ds_read_b128 v[202:205], v141 offset:1024
	ds_read_b128 v[206:209], v141 offset:2048
	ds_read_b128 v[210:213], v141 offset:3072
	ds_read_b128 v[214:217], v141 offset:4096
	ds_read_b128 v[218:221], v141 offset:5120
	ds_read_b128 v[222:225], v141 offset:6144
	ds_read_b128 v[226:229], v141 offset:7168
	global_load_lds_dwordx4 v134, s[16:17]
	s_add_i32 m0, s26, 0xe000
	s_nop 0
	global_load_lds_dwordx4 v136, s[16:17]
	s_waitcnt vmcnt(8)
	s_waitcnt lgkmcnt(0)
	s_barrier
	s_setprio 1
	s_waitcnt lgkmcnt(0)
	v_mfma_f32_16x16x32_bf16 v[124:127], v[142:145], v[190:193], v[124:127]
	v_mfma_f32_16x16x32_bf16 v[120:123], v[150:153], v[190:193], v[120:123]
	v_mfma_f32_16x16x32_bf16 v[108:111], v[142:145], v[206:209], v[108:111]
	v_mfma_f32_16x16x32_bf16 v[104:107], v[150:153], v[206:209], v[104:107]
	v_mfma_f32_16x16x32_bf16 v[92:95], v[142:145], v[214:217], v[92:95]
	v_mfma_f32_16x16x32_bf16 v[88:91], v[150:153], v[214:217], v[88:91]
	v_mfma_f32_16x16x32_bf16 v[76:79], v[142:145], v[222:225], v[76:79]
	v_mfma_f32_16x16x32_bf16 v[72:75], v[150:153], v[222:225], v[72:75]
	v_mfma_f32_16x16x32_bf16 v[124:127], v[146:149], v[202:205], v[124:127]
	v_mfma_f32_16x16x32_bf16 v[120:123], v[154:157], v[202:205], v[120:123]
	v_mfma_f32_16x16x32_bf16 v[108:111], v[146:149], v[210:213], v[108:111]
	v_mfma_f32_16x16x32_bf16 v[104:107], v[154:157], v[210:213], v[104:107]
	v_mfma_f32_16x16x32_bf16 v[92:95], v[146:149], v[218:221], v[92:95]
	v_mfma_f32_16x16x32_bf16 v[88:91], v[154:157], v[218:221], v[88:91]
	v_mfma_f32_16x16x32_bf16 v[76:79], v[146:149], v[226:229], v[76:79]
	v_mfma_f32_16x16x32_bf16 v[72:75], v[154:157], v[226:229], v[72:75]
	s_setprio 0
	s_setprio 1
	v_mfma_f32_16x16x32_bf16 v[116:119], v[174:177], v[190:193], v[116:119]
	v_mfma_f32_16x16x32_bf16 v[112:115], v[182:185], v[190:193], v[112:115]
	v_mfma_f32_16x16x32_bf16 v[100:103], v[174:177], v[206:209], v[100:103]
	v_mfma_f32_16x16x32_bf16 v[96:99], v[182:185], v[206:209], v[96:99]
	v_mfma_f32_16x16x32_bf16 v[84:87], v[174:177], v[214:217], v[84:87]
	v_mfma_f32_16x16x32_bf16 v[80:83], v[182:185], v[214:217], v[80:83]
	v_mfma_f32_16x16x32_bf16 v[68:71], v[174:177], v[222:225], v[68:71]
	v_mfma_f32_16x16x32_bf16 v[64:67], v[182:185], v[222:225], v[64:67]
	v_mfma_f32_16x16x32_bf16 v[116:119], v[178:181], v[202:205], v[116:119]
	v_mfma_f32_16x16x32_bf16 v[112:115], v[186:189], v[202:205], v[112:115]
	v_mfma_f32_16x16x32_bf16 v[100:103], v[178:181], v[210:213], v[100:103]
	v_mfma_f32_16x16x32_bf16 v[96:99], v[186:189], v[210:213], v[96:99]
	v_mfma_f32_16x16x32_bf16 v[84:87], v[178:181], v[218:221], v[84:87]
	v_mfma_f32_16x16x32_bf16 v[80:83], v[186:189], v[218:221], v[80:83]
	v_mfma_f32_16x16x32_bf16 v[68:71], v[178:181], v[226:229], v[68:71]
	v_mfma_f32_16x16x32_bf16 v[64:67], v[186:189], v[226:229], v[64:67]
	s_setprio 0
	s_barrier
	s_add_i32 s45, s45, s25
	v_lshl_add_u64 v[158:159], s[18:19], 0, v[160:161]
	s_mov_b32 m0, s45
	ds_read_b128 v[190:193], v141 offset:16384
	ds_read_b128 v[202:205], v141 offset:17408
	ds_read_b128 v[206:209], v141 offset:18432
	ds_read_b128 v[210:213], v141 offset:19456
	ds_read_b128 v[214:217], v141 offset:20480
	ds_read_b128 v[218:221], v141 offset:21504
	ds_read_b128 v[222:225], v141 offset:22528
	ds_read_b128 v[226:229], v141 offset:23552
	global_load_lds_dwordx4 v160, s[18:19]
	s_add_i32 m0, s45, 0x2000
	s_add_u32 s46, s18, 0x20000
	v_lshl_add_u64 v[168:169], s[18:19], 0, v[132:133]
	s_addc_u32 s47, s19, 0
	s_add_i32 s45, s48, s25
	global_load_lds_dwordx4 v132, s[18:19]
	s_mov_b32 m0, s45
	v_lshl_add_u64 v[196:197], s[20:21], 0, v[130:131]
	global_load_lds_dwordx4 v160, s[46:47]
	s_add_i32 m0, s45, 0x2000
	s_nop 0
	global_load_lds_dwordx4 v132, s[46:47]
	v_lshl_add_u64 v[170:171], s[20:21], 0, v[128:129]
	s_mov_b32 m0, s26
	s_nop 0
	global_load_lds_dwordx4 v128, s[20:21]
	s_mov_b32 m0, s27
	s_nop 0
	global_load_lds_dwordx4 v130, s[20:21]
	s_waitcnt vmcnt(8)
	s_waitcnt lgkmcnt(0)
	s_barrier
; #define PG8_STAGE(bufoff, gbase, voff) do { _Pragma("unroll") for (int _i = 0; _i < 2; ++_i) \
;         __builtin_amdgcn_global_load_lds((const unsigned*)((const char*)(gbase) + (voff)[_i]), (LAS unsigned*)(lds + (bufoff) + ldsw + _i * 8192), 16, 0, 0); } while (0)
; #define PG8_LDA(dst, b, h) do { _Pragma("unroll") for (int m = 0; m < 4; ++m) _Pragma("unroll") for (int k = 0; k < 2; ++k) dst[m][k] = *(const LAS bf16x8*)(lds + PG8_SA(b, h) + aoff + m * 2048 + k * 1024); } while (0)
; #define PG8_LDB(dst, b, h) do { _Pragma("unroll") for (int n = 0; n < 2; ++n) _Pragma("unroll") for (int k = 0; k < 2; ++k) dst[n][k] = *(const LAS bf16x8*)(lds + PG8_SB(b, h) + boff + n * 2048 + k * 1024); } while (0)
; #define PG8_MMA(ai, bj, At, Bt) do { __builtin_amdgcn_s_setprio(1); _Pragma("unroll") for (int m = 0; m < 4; ++m) _Pragma("unroll") for (int n = 0; n < 2; ++n) _Pragma("unroll") for (int k = 0; k < 2; ++k) \
;         acc[ai][bj][m][n] = __builtin_amdgcn_mfma_f32_16x16x32_bf16(Bt[n][k], At[m][k], acc[ai][bj][m][n], 0, 0, 0); __builtin_amdgcn_s_setprio(0); } while (0)
; #define PG8_WAIT_V(n) asm volatile("s_waitcnt vmcnt(" #n ")" ::: "memory")
; #define PG8_WAIT_L(n) asm volatile("s_waitcnt lgkmcnt(" #n ")" ::: "memory")
; #define PG8_BAR __builtin_amdgcn_s_barrier()
; #define PG8_SCHED __builtin_amdgcn_sched_barrier(0)
; template <class Epi, int GM, int GN, int GK, int LDA, int AMOD, int ASTRIDE, int WG = WGM>
; __device__ __forceinline__ void gemm_phase(LAS unsigned char* lds, const Gemm g, const Epi& E, int wv_) {
;     ...
;             PG8_WAIT_V(8); PG8_WAIT_L(0); PG8_BAR; PG8_MMA(1, 0, At, B0); PG8_MMA(1, 1, At, B1); PG8_BAR; PG8_SCHED;
;             PG8_LDB(B0, 1, 0); PG8_LDB(B1, 1, 1); PG8_SCHED; PG8_LDA(At, 1, 0); PG8_STAGE(PG8_SA(0, 1), a2 + hstepA, voffA);
;             PG8_WAIT_V(8); PG8_WAIT_L(0); PG8_BAR; PG8_MMA(0, 0, At, B0); PG8_MMA(0, 1, At, B1); PG8_BAR; PG8_SCHED;
	s_setprio 1
	s_waitcnt lgkmcnt(0)
	v_mfma_f32_16x16x32_bf16 v[60:63], v[142:145], v[190:193], v[60:63]
	v_mfma_f32_16x16x32_bf16 v[56:59], v[150:153], v[190:193], v[56:59]
	v_mfma_f32_16x16x32_bf16 v[44:47], v[142:145], v[206:209], v[44:47]
	v_mfma_f32_16x16x32_bf16 v[40:43], v[150:153], v[206:209], v[40:43]
	v_mfma_f32_16x16x32_bf16 v[28:31], v[142:145], v[214:217], v[28:31]
	v_mfma_f32_16x16x32_bf16 v[24:27], v[150:153], v[214:217], v[24:27]
	v_mfma_f32_16x16x32_bf16 v[12:15], v[142:145], v[222:225], v[12:15]
	v_mfma_f32_16x16x32_bf16 v[8:11], v[150:153], v[222:225], v[8:11]
	v_mfma_f32_16x16x32_bf16 v[60:63], v[146:149], v[202:205], v[60:63]
	v_mfma_f32_16x16x32_bf16 v[56:59], v[154:157], v[202:205], v[56:59]
	v_mfma_f32_16x16x32_bf16 v[44:47], v[146:149], v[210:213], v[44:47]
	v_mfma_f32_16x16x32_bf16 v[40:43], v[154:157], v[210:213], v[40:43]
	v_mfma_f32_16x16x32_bf16 v[28:31], v[146:149], v[218:221], v[28:31]
	v_mfma_f32_16x16x32_bf16 v[24:27], v[154:157], v[218:221], v[24:27]
	v_mfma_f32_16x16x32_bf16 v[12:15], v[146:149], v[226:229], v[12:15]
	v_mfma_f32_16x16x32_bf16 v[8:11], v[154:157], v[226:229], v[8:11]
	s_setprio 0
	s_setprio 1
	v_mfma_f32_16x16x32_bf16 v[52:55], v[174:177], v[190:193], v[52:55]
	v_mfma_f32_16x16x32_bf16 v[48:51], v[182:185], v[190:193], v[48:51]
	v_mfma_f32_16x16x32_bf16 v[36:39], v[174:177], v[206:209], v[36:39]
	v_mfma_f32_16x16x32_bf16 v[32:35], v[182:185], v[206:209], v[32:35]
	v_mfma_f32_16x16x32_bf16 v[20:23], v[174:177], v[214:217], v[20:23]
	v_mfma_f32_16x16x32_bf16 v[16:19], v[182:185], v[214:217], v[16:19]
	v_mfma_f32_16x16x32_bf16 v[4:7], v[174:177], v[222:225], v[4:7]
	v_mfma_f32_16x16x32_bf16 v[0:3], v[182:185], v[222:225], v[0:3]
	v_mfma_f32_16x16x32_bf16 v[52:55], v[178:181], v[202:205], v[52:55]
	v_mfma_f32_16x16x32_bf16 v[48:51], v[186:189], v[202:205], v[48:51]
	v_mfma_f32_16x16x32_bf16 v[36:39], v[178:181], v[210:213], v[36:39]
	v_mfma_f32_16x16x32_bf16 v[32:35], v[186:189], v[210:213], v[32:35]
	v_mfma_f32_16x16x32_bf16 v[20:23], v[178:181], v[218:221], v[20:23]
	v_mfma_f32_16x16x32_bf16 v[16:19], v[186:189], v[218:221], v[16:19]
	v_mfma_f32_16x16x32_bf16 v[4:7], v[178:181], v[226:229], v[4:7]
	v_mfma_f32_16x16x32_bf16 v[0:3], v[186:189], v[226:229], v[0:3]
	s_setprio 0
	s_barrier
	s_add_i32 s45, 0, 0x18000
	s_add_i32 s46, 0, 0x1c000
	v_add_u32_e32 v154, s45, v140
	v_add_u32_e32 v186, s46, v140
	ds_read_b128 v[142:145], v154
	ds_read_b128 v[146:149], v154 offset:1024
	ds_read_b128 v[150:153], v154 offset:2048
	ds_read_b128 v[154:157], v154 offset:3072
	ds_read_b128 v[174:177], v186
	ds_read_b128 v[178:181], v186 offset:1024
	ds_read_b128 v[182:185], v186 offset:2048
	ds_read_b128 v[186:189], v186 offset:3072
	s_add_u32 s20, s20, 0x20000
	s_addc_u32 s21, s21, 0
	s_mov_b32 m0, s28
	ds_read_b128 v[190:193], v141 offset:32768
	ds_read_b128 v[202:205], v141 offset:33792
	ds_read_b128 v[206:209], v141 offset:34816
	ds_read_b128 v[210:213], v141 offset:35840
	ds_read_b128 v[214:217], v141 offset:36864
	ds_read_b128 v[218:221], v141 offset:37888
	ds_read_b128 v[222:225], v141 offset:38912
	ds_read_b128 v[226:229], v141 offset:39936
	global_load_lds_dwordx4 v128, s[20:21]
	v_lshl_add_u64 v[198:199], s[20:21], 0, v[130:131]
	s_mov_b32 m0, s29
	s_nop 0
	global_load_lds_dwordx4 v130, s[20:21]
	s_waitcnt vmcnt(8)
	s_waitcnt lgkmcnt(0)
	s_barrier
	s_setprio 1
	s_waitcnt lgkmcnt(0)
	v_mfma_f32_16x16x32_bf16 v[124:127], v[142:145], v[190:193], v[124:127]
	v_mfma_f32_16x16x32_bf16 v[120:123], v[150:153], v[190:193], v[120:123]
	v_mfma_f32_16x16x32_bf16 v[108:111], v[142:145], v[206:209], v[108:111]
	v_mfma_f32_16x16x32_bf16 v[104:107], v[150:153], v[206:209], v[104:107]
	v_mfma_f32_16x16x32_bf16 v[92:95], v[142:145], v[214:217], v[92:95]
	v_mfma_f32_16x16x32_bf16 v[88:91], v[150:153], v[214:217], v[88:91]
	v_mfma_f32_16x16x32_bf16 v[76:79], v[142:145], v[222:225], v[76:79]
	v_mfma_f32_16x16x32_bf16 v[72:75], v[150:153], v[222:225], v[72:75]
	v_mfma_f32_16x16x32_bf16 v[124:127], v[146:149], v[202:205], v[124:127]
	v_mfma_f32_16x16x32_bf16 v[120:123], v[154:157], v[202:205], v[120:123]
	v_mfma_f32_16x16x32_bf16 v[108:111], v[146:149], v[210:213], v[108:111]
	v_mfma_f32_16x16x32_bf16 v[104:107], v[154:157], v[210:213], v[104:107]
	v_mfma_f32_16x16x32_bf16 v[92:95], v[146:149], v[218:221], v[92:95]
	v_mfma_f32_16x16x32_bf16 v[88:91], v[154:157], v[218:221], v[88:91]
	v_mfma_f32_16x16x32_bf16 v[76:79], v[146:149], v[226:229], v[76:79]
	v_mfma_f32_16x16x32_bf16 v[72:75], v[154:157], v[226:229], v[72:75]
	s_setprio 0
	s_setprio 1
	v_mfma_f32_16x16x32_bf16 v[116:119], v[174:177], v[190:193], v[116:119]
	v_mfma_f32_16x16x32_bf16 v[112:115], v[182:185], v[190:193], v[112:115]
	v_mfma_f32_16x16x32_bf16 v[100:103], v[174:177], v[206:209], v[100:103]
	v_mfma_f32_16x16x32_bf16 v[96:99], v[182:185], v[206:209], v[96:99]
	v_mfma_f32_16x16x32_bf16 v[84:87], v[174:177], v[214:217], v[84:87]
	v_mfma_f32_16x16x32_bf16 v[80:83], v[182:185], v[214:217], v[80:83]
	v_mfma_f32_16x16x32_bf16 v[68:71], v[174:177], v[222:225], v[68:71]
	v_mfma_f32_16x16x32_bf16 v[64:67], v[182:185], v[222:225], v[64:67]
	v_mfma_f32_16x16x32_bf16 v[116:119], v[178:181], v[202:205], v[116:119]
	v_mfma_f32_16x16x32_bf16 v[112:115], v[186:189], v[202:205], v[112:115]
	v_mfma_f32_16x16x32_bf16 v[100:103], v[178:181], v[210:213], v[100:103]
	v_mfma_f32_16x16x32_bf16 v[96:99], v[186:189], v[210:213], v[96:99]
	v_mfma_f32_16x16x32_bf16 v[84:87], v[178:181], v[218:221], v[84:87]
	v_mfma_f32_16x16x32_bf16 v[80:83], v[186:189], v[218:221], v[80:83]
	v_mfma_f32_16x16x32_bf16 v[68:71], v[178:181], v[226:229], v[68:71]
	v_mfma_f32_16x16x32_bf16 v[64:67], v[186:189], v[226:229], v[64:67]
	s_setprio 0
	s_barrier
; #define PG8_STAGE(bufoff, gbase, voff) do { _Pragma("unroll") for (int _i = 0; _i < 2; ++_i) \
;         __builtin_amdgcn_global_load_lds((const unsigned*)((const char*)(gbase) + (voff)[_i]), (LAS unsigned*)(lds + (bufoff) + ldsw + _i * 8192), 16, 0, 0); } while (0)
; #define PG8_LDA(dst, b, h) do { _Pragma("unroll") for (int m = 0; m < 4; ++m) _Pragma("unroll") for (int k = 0; k < 2; ++k) dst[m][k] = *(const LAS bf16x8*)(lds + PG8_SA(b, h) + aoff + m * 2048 + k * 1024); } while (0)
; #define PG8_MMA(ai, bj, At, Bt) do { __builtin_amdgcn_s_setprio(1); _Pragma("unroll") for (int m = 0; m < 4; ++m) _Pragma("unroll") for (int n = 0; n < 2; ++n) _Pragma("unroll") for (int k = 0; k < 2; ++k) \
;         acc[ai][bj][m][n] = __builtin_amdgcn_mfma_f32_16x16x32_bf16(Bt[n][k], At[m][k], acc[ai][bj][m][n], 0, 0, 0); __builtin_amdgcn_s_setprio(0); } while (0)
; #define PG8_WAIT_V(n) asm volatile("s_waitcnt vmcnt(" #n ")" ::: "memory")
; #define PG8_WAIT_L(n) asm volatile("s_waitcnt lgkmcnt(" #n ")" ::: "memory")
; #define PG8_BAR __builtin_amdgcn_s_barrier()
; #define PG8_SCHED __builtin_amdgcn_sched_barrier(0)
; template <class Epi, int GM, int GN, int GK, int LDA, int AMOD, int ASTRIDE, int WG = WGM>
; __device__ __forceinline__ void gemm_phase(LAS unsigned char* lds, const Gemm g, const Epi& E, int wv_) {
;     ...
;             PG8_LDA(At, 1, 1); PG8_STAGE(PG8_SB(1, 0), b3, voffB); PG8_STAGE(PG8_SB(1, 1), b3 + hstepB, voffB); PG8_STAGE(PG8_SA(1, 0), a3, voffA);
;             PG8_WAIT_V(8); PG8_WAIT_L(0); PG8_BAR; PG8_MMA(1, 0, At, B0); PG8_MMA(1, 1, At, B1); PG8_BAR; PG8_SCHED;
;         }
	s_add_i32 s20, s45, s25
	v_lshl_add_u64 v[158:159], v[158:159], 0, s[70:71]
	s_mov_b32 m0, s20
	ds_read_b128 v[190:193], v141 offset:49152
	ds_read_b128 v[202:205], v141 offset:50176
	ds_read_b128 v[206:209], v141 offset:51200
	ds_read_b128 v[210:213], v141 offset:52224
	ds_read_b128 v[214:217], v141 offset:53248
	ds_read_b128 v[218:221], v141 offset:54272
	ds_read_b128 v[222:225], v141 offset:55296
	ds_read_b128 v[226:229], v141 offset:56320
	global_load_lds_dwordx4 v[158:159], off
	s_add_i32 m0, s20, 0x2000
	s_add_u32 s18, s18, 0x20080
	v_lshl_add_u64 v[158:159], v[168:169], 0, s[70:71]
	s_addc_u32 s19, s19, 0
	s_add_i32 s20, s46, s25
	global_load_lds_dwordx4 v[158:159], off
	s_mov_b32 m0, s20
	s_nop 0
	global_load_lds_dwordx4 v160, s[18:19]
	s_add_i32 m0, s20, 0x2000
	s_nop 0
	global_load_lds_dwordx4 v132, s[18:19]
	v_lshl_add_u64 v[158:159], v[170:171], 0, s[70:71]
	s_mov_b32 m0, s34
	s_nop 0
	global_load_lds_dwordx4 v[158:159], off
	v_lshl_add_u64 v[158:159], v[196:197], 0, s[70:71]
	s_mov_b32 m0, s35
	s_nop 0
	global_load_lds_dwordx4 v[158:159], off
	s_waitcnt vmcnt(8)
	s_waitcnt lgkmcnt(0)
	s_barrier
	s_setprio 1
	s_waitcnt lgkmcnt(0)
	v_mfma_f32_16x16x32_bf16 v[60:63], v[142:145], v[190:193], v[60:63]
	v_mfma_f32_16x16x32_bf16 v[56:59], v[150:153], v[190:193], v[56:59]
	v_mfma_f32_16x16x32_bf16 v[44:47], v[142:145], v[206:209], v[44:47]
	v_mfma_f32_16x16x32_bf16 v[40:43], v[150:153], v[206:209], v[40:43]
	v_mfma_f32_16x16x32_bf16 v[28:31], v[142:145], v[214:217], v[28:31]
	v_mfma_f32_16x16x32_bf16 v[24:27], v[150:153], v[214:217], v[24:27]
	v_mfma_f32_16x16x32_bf16 v[12:15], v[142:145], v[222:225], v[12:15]
	v_mfma_f32_16x16x32_bf16 v[8:11], v[150:153], v[222:225], v[8:11]
	v_mfma_f32_16x16x32_bf16 v[60:63], v[146:149], v[202:205], v[60:63]
	v_mfma_f32_16x16x32_bf16 v[56:59], v[154:157], v[202:205], v[56:59]
	v_mfma_f32_16x16x32_bf16 v[44:47], v[146:149], v[210:213], v[44:47]
	v_mfma_f32_16x16x32_bf16 v[40:43], v[154:157], v[210:213], v[40:43]
	v_mfma_f32_16x16x32_bf16 v[28:31], v[146:149], v[218:221], v[28:31]
	v_mfma_f32_16x16x32_bf16 v[24:27], v[154:157], v[218:221], v[24:27]
	v_mfma_f32_16x16x32_bf16 v[12:15], v[146:149], v[226:229], v[12:15]
	v_mfma_f32_16x16x32_bf16 v[8:11], v[154:157], v[226:229], v[8:11]
	s_setprio 0
	s_setprio 1
	v_mfma_f32_16x16x32_bf16 v[52:55], v[174:177], v[190:193], v[52:55]
	v_mfma_f32_16x16x32_bf16 v[48:51], v[182:185], v[190:193], v[48:51]
	v_mfma_f32_16x16x32_bf16 v[36:39], v[174:177], v[206:209], v[36:39]
	v_mfma_f32_16x16x32_bf16 v[32:35], v[182:185], v[206:209], v[32:35]
	v_mfma_f32_16x16x32_bf16 v[20:23], v[174:177], v[214:217], v[20:23]
	v_mfma_f32_16x16x32_bf16 v[16:19], v[182:185], v[214:217], v[16:19]
	v_mfma_f32_16x16x32_bf16 v[4:7], v[174:177], v[222:225], v[4:7]
	v_mfma_f32_16x16x32_bf16 v[0:3], v[182:185], v[222:225], v[0:3]
	v_mfma_f32_16x16x32_bf16 v[52:55], v[178:181], v[202:205], v[52:55]
	v_mfma_f32_16x16x32_bf16 v[48:51], v[186:189], v[202:205], v[48:51]
	v_mfma_f32_16x16x32_bf16 v[36:39], v[178:181], v[210:213], v[36:39]
	v_mfma_f32_16x16x32_bf16 v[32:35], v[186:189], v[210:213], v[32:35]
	v_mfma_f32_16x16x32_bf16 v[20:23], v[178:181], v[218:221], v[20:23]
	v_mfma_f32_16x16x32_bf16 v[16:19], v[186:189], v[218:221], v[16:19]
	v_mfma_f32_16x16x32_bf16 v[4:7], v[178:181], v[226:229], v[4:7]
	v_mfma_f32_16x16x32_bf16 v[0:3], v[186:189], v[226:229], v[0:3]
	s_setprio 0
	s_barrier
	s_add_u32 s16, s16, 0x100
	s_addc_u32 s17, s17, 0
	s_add_u32 s42, s42, 0x100
	s_addc_u32 s43, s43, 0
	s_cmp_ge_i32 s44, s23
	s_mov_b32 s18, s44
	s_cbranch_scc0 .LBB0_303
	s_and_b64 vcc, exec, s[4:5]
	s_cbranch_vccz .LBB0_306

; #define PG8_STAGE(bufoff, gbase, voff) do { _Pragma("unroll") for (int _i = 0; _i < 2; ++_i) \
;         __builtin_amdgcn_global_load_lds((const unsigned*)((const char*)(gbase) + (voff)[_i]), (LAS unsigned*)(lds + (bufoff) + ldsw + _i * 8192), 16, 0, 0); } while (0)
; #define PG8_WAIT_V(n) asm volatile("s_waitcnt vmcnt(" #n ")" ::: "memory")
; #define PG8_BAR __builtin_amdgcn_s_barrier()
; template <class Epi, int GM, int GN, int GK, int LDA, int AMOD, int ASTRIDE, int WG = WGM>
; __device__ __forceinline__ void gemm_phase(LAS unsigned char* lds, const Gemm g, const Epi& E, int wv_) {
;     ...
;     for (int i = 0; i < 2; ++i) { int R, C; stage_rc(tid * 16 + i * 8192, R, C); const int Rb = Epi::PERM ? ((R & ~31) + perm32(R & 31)) : R;
;         voffA[i] = (unsigned)(R * lda + C) * 2u; voffB[i] = (unsigned)(Rb * K + C) * 2u; }
;     const size_t kstep = (size_t)(BK * 2);
;     const size_t hstepA = (size_t)HALF * lda * 2, tstepA = 2 * hstepA;
;     const size_t hstepB = (size_t)HALF * K * 2, tstepB = 2 * hstepB;
;     const unsigned ldsw = (unsigned)wid * 1024u;
;     const int aoff = lds_byte(wr * 64 + fr, fq * 8), boff = lds_byte(wc * 32 + fr, fq * 8);
;     ...
;     PG8_STAGE(PG8_SB(0, 0), cB, voffB); PG8_STAGE(PG8_SB(0, 1), cB + hstepB, voffB); PG8_STAGE(PG8_SA(0, 0), cA, voffA); PG8_STAGE(PG8_SA(0, 1), cA + hstepA, voffA);
;     if (wr == 1) PG8_BAR;
;     PG8_WAIT_V(2); PG8_BAR;
;     PG8_STAGE(PG8_SB(1, 0), cB + kstep, voffB); PG8_STAGE(PG8_SA(1, 0), cA + kstep, voffA); PG8_STAGE(PG8_SB(1, 1), cB + hstepB + kstep, voffB);
;     PG8_WAIT_V(6); PG8_BAR;
.LBB0_320:
	s_lshl_b32 s24, s0, 6
	s_lshl_b32 s2, s0, 13
	s_lshl_b32 s0, s1, 5
	s_and_b32 s25, s0, 0x60
	s_add_i32 m0, s9, 0x18000
	v_lshl_add_u64 v[6:7], v[6:7], 0, s[70:71]
	s_lshl_b32 s3, s25, 7
	s_waitcnt vmcnt(2)
	s_barrier
	global_load_lds_dwordx4 v[6:7], off
	v_lshl_add_u64 v[4:5], v[4:5], 0, s[70:71]
	s_add_i32 m0, s9, 0x1a000
	s_add_i32 s26, s9, 0x8000
	s_add_i32 s27, s9, 0xa000
	global_load_lds_dwordx4 v[4:5], off
	v_lshl_add_u64 v[0:1], v[0:1], 0, s[70:71]
	s_mov_b32 m0, s26
	s_add_u32 s0, s12, 0x8080
	global_load_lds_dwordx4 v[0:1], off
	v_lshl_add_u64 v[0:1], v[2:3], 0, s[70:71]
	s_mov_b32 m0, s27
	s_addc_u32 s1, s13, 0
	global_load_lds_dwordx4 v[0:1], off
	s_add_i32 m0, s9, 0x1c000
	s_nop 0
	global_load_lds_dwordx4 v160, s[0:1]
	v_lshl_add_u64 v[0:1], s[0:1], 0, v[174:175]
	s_add_i32 m0, s9, 0x1e000
	v_bfe_u32 v187, v8, 4, 2
	global_load_lds_dwordx4 v174, s[0:1]
	v_and_b32_e32 v186, 15, v8
	v_lshlrev_b32_e32 v0, 4, v187
	v_lshlrev_b32_e32 v1, 2, v8
	v_lshl_or_b32 v0, v186, 6, v0
	v_and_b32_e32 v1, 32, v1
	v_bitop3_b32 v2, v0, s2, v1 bitop3:0xde
	v_bitop3_b32 v188, s3, v0, v1 bitop3:0xf6
	v_lshlrev_b32_e32 v0, 15, v9
	v_and_b32_e32 v0, 0xffff0000, v0
	v_lshl_add_u32 v0, v10, 12, v0
	v_and_b32_e32 v1, 1, v9
	v_lshl_or_b32 v0, v1, 6, v0
	v_lshl_add_u32 v176, v11, 1, v0
	v_lshlrev_b32_e32 v0, 15, v12
	s_cmp_gt_i32 s19, 0
	v_and_b32_e32 v0, 0xffff0000, v0
	s_waitcnt vmcnt(6)
	s_cselect_b64 s[46:47], -1, 0
	s_add_i32 s29, s19, -2
	v_lshl_add_u32 v0, v13, 12, v0
	v_and_b32_e32 v1, 1, v12
	s_cmpk_lt_u32 s4, 0x100
	v_lshl_or_b32 v0, v1, 6, v0
	s_mov_b32 s28, 0
	s_cselect_b64 s[2:3], -1, 0
	v_mov_b32_e32 v177, v161
	v_lshl_add_u32 v178, v14, 1, v0
	v_mov_b32_e32 v179, v161
	v_add_u32_e32 v189, 0, v2
	s_barrier
	s_branch .LBB0_323

; #define PG8_STAGE(bufoff, gbase, voff) do { _Pragma("unroll") for (int _i = 0; _i < 2; ++_i) \
;         __builtin_amdgcn_global_load_lds((const unsigned*)((const char*)(gbase) + (voff)[_i]), (LAS unsigned*)(lds + (bufoff) + ldsw + _i * 8192), 16, 0, 0); } while (0)
; #define PG8_LDA(dst, b, h) do { _Pragma("unroll") for (int m = 0; m < 4; ++m) _Pragma("unroll") for (int k = 0; k < 2; ++k) dst[m][k] = *(const LAS bf16x8*)(lds + PG8_SA(b, h) + aoff + m * 2048 + k * 1024); } while (0)
; #define PG8_LDB(dst, b, h) do { _Pragma("unroll") for (int n = 0; n < 2; ++n) _Pragma("unroll") for (int k = 0; k < 2; ++k) dst[n][k] = *(const LAS bf16x8*)(lds + PG8_SB(b, h) + boff + n * 2048 + k * 1024); } while (0)
; #define PG8_MMA(ai, bj, At, Bt) do { __builtin_amdgcn_s_setprio(1); _Pragma("unroll") for (int m = 0; m < 4; ++m) _Pragma("unroll") for (int n = 0; n < 2; ++n) _Pragma("unroll") for (int k = 0; k < 2; ++k) \
;         acc[ai][bj][m][n] = __builtin_amdgcn_mfma_f32_16x16x32_bf16(Bt[n][k], At[m][k], acc[ai][bj][m][n], 0, 0, 0); __builtin_amdgcn_s_setprio(0); } while (0)
; #define PG8_WAIT_V(n) asm volatile("s_waitcnt vmcnt(" #n ")" ::: "memory")
; #define PG8_WAIT_L(n) asm volatile("s_waitcnt lgkmcnt(" #n ")" ::: "memory")
; #define PG8_BAR __builtin_amdgcn_s_barrier()
; #define PG8_SCHED __builtin_amdgcn_sched_barrier(0)
; template <class Epi, int GM, int GN, int GK, int LDA, int AMOD, int ASTRIDE, int WG = WGM>
; __device__ __forceinline__ void gemm_phase(LAS unsigned char* lds, const Gemm g, const Epi& E, int wv_) {
;     ...
;             PG8_LDB(B0, 0, 0); PG8_LDB(B1, 0, 1); PG8_SCHED; PG8_LDA(At, 0, 0); PG8_STAGE(PG8_SA(1, 1), a1 + hstepA, voffA);
;             PG8_WAIT_V(8); PG8_WAIT_L(0); PG8_BAR; PG8_MMA(0, 0, At, B0); PG8_MMA(0, 1, At, B1); PG8_BAR; PG8_SCHED;
;             PG8_LDA(At, 0, 1); PG8_STAGE(PG8_SB(0, 0), b2, voffB); PG8_STAGE(PG8_SB(0, 1), b2 + hstepB, voffB); PG8_STAGE(PG8_SA(0, 0), a2, voffA);
;             PG8_WAIT_V(8); PG8_WAIT_L(0); PG8_BAR; PG8_MMA(1, 0, At, B0); PG8_MMA(1, 1, At, B1); PG8_BAR; PG8_SCHED;
.LBB0_333:
	s_add_i32 s31, s12, 2
	s_add_u32 s13, s0, 0xfff80080
	s_addc_u32 s14, s1, -1
	s_add_i32 s34, 0, 0x10000
	s_cmp_eq_u32 s29, s12
	s_cselect_b32 s15, s55, s14
	s_cselect_b32 s14, s54, s13
	s_cselect_b32 s13, s5, s30
	s_cselect_b32 s12, s16, s17
	s_add_i32 s36, 0, 0x14000
	v_add_u32_e32 v56, s34, v188
	v_add_u32_e32 v168, s36, v188
	ds_read_b128 v[32:35], v56
	ds_read_b128 v[40:43], v56 offset:1024
	ds_read_b128 v[48:51], v56 offset:2048
	ds_read_b128 v[56:59], v56 offset:3072
	ds_read_b128 v[64:67], v168
	ds_read_b128 v[68:71], v168 offset:1024
	ds_read_b128 v[152:155], v168 offset:2048
	ds_read_b128 v[180:183], v168 offset:3072
	s_add_i32 m0, s9, 0xc000
	ds_read_b128 v[190:193], v189
	ds_read_b128 v[202:205], v189 offset:1024
	ds_read_b128 v[206:209], v189 offset:2048
	ds_read_b128 v[210:213], v189 offset:3072
	ds_read_b128 v[214:217], v189 offset:4096
	ds_read_b128 v[218:221], v189 offset:5120
	ds_read_b128 v[222:225], v189 offset:6144
	ds_read_b128 v[226:229], v189 offset:7168
	global_load_lds_dwordx4 v176, s[0:1]
	s_add_i32 m0, s9, 0xe000
	s_nop 0
	global_load_lds_dwordx4 v178, s[0:1]
	s_waitcnt vmcnt(8)
	s_waitcnt lgkmcnt(0)
	s_barrier
	s_setprio 1
	s_waitcnt lgkmcnt(0)
	v_mfma_f32_16x16x32_bf16 v[148:151], v[32:35], v[190:193], v[148:151]
	v_mfma_f32_16x16x32_bf16 v[144:147], v[48:51], v[190:193], v[144:147]
	v_mfma_f32_16x16x32_bf16 v[132:135], v[32:35], v[206:209], v[132:135]
	v_mfma_f32_16x16x32_bf16 v[128:131], v[48:51], v[206:209], v[128:131]
	v_mfma_f32_16x16x32_bf16 v[116:119], v[32:35], v[214:217], v[116:119]
	v_mfma_f32_16x16x32_bf16 v[112:115], v[48:51], v[214:217], v[112:115]
	v_mfma_f32_16x16x32_bf16 v[100:103], v[32:35], v[222:225], v[100:103]
	v_mfma_f32_16x16x32_bf16 v[96:99], v[48:51], v[222:225], v[96:99]
	v_mfma_f32_16x16x32_bf16 v[148:151], v[40:43], v[202:205], v[148:151]
	v_mfma_f32_16x16x32_bf16 v[144:147], v[56:59], v[202:205], v[144:147]
	v_mfma_f32_16x16x32_bf16 v[132:135], v[40:43], v[210:213], v[132:135]
	v_mfma_f32_16x16x32_bf16 v[128:131], v[56:59], v[210:213], v[128:131]
	v_mfma_f32_16x16x32_bf16 v[116:119], v[40:43], v[218:221], v[116:119]
	v_mfma_f32_16x16x32_bf16 v[112:115], v[56:59], v[218:221], v[112:115]
	v_mfma_f32_16x16x32_bf16 v[100:103], v[40:43], v[226:229], v[100:103]
	v_mfma_f32_16x16x32_bf16 v[96:99], v[56:59], v[226:229], v[96:99]
	s_setprio 0
	s_setprio 1
	v_mfma_f32_16x16x32_bf16 v[136:139], v[64:67], v[190:193], v[136:139]
	v_mfma_f32_16x16x32_bf16 v[140:143], v[152:155], v[190:193], v[140:143]
	v_mfma_f32_16x16x32_bf16 v[120:123], v[64:67], v[206:209], v[120:123]
	v_mfma_f32_16x16x32_bf16 v[124:127], v[152:155], v[206:209], v[124:127]
	v_mfma_f32_16x16x32_bf16 v[104:107], v[64:67], v[214:217], v[104:107]
	v_mfma_f32_16x16x32_bf16 v[108:111], v[152:155], v[214:217], v[108:111]
	v_mfma_f32_16x16x32_bf16 v[88:91], v[64:67], v[222:225], v[88:91]
	v_mfma_f32_16x16x32_bf16 v[92:95], v[152:155], v[222:225], v[92:95]
	v_mfma_f32_16x16x32_bf16 v[136:139], v[68:71], v[202:205], v[136:139]
	v_mfma_f32_16x16x32_bf16 v[140:143], v[180:183], v[202:205], v[140:143]
	v_mfma_f32_16x16x32_bf16 v[120:123], v[68:71], v[210:213], v[120:123]
	v_mfma_f32_16x16x32_bf16 v[124:127], v[180:183], v[210:213], v[124:127]
	v_mfma_f32_16x16x32_bf16 v[104:107], v[68:71], v[218:221], v[104:107]
	v_mfma_f32_16x16x32_bf16 v[108:111], v[180:183], v[218:221], v[108:111]
	v_mfma_f32_16x16x32_bf16 v[88:91], v[68:71], v[226:229], v[88:91]
	v_mfma_f32_16x16x32_bf16 v[92:95], v[180:183], v[226:229], v[92:95]
	s_setprio 0
	s_barrier
	s_add_i32 s34, s34, s21
	v_lshl_add_u64 v[168:169], s[12:13], 0, v[160:161]
	s_mov_b32 m0, s34
	ds_read_b128 v[190:193], v189 offset:16384
	ds_read_b128 v[202:205], v189 offset:17408
	ds_read_b128 v[206:209], v189 offset:18432
	ds_read_b128 v[210:213], v189 offset:19456
	ds_read_b128 v[214:217], v189 offset:20480
	ds_read_b128 v[218:221], v189 offset:21504
	ds_read_b128 v[222:225], v189 offset:22528
	ds_read_b128 v[226:229], v189 offset:23552
	global_load_lds_dwordx4 v160, s[12:13]
	s_add_i32 m0, s34, 0x2000
	s_add_u32 s34, s12, 0x8000
	v_lshl_add_u64 v[170:171], s[12:13], 0, v[174:175]
	s_addc_u32 s35, s13, 0
	s_add_i32 s36, s36, s21
	global_load_lds_dwordx4 v174, s[12:13]
	s_mov_b32 m0, s36
	v_lshl_add_u64 v[196:197], s[14:15], 0, v[158:159]
	global_load_lds_dwordx4 v160, s[34:35]
	s_add_i32 m0, s36, 0x2000
	s_nop 0
	global_load_lds_dwordx4 v174, s[34:35]
	v_lshl_add_u64 v[184:185], s[14:15], 0, v[156:157]
	s_mov_b32 m0, s9
	s_nop 0
	global_load_lds_dwordx4 v156, s[14:15]
	s_mov_b32 m0, s11
	s_nop 0
	global_load_lds_dwordx4 v158, s[14:15]
	s_waitcnt vmcnt(8)
	s_waitcnt lgkmcnt(0)
	s_barrier
; #define PG8_STAGE(bufoff, gbase, voff) do { _Pragma("unroll") for (int _i = 0; _i < 2; ++_i) \
;         __builtin_amdgcn_global_load_lds((const unsigned*)((const char*)(gbase) + (voff)[_i]), (LAS unsigned*)(lds + (bufoff) + ldsw + _i * 8192), 16, 0, 0); } while (0)
; #define PG8_LDA(dst, b, h) do { _Pragma("unroll") for (int m = 0; m < 4; ++m) _Pragma("unroll") for (int k = 0; k < 2; ++k) dst[m][k] = *(const LAS bf16x8*)(lds + PG8_SA(b, h) + aoff + m * 2048 + k * 1024); } while (0)
; #define PG8_LDB(dst, b, h) do { _Pragma("unroll") for (int n = 0; n < 2; ++n) _Pragma("unroll") for (int k = 0; k < 2; ++k) dst[n][k] = *(const LAS bf16x8*)(lds + PG8_SB(b, h) + boff + n * 2048 + k * 1024); } while (0)
; #define PG8_MMA(ai, bj, At, Bt) do { __builtin_amdgcn_s_setprio(1); _Pragma("unroll") for (int m = 0; m < 4; ++m) _Pragma("unroll") for (int n = 0; n < 2; ++n) _Pragma("unroll") for (int k = 0; k < 2; ++k) \
;         acc[ai][bj][m][n] = __builtin_amdgcn_mfma_f32_16x16x32_bf16(Bt[n][k], At[m][k], acc[ai][bj][m][n], 0, 0, 0); __builtin_amdgcn_s_setprio(0); } while (0)
; #define PG8_WAIT_V(n) asm volatile("s_waitcnt vmcnt(" #n ")" ::: "memory")
; #define PG8_WAIT_L(n) asm volatile("s_waitcnt lgkmcnt(" #n ")" ::: "memory")
; #define PG8_BAR __builtin_amdgcn_s_barrier()
; #define PG8_SCHED __builtin_amdgcn_sched_barrier(0)
; template <class Epi, int GM, int GN, int GK, int LDA, int AMOD, int ASTRIDE, int WG = WGM>
; __device__ __forceinline__ void gemm_phase(LAS unsigned char* lds, const Gemm g, const Epi& E, int wv_) {
;     ...
;             PG8_WAIT_V(8); PG8_WAIT_L(0); PG8_BAR; PG8_MMA(1, 0, At, B0); PG8_MMA(1, 1, At, B1); PG8_BAR; PG8_SCHED;
;             PG8_LDB(B0, 1, 0); PG8_LDB(B1, 1, 1); PG8_SCHED; PG8_LDA(At, 1, 0); PG8_STAGE(PG8_SA(0, 1), a2 + hstepA, voffA);
;             PG8_WAIT_V(8); PG8_WAIT_L(0); PG8_BAR; PG8_MMA(0, 0, At, B0); PG8_MMA(0, 1, At, B1); PG8_BAR; PG8_SCHED;
	s_setprio 1
	s_waitcnt lgkmcnt(0)
	v_mfma_f32_16x16x32_bf16 v[84:87], v[32:35], v[190:193], v[84:87]
	v_mfma_f32_16x16x32_bf16 v[80:83], v[48:51], v[190:193], v[80:83]
	v_mfma_f32_16x16x32_bf16 v[60:63], v[32:35], v[206:209], v[60:63]
	v_mfma_f32_16x16x32_bf16 v[52:55], v[48:51], v[206:209], v[52:55]
	v_mfma_f32_16x16x32_bf16 v[28:31], v[32:35], v[214:217], v[28:31]
	v_mfma_f32_16x16x32_bf16 v[24:27], v[48:51], v[214:217], v[24:27]
	v_mfma_f32_16x16x32_bf16 v[12:15], v[32:35], v[222:225], v[12:15]
	v_mfma_f32_16x16x32_bf16 v[8:11], v[48:51], v[222:225], v[8:11]
	v_mfma_f32_16x16x32_bf16 v[84:87], v[40:43], v[202:205], v[84:87]
	v_mfma_f32_16x16x32_bf16 v[80:83], v[56:59], v[202:205], v[80:83]
	v_mfma_f32_16x16x32_bf16 v[60:63], v[40:43], v[210:213], v[60:63]
	v_mfma_f32_16x16x32_bf16 v[52:55], v[56:59], v[210:213], v[52:55]
	v_mfma_f32_16x16x32_bf16 v[28:31], v[40:43], v[218:221], v[28:31]
	v_mfma_f32_16x16x32_bf16 v[24:27], v[56:59], v[218:221], v[24:27]
	v_mfma_f32_16x16x32_bf16 v[12:15], v[40:43], v[226:229], v[12:15]
	v_mfma_f32_16x16x32_bf16 v[8:11], v[56:59], v[226:229], v[8:11]
	s_setprio 0
	s_setprio 1
	v_mfma_f32_16x16x32_bf16 v[36:39], v[64:67], v[206:209], v[36:39]
	v_mfma_f32_16x16x32_bf16 v[44:47], v[152:155], v[206:209], v[44:47]
	v_mfma_f32_16x16x32_bf16 v[16:19], v[64:67], v[214:217], v[16:19]
	v_mfma_f32_16x16x32_bf16 v[20:23], v[152:155], v[214:217], v[20:23]
	v_mfma_f32_16x16x32_bf16 v[0:3], v[64:67], v[222:225], v[0:3]
	v_mfma_f32_16x16x32_bf16 v[4:7], v[152:155], v[222:225], v[4:7]
	v_mfma_f32_16x16x32_bf16 v[32:35], v[64:67], v[190:193], v[72:75]
	v_mfma_f32_16x16x32_bf16 v[40:43], v[152:155], v[190:193], v[76:79]
	v_mfma_f32_16x16x32_bf16 v[36:39], v[68:71], v[210:213], v[36:39]
	v_mfma_f32_16x16x32_bf16 v[44:47], v[180:183], v[210:213], v[44:47]
	v_mfma_f32_16x16x32_bf16 v[16:19], v[68:71], v[218:221], v[16:19]
	v_mfma_f32_16x16x32_bf16 v[20:23], v[180:183], v[218:221], v[20:23]
	v_mfma_f32_16x16x32_bf16 v[0:3], v[68:71], v[226:229], v[0:3]
	v_mfma_f32_16x16x32_bf16 v[4:7], v[180:183], v[226:229], v[4:7]
	v_mfma_f32_16x16x32_bf16 v[32:35], v[68:71], v[202:205], v[32:35]
	v_mfma_f32_16x16x32_bf16 v[40:43], v[180:183], v[202:205], v[40:43]
	s_setprio 0
	s_barrier
	s_add_i32 s34, 0, 0x18000
	s_add_i32 s35, 0, 0x1c000
	v_add_u32_e32 v68, s34, v188
	v_add_u32_e32 v72, s35, v188
	ds_read_b128 v[48:51], v68
	ds_read_b128 v[56:59], v68 offset:1024
	ds_read_b128 v[64:67], v68 offset:2048
	ds_read_b128 v[68:71], v68 offset:3072
	ds_read_b128 v[152:155], v72
	ds_read_b128 v[180:183], v72 offset:1024
	ds_read_b128 v[190:193], v72 offset:2048
	ds_read_b128 v[202:205], v72 offset:3072
	s_add_u32 s14, s14, 0x80000
	s_addc_u32 s15, s15, 0
	s_mov_b32 m0, s22
	ds_read_b128 v[72:75], v189 offset:32768
	ds_read_b128 v[76:79], v189 offset:33792
	ds_read_b128 v[206:209], v189 offset:34816
	ds_read_b128 v[210:213], v189 offset:35840
	ds_read_b128 v[214:217], v189 offset:36864
	ds_read_b128 v[218:221], v189 offset:37888
	ds_read_b128 v[222:225], v189 offset:38912
	ds_read_b128 v[226:229], v189 offset:39936
	global_load_lds_dwordx4 v156, s[14:15]
	v_lshl_add_u64 v[198:199], s[14:15], 0, v[158:159]
	s_mov_b32 m0, s23
	s_nop 0
	global_load_lds_dwordx4 v158, s[14:15]
	s_waitcnt vmcnt(8)
	s_waitcnt lgkmcnt(0)
	s_barrier
	s_setprio 1
	s_waitcnt lgkmcnt(0)
	v_mfma_f32_16x16x32_bf16 v[148:151], v[48:51], v[72:75], v[148:151]
	v_mfma_f32_16x16x32_bf16 v[144:147], v[64:67], v[72:75], v[144:147]
	v_mfma_f32_16x16x32_bf16 v[132:135], v[48:51], v[206:209], v[132:135]
	v_mfma_f32_16x16x32_bf16 v[128:131], v[64:67], v[206:209], v[128:131]
	v_mfma_f32_16x16x32_bf16 v[116:119], v[48:51], v[214:217], v[116:119]
	v_mfma_f32_16x16x32_bf16 v[112:115], v[64:67], v[214:217], v[112:115]
	v_mfma_f32_16x16x32_bf16 v[100:103], v[48:51], v[222:225], v[100:103]
	v_mfma_f32_16x16x32_bf16 v[96:99], v[64:67], v[222:225], v[96:99]
	v_mfma_f32_16x16x32_bf16 v[148:151], v[56:59], v[76:79], v[148:151]
	v_mfma_f32_16x16x32_bf16 v[144:147], v[68:71], v[76:79], v[144:147]
	v_mfma_f32_16x16x32_bf16 v[132:135], v[56:59], v[210:213], v[132:135]
	v_mfma_f32_16x16x32_bf16 v[128:131], v[68:71], v[210:213], v[128:131]
	v_mfma_f32_16x16x32_bf16 v[116:119], v[56:59], v[218:221], v[116:119]
	v_mfma_f32_16x16x32_bf16 v[112:115], v[68:71], v[218:221], v[112:115]
	v_mfma_f32_16x16x32_bf16 v[100:103], v[56:59], v[226:229], v[100:103]
	v_mfma_f32_16x16x32_bf16 v[96:99], v[68:71], v[226:229], v[96:99]
	s_setprio 0
	s_setprio 1
	v_mfma_f32_16x16x32_bf16 v[136:139], v[152:155], v[72:75], v[136:139]
	v_mfma_f32_16x16x32_bf16 v[72:75], v[190:193], v[72:75], v[140:143]
	v_mfma_f32_16x16x32_bf16 v[140:143], v[202:205], v[76:79], v[72:75]
	v_mfma_f32_16x16x32_bf16 v[72:75], v[152:155], v[206:209], v[120:123]
	v_mfma_f32_16x16x32_bf16 v[120:123], v[180:183], v[210:213], v[72:75]
	v_mfma_f32_16x16x32_bf16 v[72:75], v[190:193], v[206:209], v[124:127]
	v_mfma_f32_16x16x32_bf16 v[124:127], v[202:205], v[210:213], v[72:75]
	v_mfma_f32_16x16x32_bf16 v[72:75], v[152:155], v[214:217], v[104:107]
	v_mfma_f32_16x16x32_bf16 v[104:107], v[180:183], v[218:221], v[72:75]
	v_mfma_f32_16x16x32_bf16 v[72:75], v[190:193], v[214:217], v[108:111]
	v_mfma_f32_16x16x32_bf16 v[108:111], v[202:205], v[218:221], v[72:75]
	v_mfma_f32_16x16x32_bf16 v[72:75], v[152:155], v[222:225], v[88:91]
	v_mfma_f32_16x16x32_bf16 v[88:91], v[180:183], v[226:229], v[72:75]
	v_mfma_f32_16x16x32_bf16 v[72:75], v[190:193], v[222:225], v[92:95]
	v_mfma_f32_16x16x32_bf16 v[136:139], v[180:183], v[76:79], v[136:139]
	v_mfma_f32_16x16x32_bf16 v[92:95], v[202:205], v[226:229], v[72:75]
	s_setprio 0
	s_barrier
; #define PG8_STAGE(bufoff, gbase, voff) do { _Pragma("unroll") for (int _i = 0; _i < 2; ++_i) \
;         __builtin_amdgcn_global_load_lds((const unsigned*)((const char*)(gbase) + (voff)[_i]), (LAS unsigned*)(lds + (bufoff) + ldsw + _i * 8192), 16, 0, 0); } while (0)
; #define PG8_LDA(dst, b, h) do { _Pragma("unroll") for (int m = 0; m < 4; ++m) _Pragma("unroll") for (int k = 0; k < 2; ++k) dst[m][k] = *(const LAS bf16x8*)(lds + PG8_SA(b, h) + aoff + m * 2048 + k * 1024); } while (0)
; #define PG8_MMA(ai, bj, At, Bt) do { __builtin_amdgcn_s_setprio(1); _Pragma("unroll") for (int m = 0; m < 4; ++m) _Pragma("unroll") for (int n = 0; n < 2; ++n) _Pragma("unroll") for (int k = 0; k < 2; ++k) \
;         acc[ai][bj][m][n] = __builtin_amdgcn_mfma_f32_16x16x32_bf16(Bt[n][k], At[m][k], acc[ai][bj][m][n], 0, 0, 0); __builtin_amdgcn_s_setprio(0); } while (0)
; #define PG8_WAIT_V(n) asm volatile("s_waitcnt vmcnt(" #n ")" ::: "memory")
; #define PG8_WAIT_L(n) asm volatile("s_waitcnt lgkmcnt(" #n ")" ::: "memory")
; #define PG8_BAR __builtin_amdgcn_s_barrier()
; #define PG8_SCHED __builtin_amdgcn_sched_barrier(0)
; template <class Epi, int GM, int GN, int GK, int LDA, int AMOD, int ASTRIDE, int WG = WGM>
; __device__ __forceinline__ void gemm_phase(LAS unsigned char* lds, const Gemm g, const Epi& E, int wv_) {
;     ...
;             PG8_LDA(At, 1, 1); PG8_STAGE(PG8_SB(1, 0), b3, voffB); PG8_STAGE(PG8_SB(1, 1), b3 + hstepB, voffB); PG8_STAGE(PG8_SA(1, 0), a3, voffA);
;             PG8_WAIT_V(8); PG8_WAIT_L(0); PG8_BAR; PG8_MMA(1, 0, At, B0); PG8_MMA(1, 1, At, B1); PG8_BAR; PG8_SCHED;
;         }
	s_add_i32 s14, s34, s21
	s_nop 2
	v_lshl_add_u64 v[72:73], v[168:169], 0, s[70:71]
	s_mov_b32 m0, s14
	ds_read_b128 v[76:79], v189 offset:49152
	ds_read_b128 v[206:209], v189 offset:50176
	ds_read_b128 v[210:213], v189 offset:51200
	ds_read_b128 v[214:217], v189 offset:52224
	ds_read_b128 v[218:221], v189 offset:53248
	ds_read_b128 v[222:225], v189 offset:54272
	ds_read_b128 v[226:229], v189 offset:55296
	ds_read_b128 v[230:233], v189 offset:56320
	global_load_lds_dwordx4 v[72:73], off
	s_add_i32 m0, s14, 0x2000
	s_add_u32 s12, s12, 0x8080
	v_lshl_add_u64 v[72:73], v[170:171], 0, s[70:71]
	s_addc_u32 s13, s13, 0
	s_add_i32 s14, s35, s21
	global_load_lds_dwordx4 v[72:73], off
	s_mov_b32 m0, s14
	s_nop 0
	global_load_lds_dwordx4 v160, s[12:13]
	s_add_i32 m0, s14, 0x2000
	s_nop 0
	global_load_lds_dwordx4 v174, s[12:13]
	v_lshl_add_u64 v[72:73], v[184:185], 0, s[70:71]
	s_mov_b32 m0, s26
	s_nop 0
	global_load_lds_dwordx4 v[72:73], off
	v_lshl_add_u64 v[72:73], v[196:197], 0, s[70:71]
	s_mov_b32 m0, s27
	s_nop 0
	global_load_lds_dwordx4 v[72:73], off
	s_waitcnt vmcnt(8)
	s_waitcnt lgkmcnt(0)
	s_barrier
	s_setprio 1
	s_waitcnt lgkmcnt(0)
	v_mfma_f32_16x16x32_bf16 v[72:75], v[48:51], v[76:79], v[84:87]
	v_mfma_f32_16x16x32_bf16 v[84:87], v[56:59], v[206:209], v[72:75]
	v_mfma_f32_16x16x32_bf16 v[72:75], v[64:67], v[76:79], v[80:83]
	v_mfma_f32_16x16x32_bf16 v[60:63], v[48:51], v[210:213], v[60:63]
	v_mfma_f32_16x16x32_bf16 v[52:55], v[64:67], v[210:213], v[52:55]
	v_mfma_f32_16x16x32_bf16 v[28:31], v[48:51], v[218:221], v[28:31]
	v_mfma_f32_16x16x32_bf16 v[24:27], v[64:67], v[218:221], v[24:27]
	v_mfma_f32_16x16x32_bf16 v[12:15], v[48:51], v[226:229], v[12:15]
	v_mfma_f32_16x16x32_bf16 v[8:11], v[64:67], v[226:229], v[8:11]
	v_mfma_f32_16x16x32_bf16 v[80:83], v[68:71], v[206:209], v[72:75]
	v_mfma_f32_16x16x32_bf16 v[60:63], v[56:59], v[214:217], v[60:63]
	v_mfma_f32_16x16x32_bf16 v[52:55], v[68:71], v[214:217], v[52:55]
	v_mfma_f32_16x16x32_bf16 v[28:31], v[56:59], v[222:225], v[28:31]
	v_mfma_f32_16x16x32_bf16 v[24:27], v[68:71], v[222:225], v[24:27]
	v_mfma_f32_16x16x32_bf16 v[12:15], v[56:59], v[230:233], v[12:15]
	v_mfma_f32_16x16x32_bf16 v[8:11], v[68:71], v[230:233], v[8:11]
	s_setprio 0
	s_setprio 1
	v_mfma_f32_16x16x32_bf16 v[32:35], v[152:155], v[76:79], v[32:35]
	v_mfma_f32_16x16x32_bf16 v[72:75], v[180:183], v[206:209], v[32:35]
	v_mfma_f32_16x16x32_bf16 v[32:35], v[190:193], v[76:79], v[40:43]
	v_mfma_f32_16x16x32_bf16 v[76:79], v[202:205], v[206:209], v[32:35]
	v_mfma_f32_16x16x32_bf16 v[32:35], v[152:155], v[210:213], v[36:39]
	v_mfma_f32_16x16x32_bf16 v[36:39], v[180:183], v[214:217], v[32:35]
	v_mfma_f32_16x16x32_bf16 v[32:35], v[190:193], v[210:213], v[44:47]
	v_mfma_f32_16x16x32_bf16 v[16:19], v[152:155], v[218:221], v[16:19]
	v_mfma_f32_16x16x32_bf16 v[20:23], v[190:193], v[218:221], v[20:23]
	v_mfma_f32_16x16x32_bf16 v[0:3], v[152:155], v[226:229], v[0:3]
	v_mfma_f32_16x16x32_bf16 v[4:7], v[190:193], v[226:229], v[4:7]
	v_mfma_f32_16x16x32_bf16 v[44:47], v[202:205], v[214:217], v[32:35]
	v_mfma_f32_16x16x32_bf16 v[16:19], v[180:183], v[222:225], v[16:19]
	v_mfma_f32_16x16x32_bf16 v[20:23], v[202:205], v[222:225], v[20:23]
	v_mfma_f32_16x16x32_bf16 v[0:3], v[180:183], v[230:233], v[0:3]
	v_mfma_f32_16x16x32_bf16 v[4:7], v[202:205], v[230:233], v[4:7]
	s_setprio 0
	s_barrier
	s_add_u32 s0, s0, 0x100
	s_addc_u32 s1, s1, 0
	s_add_u32 s17, s17, 0x100
	s_addc_u32 s30, s30, 0
	s_cmp_ge_i32 s31, s19
	s_mov_b32 s12, s31
	s_cbranch_scc0 .LBB0_333
	s_and_b64 vcc, exec, s[2:3]
	s_cbranch_vccz .LBB0_336

; #define PG8_STAGE(bufoff, gbase, voff) do { _Pragma("unroll") for (int _i = 0; _i < 2; ++_i) \
;         __builtin_amdgcn_global_load_lds((const unsigned*)((const char*)(gbase) + (voff)[_i]), (LAS unsigned*)(lds + (bufoff) + ldsw + _i * 8192), 16, 0, 0); } while (0)
; #define PG8_WAIT_V(n) asm volatile("s_waitcnt vmcnt(" #n ")" ::: "memory")
; #define PG8_BAR __builtin_amdgcn_s_barrier()
; template <class Epi, int GM, int GN, int GK, int LDA, int AMOD, int ASTRIDE, int WG = WGM>
; __device__ __forceinline__ void gemm_phase(LAS unsigned char* lds, const Gemm g, const Epi& E, int wv_) {
;     ...
;     for (int i = 0; i < 2; ++i) { int R, C; stage_rc(tid * 16 + i * 8192, R, C); const int Rb = Epi::PERM ? ((R & ~31) + perm32(R & 31)) : R;
;         voffA[i] = (unsigned)(R * lda + C) * 2u; voffB[i] = (unsigned)(Rb * K + C) * 2u; }
;     const size_t kstep = (size_t)(BK * 2);
;     const size_t hstepA = (size_t)HALF * lda * 2, tstepA = 2 * hstepA;
;     const size_t hstepB = (size_t)HALF * K * 2, tstepB = 2 * hstepB;
;     const unsigned ldsw = (unsigned)wid * 1024u;
;     const int aoff = lds_byte(wr * 64 + fr, fq * 8), boff = lds_byte(wc * 32 + fr, fq * 8);
;     ...
;     PG8_STAGE(PG8_SB(0, 0), cB, voffB); PG8_STAGE(PG8_SB(0, 1), cB + hstepB, voffB); PG8_STAGE(PG8_SA(0, 0), cA, voffA); PG8_STAGE(PG8_SA(0, 1), cA + hstepA, voffA);
;     if (wr == 1) PG8_BAR;
;     PG8_WAIT_V(2); PG8_BAR;
;     PG8_STAGE(PG8_SB(1, 0), cB + kstep, voffB); PG8_STAGE(PG8_SA(1, 0), cA + kstep, voffA); PG8_STAGE(PG8_SB(1, 1), cB + hstepB + kstep, voffB);
;     PG8_WAIT_V(6); PG8_BAR;
.LBB0_500:
	s_lshl_b32 s3, s3, 5
	s_and_b32 s35, s3, 0x60
	s_add_i32 m0, s28, 0x18000
	v_lshl_add_u64 v[6:7], v[6:7], 0, s[70:71]
	s_lshl_b32 s34, s5, 6
	s_lshl_b32 s5, s5, 13
	s_lshl_b32 s3, s35, 7
	s_waitcnt vmcnt(2)
	s_barrier
	global_load_lds_dwordx4 v[6:7], off
	v_lshl_add_u64 v[4:5], v[4:5], 0, s[70:71]
	s_add_i32 m0, s28, 0x1a000
	s_add_i32 s36, s28, 0x8000
	s_add_i32 s37, s28, 0xa000
	global_load_lds_dwordx4 v[4:5], off
	v_lshl_add_u64 v[0:1], v[0:1], 0, s[70:71]
	s_mov_b32 m0, s36
	s_add_u32 s6, s18, 0x80080
	global_load_lds_dwordx4 v[0:1], off
	v_lshl_add_u64 v[0:1], v[2:3], 0, s[70:71]
	s_mov_b32 m0, s37
	s_addc_u32 s7, s19, 0
	global_load_lds_dwordx4 v[0:1], off
	s_add_i32 m0, s28, 0x1c000
	s_nop 0
	global_load_lds_dwordx4 v160, s[6:7]
	v_lshl_add_u64 v[0:1], s[6:7], 0, v[128:129]
	s_add_i32 m0, s28, 0x1e000
	v_bfe_u32 v139, v8, 4, 2
	global_load_lds_dwordx4 v128, s[6:7]
	v_and_b32_e32 v138, 15, v8
	v_lshlrev_b32_e32 v0, 4, v139
	v_lshlrev_b32_e32 v1, 2, v8
	v_lshl_or_b32 v0, v138, 6, v0
	v_and_b32_e32 v1, 32, v1
	v_bitop3_b32 v2, v0, s5, v1 bitop3:0xde
	v_bitop3_b32 v140, s3, v0, v1 bitop3:0xf6
	v_lshlrev_b32_e32 v0, 15, v13
	v_and_b32_e32 v0, 0xffff0000, v0
	v_lshl_add_u32 v0, v12, 12, v0
	v_and_b32_e32 v1, 1, v13
	v_lshl_or_b32 v0, v1, 6, v0
	v_lshl_add_u32 v134, v14, 1, v0
	v_lshlrev_b32_e32 v0, 15, v9
	s_cmp_gt_i32 s23, 0
	v_and_b32_e32 v0, 0xffff0000, v0
	s_sext_i32_i16 s11, s2
	s_waitcnt vmcnt(6)
	s_cselect_b64 s[2:3], -1, 0
	s_add_i32 s41, s23, -2
	v_lshl_add_u32 v0, v10, 12, v0
	v_and_b32_e32 v1, 1, v9
	s_cmpk_lt_u32 s4, 0x100
	v_lshl_or_b32 v0, v1, 6, v0
	s_mov_b32 s40, 0
	s_cselect_b64 s[4:5], -1, 0
	v_mov_b32_e32 v135, v161
	v_lshl_add_u32 v136, v11, 1, v0
	v_mov_b32_e32 v137, v161
	v_add_u32_e32 v141, 0, v2
	s_barrier
	s_waitcnt vmcnt(0)
	s_branch .LBB0_503

; #define PG8_STAGE(bufoff, gbase, voff) do { _Pragma("unroll") for (int _i = 0; _i < 2; ++_i) \
;         __builtin_amdgcn_global_load_lds((const unsigned*)((const char*)(gbase) + (voff)[_i]), (LAS unsigned*)(lds + (bufoff) + ldsw + _i * 8192), 16, 0, 0); } while (0)
; #define PG8_LDA(dst, b, h) do { _Pragma("unroll") for (int m = 0; m < 4; ++m) _Pragma("unroll") for (int k = 0; k < 2; ++k) dst[m][k] = *(const LAS bf16x8*)(lds + PG8_SA(b, h) + aoff + m * 2048 + k * 1024); } while (0)
; #define PG8_LDB(dst, b, h) do { _Pragma("unroll") for (int n = 0; n < 2; ++n) _Pragma("unroll") for (int k = 0; k < 2; ++k) dst[n][k] = *(const LAS bf16x8*)(lds + PG8_SB(b, h) + boff + n * 2048 + k * 1024); } while (0)
; #define PG8_MMA(ai, bj, At, Bt) do { __builtin_amdgcn_s_setprio(1); _Pragma("unroll") for (int m = 0; m < 4; ++m) _Pragma("unroll") for (int n = 0; n < 2; ++n) _Pragma("unroll") for (int k = 0; k < 2; ++k) \
;         acc[ai][bj][m][n] = __builtin_amdgcn_mfma_f32_16x16x32_bf16(Bt[n][k], At[m][k], acc[ai][bj][m][n], 0, 0, 0); __builtin_amdgcn_s_setprio(0); } while (0)
; #define PG8_WAIT_V(n) asm volatile("s_waitcnt vmcnt(" #n ")" ::: "memory")
; #define PG8_WAIT_L(n) asm volatile("s_waitcnt lgkmcnt(" #n ")" ::: "memory")
; #define PG8_BAR __builtin_amdgcn_s_barrier()
; #define PG8_SCHED __builtin_amdgcn_sched_barrier(0)
; template <class Epi, int GM, int GN, int GK, int LDA, int AMOD, int ASTRIDE, int WG = WGM>
; __device__ __forceinline__ void gemm_phase(LAS unsigned char* lds, const Gemm g, const Epi& E, int wv_) {
;     ...
;             PG8_LDB(B0, 0, 0); PG8_LDB(B1, 0, 1); PG8_SCHED; PG8_LDA(At, 0, 0); PG8_STAGE(PG8_SA(1, 1), a1 + hstepA, voffA);
;             PG8_WAIT_V(8); PG8_WAIT_L(0); PG8_BAR; PG8_MMA(0, 0, At, B0); PG8_MMA(0, 1, At, B1); PG8_BAR; PG8_SCHED;
;             PG8_LDA(At, 0, 1); PG8_STAGE(PG8_SB(0, 0), b2, voffB); PG8_STAGE(PG8_SB(0, 1), b2 + hstepB, voffB); PG8_STAGE(PG8_SA(0, 0), a2, voffA);
;             PG8_WAIT_V(8); PG8_WAIT_L(0); PG8_BAR; PG8_MMA(1, 0, At, B0); PG8_MMA(1, 1, At, B1); PG8_BAR; PG8_SCHED;
.LBB0_507:
	s_add_i32 s46, s18, 2
	s_add_u32 s19, s16, 0xfff80080
	s_addc_u32 s20, s17, -1
	s_add_i32 s47, 0, 0x10000
	s_cmp_eq_u32 s41, s18
	s_cselect_b32 s21, s7, s20
	s_cselect_b32 s20, s9, s19
	s_cselect_b32 s19, s42, s45
	s_cselect_b32 s18, s43, s44
	s_add_i32 s50, 0, 0x14000
	v_add_u32_e32 v154, s47, v140
	v_add_u32_e32 v158, s50, v140
	ds_read_b128 v[142:145], v154
	ds_read_b128 v[146:149], v154 offset:1024
	ds_read_b128 v[150:153], v154 offset:2048
	ds_read_b128 v[154:157], v154 offset:3072
	ds_read_b128 v[174:177], v158
	ds_read_b128 v[178:181], v158 offset:1024
	ds_read_b128 v[182:185], v158 offset:2048
	ds_read_b128 v[186:189], v158 offset:3072
	s_add_i32 m0, s28, 0xc000
	ds_read_b128 v[190:193], v141
	ds_read_b128 v[202:205], v141 offset:1024
	ds_read_b128 v[206:209], v141 offset:2048
	ds_read_b128 v[210:213], v141 offset:3072
	ds_read_b128 v[214:217], v141 offset:4096
	ds_read_b128 v[218:221], v141 offset:5120
	ds_read_b128 v[222:225], v141 offset:6144
	ds_read_b128 v[226:229], v141 offset:7168
	global_load_lds_dwordx4 v134, s[16:17]
	s_add_i32 m0, s28, 0xe000
	s_nop 0
	global_load_lds_dwordx4 v136, s[16:17]
	s_waitcnt vmcnt(8)
	s_waitcnt lgkmcnt(0)
	s_barrier
	s_setprio 1
	s_waitcnt lgkmcnt(0)
	v_mfma_f32_16x16x32_bf16 v[124:127], v[142:145], v[190:193], v[124:127]
	v_mfma_f32_16x16x32_bf16 v[120:123], v[150:153], v[190:193], v[120:123]
	v_mfma_f32_16x16x32_bf16 v[108:111], v[142:145], v[206:209], v[108:111]
	v_mfma_f32_16x16x32_bf16 v[104:107], v[150:153], v[206:209], v[104:107]
	v_mfma_f32_16x16x32_bf16 v[92:95], v[142:145], v[214:217], v[92:95]
	v_mfma_f32_16x16x32_bf16 v[88:91], v[150:153], v[214:217], v[88:91]
	v_mfma_f32_16x16x32_bf16 v[76:79], v[142:145], v[222:225], v[76:79]
	v_mfma_f32_16x16x32_bf16 v[72:75], v[150:153], v[222:225], v[72:75]
	v_mfma_f32_16x16x32_bf16 v[124:127], v[146:149], v[202:205], v[124:127]
	v_mfma_f32_16x16x32_bf16 v[120:123], v[154:157], v[202:205], v[120:123]
	v_mfma_f32_16x16x32_bf16 v[108:111], v[146:149], v[210:213], v[108:111]
	v_mfma_f32_16x16x32_bf16 v[104:107], v[154:157], v[210:213], v[104:107]
	v_mfma_f32_16x16x32_bf16 v[92:95], v[146:149], v[218:221], v[92:95]
	v_mfma_f32_16x16x32_bf16 v[88:91], v[154:157], v[218:221], v[88:91]
	v_mfma_f32_16x16x32_bf16 v[76:79], v[146:149], v[226:229], v[76:79]
	v_mfma_f32_16x16x32_bf16 v[72:75], v[154:157], v[226:229], v[72:75]
	s_setprio 0
	s_setprio 1
	v_mfma_f32_16x16x32_bf16 v[116:119], v[174:177], v[190:193], v[116:119]
	v_mfma_f32_16x16x32_bf16 v[112:115], v[182:185], v[190:193], v[112:115]
	v_mfma_f32_16x16x32_bf16 v[100:103], v[174:177], v[206:209], v[100:103]
	v_mfma_f32_16x16x32_bf16 v[96:99], v[182:185], v[206:209], v[96:99]
	v_mfma_f32_16x16x32_bf16 v[84:87], v[174:177], v[214:217], v[84:87]
	v_mfma_f32_16x16x32_bf16 v[80:83], v[182:185], v[214:217], v[80:83]
	v_mfma_f32_16x16x32_bf16 v[68:71], v[174:177], v[222:225], v[68:71]
	v_mfma_f32_16x16x32_bf16 v[64:67], v[182:185], v[222:225], v[64:67]
	v_mfma_f32_16x16x32_bf16 v[116:119], v[178:181], v[202:205], v[116:119]
	v_mfma_f32_16x16x32_bf16 v[112:115], v[186:189], v[202:205], v[112:115]
	v_mfma_f32_16x16x32_bf16 v[100:103], v[178:181], v[210:213], v[100:103]
	v_mfma_f32_16x16x32_bf16 v[96:99], v[186:189], v[210:213], v[96:99]
	v_mfma_f32_16x16x32_bf16 v[84:87], v[178:181], v[218:221], v[84:87]
	v_mfma_f32_16x16x32_bf16 v[80:83], v[186:189], v[218:221], v[80:83]
	v_mfma_f32_16x16x32_bf16 v[68:71], v[178:181], v[226:229], v[68:71]
	v_mfma_f32_16x16x32_bf16 v[64:67], v[186:189], v[226:229], v[64:67]
	s_setprio 0
	s_barrier
	s_add_i32 s47, s47, s26
	v_lshl_add_u64 v[158:159], s[18:19], 0, v[160:161]
	s_mov_b32 m0, s47
	ds_read_b128 v[190:193], v141 offset:16384
	ds_read_b128 v[202:205], v141 offset:17408
	ds_read_b128 v[206:209], v141 offset:18432
	ds_read_b128 v[210:213], v141 offset:19456
	ds_read_b128 v[214:217], v141 offset:20480
	ds_read_b128 v[218:221], v141 offset:21504
	ds_read_b128 v[222:225], v141 offset:22528
	ds_read_b128 v[226:229], v141 offset:23552
	global_load_lds_dwordx4 v160, s[18:19]
	s_add_i32 m0, s47, 0x2000
	s_add_u32 s48, s18, 0x80000
	v_lshl_add_u64 v[168:169], s[18:19], 0, v[128:129]
	s_addc_u32 s49, s19, 0
	s_add_i32 s47, s50, s26
	global_load_lds_dwordx4 v128, s[18:19]
	s_mov_b32 m0, s47
	v_lshl_add_u64 v[196:197], s[20:21], 0, v[130:131]
	global_load_lds_dwordx4 v160, s[48:49]
	s_add_i32 m0, s47, 0x2000
	s_nop 0
	global_load_lds_dwordx4 v128, s[48:49]
	v_lshl_add_u64 v[170:171], s[20:21], 0, v[132:133]
	s_mov_b32 m0, s28
	s_nop 0
	global_load_lds_dwordx4 v132, s[20:21]
	s_mov_b32 m0, s29
	s_nop 0
	global_load_lds_dwordx4 v130, s[20:21]
	s_waitcnt vmcnt(8)
	s_waitcnt lgkmcnt(0)
	s_barrier
; #define PG8_STAGE(bufoff, gbase, voff) do { _Pragma("unroll") for (int _i = 0; _i < 2; ++_i) \
;         __builtin_amdgcn_global_load_lds((const unsigned*)((const char*)(gbase) + (voff)[_i]), (LAS unsigned*)(lds + (bufoff) + ldsw + _i * 8192), 16, 0, 0); } while (0)
; #define PG8_LDA(dst, b, h) do { _Pragma("unroll") for (int m = 0; m < 4; ++m) _Pragma("unroll") for (int k = 0; k < 2; ++k) dst[m][k] = *(const LAS bf16x8*)(lds + PG8_SA(b, h) + aoff + m * 2048 + k * 1024); } while (0)
; #define PG8_LDB(dst, b, h) do { _Pragma("unroll") for (int n = 0; n < 2; ++n) _Pragma("unroll") for (int k = 0; k < 2; ++k) dst[n][k] = *(const LAS bf16x8*)(lds + PG8_SB(b, h) + boff + n * 2048 + k * 1024); } while (0)
; #define PG8_MMA(ai, bj, At, Bt) do { __builtin_amdgcn_s_setprio(1); _Pragma("unroll") for (int m = 0; m < 4; ++m) _Pragma("unroll") for (int n = 0; n < 2; ++n) _Pragma("unroll") for (int k = 0; k < 2; ++k) \
;         acc[ai][bj][m][n] = __builtin_amdgcn_mfma_f32_16x16x32_bf16(Bt[n][k], At[m][k], acc[ai][bj][m][n], 0, 0, 0); __builtin_amdgcn_s_setprio(0); } while (0)
; #define PG8_WAIT_V(n) asm volatile("s_waitcnt vmcnt(" #n ")" ::: "memory")
; #define PG8_WAIT_L(n) asm volatile("s_waitcnt lgkmcnt(" #n ")" ::: "memory")
; #define PG8_BAR __builtin_amdgcn_s_barrier()
; #define PG8_SCHED __builtin_amdgcn_sched_barrier(0)
; template <class Epi, int GM, int GN, int GK, int LDA, int AMOD, int ASTRIDE, int WG = WGM>
; __device__ __forceinline__ void gemm_phase(LAS unsigned char* lds, const Gemm g, const Epi& E, int wv_) {
;     ...
;             PG8_WAIT_V(8); PG8_WAIT_L(0); PG8_BAR; PG8_MMA(1, 0, At, B0); PG8_MMA(1, 1, At, B1); PG8_BAR; PG8_SCHED;
;             PG8_LDB(B0, 1, 0); PG8_LDB(B1, 1, 1); PG8_SCHED; PG8_LDA(At, 1, 0); PG8_STAGE(PG8_SA(0, 1), a2 + hstepA, voffA);
;             PG8_WAIT_V(8); PG8_WAIT_L(0); PG8_BAR; PG8_MMA(0, 0, At, B0); PG8_MMA(0, 1, At, B1); PG8_BAR; PG8_SCHED;
	s_setprio 1
	s_waitcnt lgkmcnt(0)
	v_mfma_f32_16x16x32_bf16 v[60:63], v[142:145], v[190:193], v[60:63]
	v_mfma_f32_16x16x32_bf16 v[56:59], v[150:153], v[190:193], v[56:59]
	v_mfma_f32_16x16x32_bf16 v[44:47], v[142:145], v[206:209], v[44:47]
	v_mfma_f32_16x16x32_bf16 v[40:43], v[150:153], v[206:209], v[40:43]
	v_mfma_f32_16x16x32_bf16 v[28:31], v[142:145], v[214:217], v[28:31]
	v_mfma_f32_16x16x32_bf16 v[24:27], v[150:153], v[214:217], v[24:27]
	v_mfma_f32_16x16x32_bf16 v[12:15], v[142:145], v[222:225], v[12:15]
	v_mfma_f32_16x16x32_bf16 v[8:11], v[150:153], v[222:225], v[8:11]
	v_mfma_f32_16x16x32_bf16 v[60:63], v[146:149], v[202:205], v[60:63]
	v_mfma_f32_16x16x32_bf16 v[56:59], v[154:157], v[202:205], v[56:59]
	v_mfma_f32_16x16x32_bf16 v[44:47], v[146:149], v[210:213], v[44:47]
	v_mfma_f32_16x16x32_bf16 v[40:43], v[154:157], v[210:213], v[40:43]
	v_mfma_f32_16x16x32_bf16 v[28:31], v[146:149], v[218:221], v[28:31]
	v_mfma_f32_16x16x32_bf16 v[24:27], v[154:157], v[218:221], v[24:27]
	v_mfma_f32_16x16x32_bf16 v[12:15], v[146:149], v[226:229], v[12:15]
	v_mfma_f32_16x16x32_bf16 v[8:11], v[154:157], v[226:229], v[8:11]
	s_setprio 0
	s_setprio 1
	v_mfma_f32_16x16x32_bf16 v[52:55], v[174:177], v[190:193], v[52:55]
	v_mfma_f32_16x16x32_bf16 v[48:51], v[182:185], v[190:193], v[48:51]
	v_mfma_f32_16x16x32_bf16 v[36:39], v[174:177], v[206:209], v[36:39]
	v_mfma_f32_16x16x32_bf16 v[32:35], v[182:185], v[206:209], v[32:35]
	v_mfma_f32_16x16x32_bf16 v[20:23], v[174:177], v[214:217], v[20:23]
	v_mfma_f32_16x16x32_bf16 v[16:19], v[182:185], v[214:217], v[16:19]
	v_mfma_f32_16x16x32_bf16 v[4:7], v[174:177], v[222:225], v[4:7]
	v_mfma_f32_16x16x32_bf16 v[0:3], v[182:185], v[222:225], v[0:3]
	v_mfma_f32_16x16x32_bf16 v[52:55], v[178:181], v[202:205], v[52:55]
	v_mfma_f32_16x16x32_bf16 v[48:51], v[186:189], v[202:205], v[48:51]
	v_mfma_f32_16x16x32_bf16 v[36:39], v[178:181], v[210:213], v[36:39]
	v_mfma_f32_16x16x32_bf16 v[32:35], v[186:189], v[210:213], v[32:35]
	v_mfma_f32_16x16x32_bf16 v[20:23], v[178:181], v[218:221], v[20:23]
	v_mfma_f32_16x16x32_bf16 v[16:19], v[186:189], v[218:221], v[16:19]
	v_mfma_f32_16x16x32_bf16 v[4:7], v[178:181], v[226:229], v[4:7]
	v_mfma_f32_16x16x32_bf16 v[0:3], v[186:189], v[226:229], v[0:3]
	s_setprio 0
	s_barrier
	s_add_i32 s47, 0, 0x18000
	s_add_i32 s48, 0, 0x1c000
	v_add_u32_e32 v154, s47, v140
	v_add_u32_e32 v186, s48, v140
	ds_read_b128 v[142:145], v154
	ds_read_b128 v[146:149], v154 offset:1024
	ds_read_b128 v[150:153], v154 offset:2048
	ds_read_b128 v[154:157], v154 offset:3072
	ds_read_b128 v[174:177], v186
	ds_read_b128 v[178:181], v186 offset:1024
	ds_read_b128 v[182:185], v186 offset:2048
	ds_read_b128 v[186:189], v186 offset:3072
	s_add_u32 s20, s20, 0x80000
	s_addc_u32 s21, s21, 0
	s_mov_b32 m0, s30
	ds_read_b128 v[190:193], v141 offset:32768
	ds_read_b128 v[202:205], v141 offset:33792
	ds_read_b128 v[206:209], v141 offset:34816
	ds_read_b128 v[210:213], v141 offset:35840
	ds_read_b128 v[214:217], v141 offset:36864
	ds_read_b128 v[218:221], v141 offset:37888
	ds_read_b128 v[222:225], v141 offset:38912
	ds_read_b128 v[226:229], v141 offset:39936
	global_load_lds_dwordx4 v132, s[20:21]
	v_lshl_add_u64 v[198:199], s[20:21], 0, v[130:131]
	s_mov_b32 m0, s31
	s_nop 0
	global_load_lds_dwordx4 v130, s[20:21]
	s_waitcnt vmcnt(8)
	s_waitcnt lgkmcnt(0)
	s_barrier
	s_setprio 1
	s_waitcnt lgkmcnt(0)
	v_mfma_f32_16x16x32_bf16 v[124:127], v[142:145], v[190:193], v[124:127]
	v_mfma_f32_16x16x32_bf16 v[120:123], v[150:153], v[190:193], v[120:123]
	v_mfma_f32_16x16x32_bf16 v[108:111], v[142:145], v[206:209], v[108:111]
	v_mfma_f32_16x16x32_bf16 v[104:107], v[150:153], v[206:209], v[104:107]
	v_mfma_f32_16x16x32_bf16 v[92:95], v[142:145], v[214:217], v[92:95]
	v_mfma_f32_16x16x32_bf16 v[88:91], v[150:153], v[214:217], v[88:91]
	v_mfma_f32_16x16x32_bf16 v[76:79], v[142:145], v[222:225], v[76:79]
	v_mfma_f32_16x16x32_bf16 v[72:75], v[150:153], v[222:225], v[72:75]
	v_mfma_f32_16x16x32_bf16 v[124:127], v[146:149], v[202:205], v[124:127]
	v_mfma_f32_16x16x32_bf16 v[120:123], v[154:157], v[202:205], v[120:123]
	v_mfma_f32_16x16x32_bf16 v[108:111], v[146:149], v[210:213], v[108:111]
	v_mfma_f32_16x16x32_bf16 v[104:107], v[154:157], v[210:213], v[104:107]
	v_mfma_f32_16x16x32_bf16 v[92:95], v[146:149], v[218:221], v[92:95]
	v_mfma_f32_16x16x32_bf16 v[88:91], v[154:157], v[218:221], v[88:91]
	v_mfma_f32_16x16x32_bf16 v[76:79], v[146:149], v[226:229], v[76:79]
	v_mfma_f32_16x16x32_bf16 v[72:75], v[154:157], v[226:229], v[72:75]
	s_setprio 0
	s_setprio 1
	v_mfma_f32_16x16x32_bf16 v[116:119], v[174:177], v[190:193], v[116:119]
	v_mfma_f32_16x16x32_bf16 v[112:115], v[182:185], v[190:193], v[112:115]
	v_mfma_f32_16x16x32_bf16 v[100:103], v[174:177], v[206:209], v[100:103]
	v_mfma_f32_16x16x32_bf16 v[96:99], v[182:185], v[206:209], v[96:99]
	v_mfma_f32_16x16x32_bf16 v[84:87], v[174:177], v[214:217], v[84:87]
	v_mfma_f32_16x16x32_bf16 v[80:83], v[182:185], v[214:217], v[80:83]
	v_mfma_f32_16x16x32_bf16 v[68:71], v[174:177], v[222:225], v[68:71]
	v_mfma_f32_16x16x32_bf16 v[64:67], v[182:185], v[222:225], v[64:67]
	v_mfma_f32_16x16x32_bf16 v[116:119], v[178:181], v[202:205], v[116:119]
	v_mfma_f32_16x16x32_bf16 v[112:115], v[186:189], v[202:205], v[112:115]
	v_mfma_f32_16x16x32_bf16 v[100:103], v[178:181], v[210:213], v[100:103]
	v_mfma_f32_16x16x32_bf16 v[96:99], v[186:189], v[210:213], v[96:99]
	v_mfma_f32_16x16x32_bf16 v[84:87], v[178:181], v[218:221], v[84:87]
	v_mfma_f32_16x16x32_bf16 v[80:83], v[186:189], v[218:221], v[80:83]
	v_mfma_f32_16x16x32_bf16 v[68:71], v[178:181], v[226:229], v[68:71]
	v_mfma_f32_16x16x32_bf16 v[64:67], v[186:189], v[226:229], v[64:67]
	s_setprio 0
	s_barrier
; #define PG8_STAGE(bufoff, gbase, voff) do { _Pragma("unroll") for (int _i = 0; _i < 2; ++_i) \
;         __builtin_amdgcn_global_load_lds((const unsigned*)((const char*)(gbase) + (voff)[_i]), (LAS unsigned*)(lds + (bufoff) + ldsw + _i * 8192), 16, 0, 0); } while (0)
; #define PG8_LDA(dst, b, h) do { _Pragma("unroll") for (int m = 0; m < 4; ++m) _Pragma("unroll") for (int k = 0; k < 2; ++k) dst[m][k] = *(const LAS bf16x8*)(lds + PG8_SA(b, h) + aoff + m * 2048 + k * 1024); } while (0)
; #define PG8_MMA(ai, bj, At, Bt) do { __builtin_amdgcn_s_setprio(1); _Pragma("unroll") for (int m = 0; m < 4; ++m) _Pragma("unroll") for (int n = 0; n < 2; ++n) _Pragma("unroll") for (int k = 0; k < 2; ++k) \
;         acc[ai][bj][m][n] = __builtin_amdgcn_mfma_f32_16x16x32_bf16(Bt[n][k], At[m][k], acc[ai][bj][m][n], 0, 0, 0); __builtin_amdgcn_s_setprio(0); } while (0)
; #define PG8_WAIT_V(n) asm volatile("s_waitcnt vmcnt(" #n ")" ::: "memory")
; #define PG8_WAIT_L(n) asm volatile("s_waitcnt lgkmcnt(" #n ")" ::: "memory")
; #define PG8_BAR __builtin_amdgcn_s_barrier()
; #define PG8_SCHED __builtin_amdgcn_sched_barrier(0)
; template <class Epi, int GM, int GN, int GK, int LDA, int AMOD, int ASTRIDE, int WG = WGM>
; __device__ __forceinline__ void gemm_phase(LAS unsigned char* lds, const Gemm g, const Epi& E, int wv_) {
;     ...
;             PG8_LDA(At, 1, 1); PG8_STAGE(PG8_SB(1, 0), b3, voffB); PG8_STAGE(PG8_SB(1, 1), b3 + hstepB, voffB); PG8_STAGE(PG8_SA(1, 0), a3, voffA);
;             PG8_WAIT_V(8); PG8_WAIT_L(0); PG8_BAR; PG8_MMA(1, 0, At, B0); PG8_MMA(1, 1, At, B1); PG8_BAR; PG8_SCHED;
;         }
	s_add_i32 s20, s47, s26
	v_lshl_add_u64 v[158:159], v[158:159], 0, s[70:71]
	s_mov_b32 m0, s20
	ds_read_b128 v[190:193], v141 offset:49152
	ds_read_b128 v[202:205], v141 offset:50176
	ds_read_b128 v[206:209], v141 offset:51200
	ds_read_b128 v[210:213], v141 offset:52224
	ds_read_b128 v[214:217], v141 offset:53248
	ds_read_b128 v[218:221], v141 offset:54272
	ds_read_b128 v[222:225], v141 offset:55296
	ds_read_b128 v[226:229], v141 offset:56320
	global_load_lds_dwordx4 v[158:159], off
	s_add_i32 m0, s20, 0x2000
	s_add_u32 s18, s18, 0x80080
	v_lshl_add_u64 v[158:159], v[168:169], 0, s[70:71]
	s_addc_u32 s19, s19, 0
	s_add_i32 s20, s48, s26
	global_load_lds_dwordx4 v[158:159], off
	s_mov_b32 m0, s20
	s_nop 0
	global_load_lds_dwordx4 v160, s[18:19]
	s_add_i32 m0, s20, 0x2000
	s_nop 0
	global_load_lds_dwordx4 v128, s[18:19]
	v_lshl_add_u64 v[158:159], v[170:171], 0, s[70:71]
	s_mov_b32 m0, s36
	s_nop 0
	global_load_lds_dwordx4 v[158:159], off
	v_lshl_add_u64 v[158:159], v[196:197], 0, s[70:71]
	s_mov_b32 m0, s37
	s_nop 0
	global_load_lds_dwordx4 v[158:159], off
	s_waitcnt vmcnt(8)
	s_waitcnt lgkmcnt(0)
	s_barrier
	s_setprio 1
	s_waitcnt lgkmcnt(0)
	v_mfma_f32_16x16x32_bf16 v[60:63], v[142:145], v[190:193], v[60:63]
	v_mfma_f32_16x16x32_bf16 v[56:59], v[150:153], v[190:193], v[56:59]
	v_mfma_f32_16x16x32_bf16 v[44:47], v[142:145], v[206:209], v[44:47]
	v_mfma_f32_16x16x32_bf16 v[40:43], v[150:153], v[206:209], v[40:43]
	v_mfma_f32_16x16x32_bf16 v[28:31], v[142:145], v[214:217], v[28:31]
	v_mfma_f32_16x16x32_bf16 v[24:27], v[150:153], v[214:217], v[24:27]
	v_mfma_f32_16x16x32_bf16 v[12:15], v[142:145], v[222:225], v[12:15]
	v_mfma_f32_16x16x32_bf16 v[8:11], v[150:153], v[222:225], v[8:11]
	v_mfma_f32_16x16x32_bf16 v[60:63], v[146:149], v[202:205], v[60:63]
	v_mfma_f32_16x16x32_bf16 v[56:59], v[154:157], v[202:205], v[56:59]
	v_mfma_f32_16x16x32_bf16 v[44:47], v[146:149], v[210:213], v[44:47]
	v_mfma_f32_16x16x32_bf16 v[40:43], v[154:157], v[210:213], v[40:43]
	v_mfma_f32_16x16x32_bf16 v[28:31], v[146:149], v[218:221], v[28:31]
	v_mfma_f32_16x16x32_bf16 v[24:27], v[154:157], v[218:221], v[24:27]
	v_mfma_f32_16x16x32_bf16 v[12:15], v[146:149], v[226:229], v[12:15]
	v_mfma_f32_16x16x32_bf16 v[8:11], v[154:157], v[226:229], v[8:11]
	s_setprio 0
	s_setprio 1
	v_mfma_f32_16x16x32_bf16 v[52:55], v[174:177], v[190:193], v[52:55]
	v_mfma_f32_16x16x32_bf16 v[48:51], v[182:185], v[190:193], v[48:51]
	v_mfma_f32_16x16x32_bf16 v[36:39], v[174:177], v[206:209], v[36:39]
	v_mfma_f32_16x16x32_bf16 v[32:35], v[182:185], v[206:209], v[32:35]
	v_mfma_f32_16x16x32_bf16 v[20:23], v[174:177], v[214:217], v[20:23]
	v_mfma_f32_16x16x32_bf16 v[16:19], v[182:185], v[214:217], v[16:19]
	v_mfma_f32_16x16x32_bf16 v[4:7], v[174:177], v[222:225], v[4:7]
	v_mfma_f32_16x16x32_bf16 v[0:3], v[182:185], v[222:225], v[0:3]
	v_mfma_f32_16x16x32_bf16 v[52:55], v[178:181], v[202:205], v[52:55]
	v_mfma_f32_16x16x32_bf16 v[48:51], v[186:189], v[202:205], v[48:51]
	v_mfma_f32_16x16x32_bf16 v[36:39], v[178:181], v[210:213], v[36:39]
	v_mfma_f32_16x16x32_bf16 v[32:35], v[186:189], v[210:213], v[32:35]
	v_mfma_f32_16x16x32_bf16 v[20:23], v[178:181], v[218:221], v[20:23]
	v_mfma_f32_16x16x32_bf16 v[16:19], v[186:189], v[218:221], v[16:19]
	v_mfma_f32_16x16x32_bf16 v[4:7], v[178:181], v[226:229], v[4:7]
	v_mfma_f32_16x16x32_bf16 v[0:3], v[186:189], v[226:229], v[0:3]
	s_setprio 0
	s_barrier
	s_add_u32 s16, s16, 0x100
	s_addc_u32 s17, s17, 0
	s_add_u32 s44, s44, 0x100
	s_addc_u32 s45, s45, 0
	s_cmp_ge_i32 s46, s23
	s_mov_b32 s18, s46
	s_cbranch_scc0 .LBB0_507
	s_and_b64 vcc, exec, s[4:5]
	s_cbranch_vccz .LBB0_510
